# GEMM K-loops: hipcc's per-phase s_setprio 1/0 flips deleted (A/B of the template's priority toggling)
# baseline (speedup 1.0000x reference)
; #define PG8_STAGE(bufoff, gbase, voff) do { _Pragma("unroll") for (int _i = 0; _i < 2; ++_i) \
;         __builtin_amdgcn_global_load_lds((const unsigned*)((const char*)(gbase) + (voff)[_i]), (PG8_LAS unsigned*)(lds + (bufoff) + ldsw + _i * 8192), 16, 0, 0); } while (0)
; #define PG8_LDA(dst, b, h) do { _Pragma("unroll") for (int m = 0; m < 4; ++m) _Pragma("unroll") for (int k = 0; k < 2; ++k) dst[m][k] = *(const PG8_LAS bf16x8*)(lds + PG8_SA(b, h) + aoff + m * 2048 + k * 1024); } while (0)
; #define PG8_LDB(dst, b, h) do { _Pragma("unroll") for (int n = 0; n < 2; ++n) _Pragma("unroll") for (int k = 0; k < 2; ++k) dst[n][k] = *(const PG8_LAS bf16x8*)(lds + PG8_SB(b, h) + boff + n * 2048 + k * 1024); } while (0)
; #define PG8_MMA(ai, bj, At, Bt) do { __builtin_amdgcn_s_setprio(1); _Pragma("unroll") for (int m = 0; m < 4; ++m) _Pragma("unroll") for (int n = 0; n < 2; ++n) _Pragma("unroll") for (int k = 0; k < 2; ++k) \
;         acc[ai][bj][m][n] = __builtin_amdgcn_mfma_f32_16x16x32_bf16(Bt[n][k], At[m][k], acc[ai][bj][m][n], 0, 0, 0); __builtin_amdgcn_s_setprio(0); } while (0)
; #define PG8_WAIT_V(n) asm volatile("s_waitcnt vmcnt(" #n ")" ::: "memory")
; #define PG8_WAIT_L(n) asm volatile("s_waitcnt lgkmcnt(" #n ")" ::: "memory")
; #define PG8_BAR __builtin_amdgcn_s_barrier()
; #define PG8_SCHED __builtin_amdgcn_sched_barrier(0)
; template <class Epi, class Sched, bool ALIGN_EPI = false, bool SP2 = false>
; __device__ __forceinline__ void gemm_phase(PG8_LAS unsigned char* lds, const Gemm g, const Sched& S, const Epi& E) {
;     ...
;             PG8_LDB(B0, 0, 0); PG8_LDB(B1, 0, 1); PG8_SCHED; PG8_LDA(At, 0, 0); PG8_STAGE(PG8_SA(1, 1), a1 + hstepA, voffA);
;             PG8_WAIT_V(8); PG8_WAIT_L(0); PG8_BAR; PG8_MMA(0, 0, At, B0); PG8_MMA(0, 1, At, B1); PG8_BAR; PG8_SCHED;
;             PG8_LDA(At, 0, 1); PG8_STAGE(PG8_SB(0, 0), b2, voffB); PG8_STAGE(PG8_SB(0, 1), b2 + hstepB, voffB); PG8_STAGE(PG8_SA(0, 0), a2, voffA);
.LBB0_154:
	ds_read_b128 v[152:155], v149
	ds_read_b128 v[156:159], v149 offset:1024
	ds_read_b128 v[160:163], v149 offset:2048
	ds_read_b128 v[164:167], v149 offset:3072
	ds_read_b128 v[168:171], v150
	ds_read_b128 v[172:175], v150 offset:1024
	ds_read_b128 v[176:179], v150 offset:2048
	ds_read_b128 v[180:183], v150 offset:3072
	s_add_i32 s48, s46, 2
	s_add_u32 s49, s6, 0x80
	s_addc_u32 s47, s7, 0
	s_cmp_eq_u32 s61, s46
	s_cselect_b32 s46, s42, s49
	s_cselect_b32 s47, s43, s47
	s_cselect_b32 s81, s45, s79
	s_cselect_b32 s80, s44, s78
	v_lshl_add_u64 v[144:145], s[6:7], 0, v[140:141]
	s_add_i32 m0, s53, 0xc000
	ds_read_b128 v[184:187], v151
	ds_read_b128 v[188:191], v151 offset:1024
	ds_read_b128 v[192:195], v151 offset:2048
	ds_read_b128 v[196:199], v151 offset:3072
	ds_read_b128 v[200:203], v151 offset:4096
	ds_read_b128 v[204:207], v151 offset:5120
	ds_read_b128 v[208:211], v151 offset:6144
	ds_read_b128 v[212:215], v151 offset:7168
	global_load_lds_dwordx4 v[144:145], off
	v_lshl_add_u64 v[144:145], s[6:7], 0, v[138:139]
	s_add_i32 m0, s53, 0xe000
	s_nop 0
	global_load_lds_dwordx4 v[144:145], off
	s_waitcnt vmcnt(8)
	s_waitcnt lgkmcnt(0)
	s_barrier
	s_waitcnt lgkmcnt(0)
	v_mfma_f32_16x16x32_bf16 v[122:125], v[152:155], v[184:187], v[122:125]
	v_mfma_f32_16x16x32_bf16 v[126:129], v[160:163], v[184:187], v[126:129]
	v_mfma_f32_16x16x32_bf16 v[110:113], v[152:155], v[192:195], v[110:113]
	v_mfma_f32_16x16x32_bf16 v[106:109], v[160:163], v[192:195], v[106:109]
	v_mfma_f32_16x16x32_bf16 v[94:97], v[152:155], v[200:203], v[94:97]
	v_mfma_f32_16x16x32_bf16 v[90:93], v[160:163], v[200:203], v[90:93]
	v_mfma_f32_16x16x32_bf16 v[78:81], v[152:155], v[208:211], v[78:81]
	v_mfma_f32_16x16x32_bf16 v[74:77], v[160:163], v[208:211], v[74:77]
	v_mfma_f32_16x16x32_bf16 v[122:125], v[156:159], v[188:191], v[122:125]
	v_mfma_f32_16x16x32_bf16 v[126:129], v[164:167], v[188:191], v[126:129]
	v_mfma_f32_16x16x32_bf16 v[110:113], v[156:159], v[196:199], v[110:113]
	v_mfma_f32_16x16x32_bf16 v[106:109], v[164:167], v[196:199], v[106:109]
	v_mfma_f32_16x16x32_bf16 v[94:97], v[156:159], v[204:207], v[94:97]
	v_mfma_f32_16x16x32_bf16 v[90:93], v[164:167], v[204:207], v[90:93]
	v_mfma_f32_16x16x32_bf16 v[78:81], v[156:159], v[212:215], v[78:81]
	v_mfma_f32_16x16x32_bf16 v[74:77], v[164:167], v[212:215], v[74:77]
	v_mfma_f32_16x16x32_bf16 v[118:121], v[168:171], v[184:187], v[118:121]
	v_mfma_f32_16x16x32_bf16 v[114:117], v[176:179], v[184:187], v[114:117]
	v_mfma_f32_16x16x32_bf16 v[102:105], v[168:171], v[192:195], v[102:105]
	v_mfma_f32_16x16x32_bf16 v[98:101], v[176:179], v[192:195], v[98:101]
	v_mfma_f32_16x16x32_bf16 v[86:89], v[168:171], v[200:203], v[86:89]
	v_mfma_f32_16x16x32_bf16 v[82:85], v[176:179], v[200:203], v[82:85]
	v_mfma_f32_16x16x32_bf16 v[70:73], v[168:171], v[208:211], v[70:73]
	v_mfma_f32_16x16x32_bf16 v[66:69], v[176:179], v[208:211], v[66:69]
	v_mfma_f32_16x16x32_bf16 v[118:121], v[172:175], v[188:191], v[118:121]
	v_mfma_f32_16x16x32_bf16 v[114:117], v[180:183], v[188:191], v[114:117]
	v_mfma_f32_16x16x32_bf16 v[102:105], v[172:175], v[196:199], v[102:105]
	v_mfma_f32_16x16x32_bf16 v[98:101], v[180:183], v[196:199], v[98:101]
	v_mfma_f32_16x16x32_bf16 v[86:89], v[172:175], v[204:207], v[86:89]
	v_mfma_f32_16x16x32_bf16 v[82:85], v[180:183], v[204:207], v[82:85]
	v_mfma_f32_16x16x32_bf16 v[70:73], v[172:175], v[212:215], v[70:73]
	v_mfma_f32_16x16x32_bf16 v[66:69], v[180:183], v[212:215], v[66:69]
	s_barrier
	s_add_i32 s49, s68, s52
	v_lshl_add_u64 v[144:145], s[80:81], 0, v[132:133]
	s_mov_b32 m0, s49
	ds_read_b128 v[184:187], v151 offset:16384
	ds_read_b128 v[188:191], v151 offset:17408
	ds_read_b128 v[192:195], v151 offset:18432
	ds_read_b128 v[196:199], v151 offset:19456
	ds_read_b128 v[200:203], v151 offset:20480
	ds_read_b128 v[204:207], v151 offset:21504
	ds_read_b128 v[208:211], v151 offset:22528
	ds_read_b128 v[212:215], v151 offset:23552
	global_load_lds_dwordx4 v[144:145], off
	s_add_i32 m0, s49, 0x2000
	v_lshl_add_u64 v[216:217], s[80:81], 0, v[136:137]
	s_add_u32 s80, s80, s16
	s_addc_u32 s81, s81, s17
	s_add_i32 s49, s69, s52
	global_load_lds_dwordx4 v[216:217], off
	v_lshl_add_u64 v[218:219], s[80:81], 0, v[132:133]
	s_mov_b32 m0, s49
	v_lshl_add_u64 v[220:221], s[80:81], 0, v[136:137]
	global_load_lds_dwordx4 v[218:219], off
	s_add_i32 m0, s49, 0x2000
	v_lshl_add_u64 v[222:223], s[46:47], 0, v[130:131]
	global_load_lds_dwordx4 v[220:221], off
	s_mov_b32 m0, s53
	v_lshl_add_u64 v[224:225], s[46:47], 0, v[134:135]
	global_load_lds_dwordx4 v[222:223], off
	s_mov_b32 m0, s54
	s_nop 0
	global_load_lds_dwordx4 v[224:225], off
	s_waitcnt vmcnt(8)
	s_waitcnt lgkmcnt(0)
	s_barrier
; #define PG8_STAGE(bufoff, gbase, voff) do { _Pragma("unroll") for (int _i = 0; _i < 2; ++_i) \
;         __builtin_amdgcn_global_load_lds((const unsigned*)((const char*)(gbase) + (voff)[_i]), (PG8_LAS unsigned*)(lds + (bufoff) + ldsw + _i * 8192), 16, 0, 0); } while (0)
; #define PG8_LDA(dst, b, h) do { _Pragma("unroll") for (int m = 0; m < 4; ++m) _Pragma("unroll") for (int k = 0; k < 2; ++k) dst[m][k] = *(const PG8_LAS bf16x8*)(lds + PG8_SA(b, h) + aoff + m * 2048 + k * 1024); } while (0)
; #define PG8_LDB(dst, b, h) do { _Pragma("unroll") for (int n = 0; n < 2; ++n) _Pragma("unroll") for (int k = 0; k < 2; ++k) dst[n][k] = *(const PG8_LAS bf16x8*)(lds + PG8_SB(b, h) + boff + n * 2048 + k * 1024); } while (0)
; #define PG8_MMA(ai, bj, At, Bt) do { __builtin_amdgcn_s_setprio(1); _Pragma("unroll") for (int m = 0; m < 4; ++m) _Pragma("unroll") for (int n = 0; n < 2; ++n) _Pragma("unroll") for (int k = 0; k < 2; ++k) \
;         acc[ai][bj][m][n] = __builtin_amdgcn_mfma_f32_16x16x32_bf16(Bt[n][k], At[m][k], acc[ai][bj][m][n], 0, 0, 0); __builtin_amdgcn_s_setprio(0); } while (0)
; #define PG8_WAIT_V(n) asm volatile("s_waitcnt vmcnt(" #n ")" ::: "memory")
; #define PG8_WAIT_L(n) asm volatile("s_waitcnt lgkmcnt(" #n ")" ::: "memory")
; #define PG8_BAR __builtin_amdgcn_s_barrier()
; #define PG8_SCHED __builtin_amdgcn_sched_barrier(0)
; template <class Epi, class Sched, bool ALIGN_EPI = false, bool SP2 = false>
; __device__ __forceinline__ void gemm_phase(PG8_LAS unsigned char* lds, const Gemm g, const Sched& S, const Epi& E) {
;     ...
;             PG8_WAIT_V(8); PG8_WAIT_L(0); PG8_BAR; PG8_MMA(1, 0, At, B0); PG8_MMA(1, 1, At, B1); PG8_BAR; PG8_SCHED;
;             PG8_LDB(B0, 1, 0); PG8_LDB(B1, 1, 1); PG8_SCHED; PG8_LDA(At, 1, 0); PG8_STAGE(PG8_SA(0, 1), a2 + hstepA, voffA);
;             PG8_WAIT_V(8); PG8_WAIT_L(0); PG8_BAR; PG8_MMA(0, 0, At, B0); PG8_MMA(0, 1, At, B1); PG8_BAR; PG8_SCHED;
	s_waitcnt lgkmcnt(0)
	v_mfma_f32_16x16x32_bf16 v[62:65], v[152:155], v[184:187], v[62:65]
	v_mfma_f32_16x16x32_bf16 v[58:61], v[160:163], v[184:187], v[58:61]
	v_mfma_f32_16x16x32_bf16 v[46:49], v[152:155], v[192:195], v[46:49]
	v_mfma_f32_16x16x32_bf16 v[42:45], v[160:163], v[192:195], v[42:45]
	v_mfma_f32_16x16x32_bf16 v[30:33], v[152:155], v[200:203], v[30:33]
	v_mfma_f32_16x16x32_bf16 v[26:29], v[160:163], v[200:203], v[26:29]
	v_mfma_f32_16x16x32_bf16 v[14:17], v[152:155], v[208:211], v[14:17]
	v_mfma_f32_16x16x32_bf16 v[10:13], v[160:163], v[208:211], v[10:13]
	v_mfma_f32_16x16x32_bf16 v[62:65], v[156:159], v[188:191], v[62:65]
	v_mfma_f32_16x16x32_bf16 v[58:61], v[164:167], v[188:191], v[58:61]
	v_mfma_f32_16x16x32_bf16 v[46:49], v[156:159], v[196:199], v[46:49]
	v_mfma_f32_16x16x32_bf16 v[42:45], v[164:167], v[196:199], v[42:45]
	v_mfma_f32_16x16x32_bf16 v[30:33], v[156:159], v[204:207], v[30:33]
	v_mfma_f32_16x16x32_bf16 v[26:29], v[164:167], v[204:207], v[26:29]
	v_mfma_f32_16x16x32_bf16 v[14:17], v[156:159], v[212:215], v[14:17]
	v_mfma_f32_16x16x32_bf16 v[10:13], v[164:167], v[212:215], v[10:13]
	v_mfma_f32_16x16x32_bf16 v[54:57], v[168:171], v[184:187], v[54:57]
	v_mfma_f32_16x16x32_bf16 v[50:53], v[176:179], v[184:187], v[50:53]
	v_mfma_f32_16x16x32_bf16 v[38:41], v[168:171], v[192:195], v[38:41]
	v_mfma_f32_16x16x32_bf16 v[34:37], v[176:179], v[192:195], v[34:37]
	v_mfma_f32_16x16x32_bf16 v[22:25], v[168:171], v[200:203], v[22:25]
	v_mfma_f32_16x16x32_bf16 v[18:21], v[176:179], v[200:203], v[18:21]
	v_mfma_f32_16x16x32_bf16 v[6:9], v[168:171], v[208:211], v[6:9]
	v_mfma_f32_16x16x32_bf16 v[2:5], v[176:179], v[208:211], v[2:5]
	v_mfma_f32_16x16x32_bf16 v[54:57], v[172:175], v[188:191], v[54:57]
	v_mfma_f32_16x16x32_bf16 v[50:53], v[180:183], v[188:191], v[50:53]
	v_mfma_f32_16x16x32_bf16 v[38:41], v[172:175], v[196:199], v[38:41]
	v_mfma_f32_16x16x32_bf16 v[34:37], v[180:183], v[196:199], v[34:37]
	v_mfma_f32_16x16x32_bf16 v[22:25], v[172:175], v[204:207], v[22:25]
	v_mfma_f32_16x16x32_bf16 v[18:21], v[180:183], v[204:207], v[18:21]
	v_mfma_f32_16x16x32_bf16 v[6:9], v[172:175], v[212:215], v[6:9]
	v_mfma_f32_16x16x32_bf16 v[2:5], v[180:183], v[212:215], v[2:5]
	s_barrier
	s_add_i32 s49, 0, 0x18000
	s_add_i32 s80, 0, 0x1c000
	v_add_u32_e32 v164, s49, v147
	v_add_u32_e32 v180, s80, v147
	ds_read_b128 v[152:155], v164
	ds_read_b128 v[156:159], v164 offset:1024
	ds_read_b128 v[160:163], v164 offset:2048
	ds_read_b128 v[164:167], v164 offset:3072
	ds_read_b128 v[168:171], v180
	ds_read_b128 v[172:175], v180 offset:1024
	ds_read_b128 v[176:179], v180 offset:2048
	ds_read_b128 v[180:183], v180 offset:3072
	s_add_u32 s46, s46, s10
	s_addc_u32 s47, s47, s11
	s_mov_b32 m0, s55
	v_lshl_add_u64 v[226:227], s[46:47], 0, v[130:131]
	ds_read_b128 v[184:187], v151 offset:32768
	ds_read_b128 v[188:191], v151 offset:33792
	ds_read_b128 v[192:195], v151 offset:34816
	ds_read_b128 v[196:199], v151 offset:35840
	ds_read_b128 v[200:203], v151 offset:36864
	ds_read_b128 v[204:207], v151 offset:37888
	ds_read_b128 v[208:211], v151 offset:38912
	ds_read_b128 v[212:215], v151 offset:39936
	global_load_lds_dwordx4 v[226:227], off
	v_lshl_add_u64 v[226:227], s[46:47], 0, v[134:135]
	s_mov_b32 m0, s56
	s_nop 0
	global_load_lds_dwordx4 v[226:227], off
	s_waitcnt vmcnt(8)
	s_waitcnt lgkmcnt(0)
	s_barrier
	s_waitcnt lgkmcnt(0)
	v_mfma_f32_16x16x32_bf16 v[122:125], v[152:155], v[184:187], v[122:125]
	v_mfma_f32_16x16x32_bf16 v[126:129], v[160:163], v[184:187], v[126:129]
	v_mfma_f32_16x16x32_bf16 v[110:113], v[152:155], v[192:195], v[110:113]
	v_mfma_f32_16x16x32_bf16 v[106:109], v[160:163], v[192:195], v[106:109]
	v_mfma_f32_16x16x32_bf16 v[94:97], v[152:155], v[200:203], v[94:97]
	v_mfma_f32_16x16x32_bf16 v[90:93], v[160:163], v[200:203], v[90:93]
	v_mfma_f32_16x16x32_bf16 v[78:81], v[152:155], v[208:211], v[78:81]
	v_mfma_f32_16x16x32_bf16 v[74:77], v[160:163], v[208:211], v[74:77]
	v_mfma_f32_16x16x32_bf16 v[122:125], v[156:159], v[188:191], v[122:125]
	v_mfma_f32_16x16x32_bf16 v[126:129], v[164:167], v[188:191], v[126:129]
	v_mfma_f32_16x16x32_bf16 v[110:113], v[156:159], v[196:199], v[110:113]
	v_mfma_f32_16x16x32_bf16 v[106:109], v[164:167], v[196:199], v[106:109]
	v_mfma_f32_16x16x32_bf16 v[94:97], v[156:159], v[204:207], v[94:97]
	v_mfma_f32_16x16x32_bf16 v[90:93], v[164:167], v[204:207], v[90:93]
	v_mfma_f32_16x16x32_bf16 v[78:81], v[156:159], v[212:215], v[78:81]
	v_mfma_f32_16x16x32_bf16 v[74:77], v[164:167], v[212:215], v[74:77]
	v_mfma_f32_16x16x32_bf16 v[118:121], v[168:171], v[184:187], v[118:121]
	v_mfma_f32_16x16x32_bf16 v[114:117], v[176:179], v[184:187], v[114:117]
	v_mfma_f32_16x16x32_bf16 v[102:105], v[168:171], v[192:195], v[102:105]
	v_mfma_f32_16x16x32_bf16 v[98:101], v[176:179], v[192:195], v[98:101]
	v_mfma_f32_16x16x32_bf16 v[86:89], v[168:171], v[200:203], v[86:89]
	v_mfma_f32_16x16x32_bf16 v[82:85], v[176:179], v[200:203], v[82:85]
	v_mfma_f32_16x16x32_bf16 v[70:73], v[168:171], v[208:211], v[70:73]
	v_mfma_f32_16x16x32_bf16 v[66:69], v[176:179], v[208:211], v[66:69]
	v_mfma_f32_16x16x32_bf16 v[118:121], v[172:175], v[188:191], v[118:121]
	v_mfma_f32_16x16x32_bf16 v[114:117], v[180:183], v[188:191], v[114:117]
	v_mfma_f32_16x16x32_bf16 v[102:105], v[172:175], v[196:199], v[102:105]
	v_mfma_f32_16x16x32_bf16 v[98:101], v[180:183], v[196:199], v[98:101]
	v_mfma_f32_16x16x32_bf16 v[86:89], v[172:175], v[204:207], v[86:89]
	v_mfma_f32_16x16x32_bf16 v[82:85], v[180:183], v[204:207], v[82:85]
	v_mfma_f32_16x16x32_bf16 v[70:73], v[172:175], v[212:215], v[70:73]
	v_mfma_f32_16x16x32_bf16 v[66:69], v[180:183], v[212:215], v[66:69]
	s_barrier
; #define PG8_STAGE(bufoff, gbase, voff) do { _Pragma("unroll") for (int _i = 0; _i < 2; ++_i) \
;         __builtin_amdgcn_global_load_lds((const unsigned*)((const char*)(gbase) + (voff)[_i]), (PG8_LAS unsigned*)(lds + (bufoff) + ldsw + _i * 8192), 16, 0, 0); } while (0)
; #define PG8_LDA(dst, b, h) do { _Pragma("unroll") for (int m = 0; m < 4; ++m) _Pragma("unroll") for (int k = 0; k < 2; ++k) dst[m][k] = *(const PG8_LAS bf16x8*)(lds + PG8_SA(b, h) + aoff + m * 2048 + k * 1024); } while (0)
; #define PG8_MMA(ai, bj, At, Bt) do { __builtin_amdgcn_s_setprio(1); _Pragma("unroll") for (int m = 0; m < 4; ++m) _Pragma("unroll") for (int n = 0; n < 2; ++n) _Pragma("unroll") for (int k = 0; k < 2; ++k) \
;         acc[ai][bj][m][n] = __builtin_amdgcn_mfma_f32_16x16x32_bf16(Bt[n][k], At[m][k], acc[ai][bj][m][n], 0, 0, 0); __builtin_amdgcn_s_setprio(0); } while (0)
; #define PG8_WAIT_V(n) asm volatile("s_waitcnt vmcnt(" #n ")" ::: "memory")
; #define PG8_WAIT_L(n) asm volatile("s_waitcnt lgkmcnt(" #n ")" ::: "memory")
; #define PG8_BAR __builtin_amdgcn_s_barrier()
; #define PG8_SCHED __builtin_amdgcn_sched_barrier(0)
; template <class Epi, class Sched, bool ALIGN_EPI = false, bool SP2 = false>
; __device__ __forceinline__ void gemm_phase(PG8_LAS unsigned char* lds, const Gemm g, const Sched& S, const Epi& E) {
;     ...
;         for (int t = 0; t < nt; t += 2) {
;     ...
;             PG8_LDA(At, 1, 1); PG8_STAGE(PG8_SB(1, 0), b3, voffB); PG8_STAGE(PG8_SB(1, 1), b3 + hstepB, voffB); PG8_STAGE(PG8_SA(1, 0), a3, voffA);
;             PG8_WAIT_V(8); PG8_WAIT_L(0); PG8_BAR; PG8_MMA(1, 0, At, B0); PG8_MMA(1, 1, At, B1); PG8_BAR; PG8_SCHED;
	s_add_i32 s46, s49, s52
	v_lshl_add_u64 v[144:145], v[144:145], 0, s[34:35]
	s_mov_b32 m0, s46
	ds_read_b128 v[184:187], v151 offset:49152
	ds_read_b128 v[188:191], v151 offset:50176
	ds_read_b128 v[192:195], v151 offset:51200
	ds_read_b128 v[196:199], v151 offset:52224
	ds_read_b128 v[200:203], v151 offset:53248
	ds_read_b128 v[204:207], v151 offset:54272
	ds_read_b128 v[208:211], v151 offset:55296
	ds_read_b128 v[212:215], v151 offset:56320
	global_load_lds_dwordx4 v[144:145], off
	v_lshl_add_u64 v[144:145], v[216:217], 0, s[34:35]
	s_add_i32 m0, s46, 0x2000
	s_add_i32 s46, s80, s52
	global_load_lds_dwordx4 v[144:145], off
	v_lshl_add_u64 v[144:145], v[218:219], 0, s[34:35]
	s_mov_b32 m0, s46
	s_nop 0
	global_load_lds_dwordx4 v[144:145], off
	v_lshl_add_u64 v[144:145], v[220:221], 0, s[34:35]
	s_add_i32 m0, s46, 0x2000
	s_nop 0
	global_load_lds_dwordx4 v[144:145], off
	v_lshl_add_u64 v[144:145], v[222:223], 0, s[34:35]
	s_mov_b32 m0, s58
	s_nop 0
	global_load_lds_dwordx4 v[144:145], off
	v_lshl_add_u64 v[144:145], v[224:225], 0, s[34:35]
	s_mov_b32 m0, s59
	s_nop 0
	global_load_lds_dwordx4 v[144:145], off
	s_waitcnt vmcnt(8)
	s_waitcnt lgkmcnt(0)
	s_barrier
	s_waitcnt lgkmcnt(0)
	v_mfma_f32_16x16x32_bf16 v[62:65], v[152:155], v[184:187], v[62:65]
	v_mfma_f32_16x16x32_bf16 v[58:61], v[160:163], v[184:187], v[58:61]
	v_mfma_f32_16x16x32_bf16 v[46:49], v[152:155], v[192:195], v[46:49]
	v_mfma_f32_16x16x32_bf16 v[42:45], v[160:163], v[192:195], v[42:45]
	v_mfma_f32_16x16x32_bf16 v[30:33], v[152:155], v[200:203], v[30:33]
	v_mfma_f32_16x16x32_bf16 v[26:29], v[160:163], v[200:203], v[26:29]
	v_mfma_f32_16x16x32_bf16 v[14:17], v[152:155], v[208:211], v[14:17]
	v_mfma_f32_16x16x32_bf16 v[10:13], v[160:163], v[208:211], v[10:13]
	v_mfma_f32_16x16x32_bf16 v[62:65], v[156:159], v[188:191], v[62:65]
	v_mfma_f32_16x16x32_bf16 v[58:61], v[164:167], v[188:191], v[58:61]
	v_mfma_f32_16x16x32_bf16 v[46:49], v[156:159], v[196:199], v[46:49]
	v_mfma_f32_16x16x32_bf16 v[42:45], v[164:167], v[196:199], v[42:45]
	v_mfma_f32_16x16x32_bf16 v[30:33], v[156:159], v[204:207], v[30:33]
	v_mfma_f32_16x16x32_bf16 v[26:29], v[164:167], v[204:207], v[26:29]
	v_mfma_f32_16x16x32_bf16 v[14:17], v[156:159], v[212:215], v[14:17]
	v_mfma_f32_16x16x32_bf16 v[10:13], v[164:167], v[212:215], v[10:13]
	v_mfma_f32_16x16x32_bf16 v[54:57], v[168:171], v[184:187], v[54:57]
	v_mfma_f32_16x16x32_bf16 v[50:53], v[176:179], v[184:187], v[50:53]
	v_mfma_f32_16x16x32_bf16 v[38:41], v[168:171], v[192:195], v[38:41]
	v_mfma_f32_16x16x32_bf16 v[34:37], v[176:179], v[192:195], v[34:37]
	v_mfma_f32_16x16x32_bf16 v[22:25], v[168:171], v[200:203], v[22:25]
	v_mfma_f32_16x16x32_bf16 v[18:21], v[176:179], v[200:203], v[18:21]
	v_mfma_f32_16x16x32_bf16 v[6:9], v[168:171], v[208:211], v[6:9]
	v_mfma_f32_16x16x32_bf16 v[2:5], v[176:179], v[208:211], v[2:5]
	v_mfma_f32_16x16x32_bf16 v[54:57], v[172:175], v[188:191], v[54:57]
	v_mfma_f32_16x16x32_bf16 v[50:53], v[180:183], v[188:191], v[50:53]
	v_mfma_f32_16x16x32_bf16 v[38:41], v[172:175], v[196:199], v[38:41]
	v_mfma_f32_16x16x32_bf16 v[34:37], v[180:183], v[196:199], v[34:37]
	v_mfma_f32_16x16x32_bf16 v[22:25], v[172:175], v[204:207], v[22:25]
	v_mfma_f32_16x16x32_bf16 v[18:21], v[180:183], v[204:207], v[18:21]
	v_mfma_f32_16x16x32_bf16 v[6:9], v[172:175], v[212:215], v[6:9]
	v_mfma_f32_16x16x32_bf16 v[2:5], v[180:183], v[212:215], v[2:5]
	s_barrier
	s_add_u32 s78, s78, 0x100
	s_addc_u32 s79, s79, 0
	s_add_u32 s6, s6, 0x100
	s_addc_u32 s7, s7, 0
	s_cmp_ge_i32 s48, s60
	s_mov_b32 s46, s48
	s_cbranch_scc0 .LBB0_154

; #define PG8_STAGE(bufoff, gbase, voff) do { _Pragma("unroll") for (int _i = 0; _i < 2; ++_i) \
;         __builtin_amdgcn_global_load_lds((const unsigned*)((const char*)(gbase) + (voff)[_i]), (PG8_LAS unsigned*)(lds + (bufoff) + ldsw + _i * 8192), 16, 0, 0); } while (0)
; #define PG8_LDA(dst, b, h) do { _Pragma("unroll") for (int m = 0; m < 4; ++m) _Pragma("unroll") for (int k = 0; k < 2; ++k) dst[m][k] = *(const PG8_LAS bf16x8*)(lds + PG8_SA(b, h) + aoff + m * 2048 + k * 1024); } while (0)
; #define PG8_LDB(dst, b, h) do { _Pragma("unroll") for (int n = 0; n < 2; ++n) _Pragma("unroll") for (int k = 0; k < 2; ++k) dst[n][k] = *(const PG8_LAS bf16x8*)(lds + PG8_SB(b, h) + boff + n * 2048 + k * 1024); } while (0)
; #define PG8_MMA(ai, bj, At, Bt) do { __builtin_amdgcn_s_setprio(1); _Pragma("unroll") for (int m = 0; m < 4; ++m) _Pragma("unroll") for (int n = 0; n < 2; ++n) _Pragma("unroll") for (int k = 0; k < 2; ++k) \
;         acc[ai][bj][m][n] = __builtin_amdgcn_mfma_f32_16x16x32_bf16(Bt[n][k], At[m][k], acc[ai][bj][m][n], 0, 0, 0); __builtin_amdgcn_s_setprio(0); } while (0)
; #define PG8_WAIT_V(n) asm volatile("s_waitcnt vmcnt(" #n ")" ::: "memory")
; #define PG8_WAIT_L(n) asm volatile("s_waitcnt lgkmcnt(" #n ")" ::: "memory")
; #define PG8_BAR __builtin_amdgcn_s_barrier()
; #define PG8_SCHED __builtin_amdgcn_sched_barrier(0)
; template <class Epi, class Sched, bool ALIGN_EPI = false, bool SP2 = false>
; __device__ __forceinline__ void gemm_phase(PG8_LAS unsigned char* lds, const Gemm g, const Sched& S, const Epi& E) {
;     ...
;             PG8_LDB(B0, 0, 0); PG8_LDB(B1, 0, 1); PG8_SCHED; PG8_LDA(At, 0, 0); PG8_STAGE(PG8_SA(1, 1), a1 + hstepA, voffA);
;             PG8_WAIT_V(8); PG8_WAIT_L(0); PG8_BAR; PG8_MMA(0, 0, At, B0); PG8_MMA(0, 1, At, B1); PG8_BAR; PG8_SCHED;
;             PG8_LDA(At, 0, 1); PG8_STAGE(PG8_SB(0, 0), b2, voffB); PG8_STAGE(PG8_SB(0, 1), b2 + hstepB, voffB); PG8_STAGE(PG8_SA(0, 0), a2, voffA);
.LBB0_369:
	ds_read_b128 v[154:157], v149
	ds_read_b128 v[158:161], v149 offset:1024
	ds_read_b128 v[162:165], v149 offset:2048
	ds_read_b128 v[166:169], v149 offset:3072
	ds_read_b128 v[170:173], v151
	ds_read_b128 v[174:177], v151 offset:1024
	ds_read_b128 v[178:181], v151 offset:2048
	ds_read_b128 v[182:185], v151 offset:3072
	s_add_i32 s52, s50, 2
	s_add_u32 s53, s6, 0x80
	s_addc_u32 s51, s7, 0
	s_cmp_eq_u32 s66, s50
	s_cselect_b32 s50, s46, s53
	s_cselect_b32 s51, s47, s51
	s_cselect_b32 s87, s49, s84
	s_cselect_b32 s86, s48, s83
	v_lshl_add_u64 v[144:145], s[6:7], 0, v[140:141]
	s_add_i32 m0, s58, 0xc000
	ds_read_b128 v[186:189], v152
	ds_read_b128 v[190:193], v152 offset:1024
	ds_read_b128 v[194:197], v152 offset:2048
	ds_read_b128 v[198:201], v152 offset:3072
	ds_read_b128 v[202:205], v152 offset:4096
	ds_read_b128 v[206:209], v152 offset:5120
	ds_read_b128 v[210:213], v152 offset:6144
	ds_read_b128 v[214:217], v152 offset:7168
	global_load_lds_dwordx4 v[144:145], off
	v_lshl_add_u64 v[144:145], s[6:7], 0, v[138:139]
	s_add_i32 m0, s58, 0xe000
	s_nop 0
	global_load_lds_dwordx4 v[144:145], off
	s_waitcnt vmcnt(8)
	s_waitcnt lgkmcnt(0)
	s_barrier
	s_waitcnt lgkmcnt(0)
	v_mfma_f32_16x16x32_bf16 v[122:125], v[154:157], v[186:189], v[122:125]
	v_mfma_f32_16x16x32_bf16 v[126:129], v[162:165], v[186:189], v[126:129]
	v_mfma_f32_16x16x32_bf16 v[110:113], v[154:157], v[194:197], v[110:113]
	v_mfma_f32_16x16x32_bf16 v[106:109], v[162:165], v[194:197], v[106:109]
	v_mfma_f32_16x16x32_bf16 v[94:97], v[154:157], v[202:205], v[94:97]
	v_mfma_f32_16x16x32_bf16 v[90:93], v[162:165], v[202:205], v[90:93]
	v_mfma_f32_16x16x32_bf16 v[78:81], v[154:157], v[210:213], v[78:81]
	v_mfma_f32_16x16x32_bf16 v[74:77], v[162:165], v[210:213], v[74:77]
	v_mfma_f32_16x16x32_bf16 v[122:125], v[158:161], v[190:193], v[122:125]
	v_mfma_f32_16x16x32_bf16 v[126:129], v[166:169], v[190:193], v[126:129]
	v_mfma_f32_16x16x32_bf16 v[110:113], v[158:161], v[198:201], v[110:113]
	v_mfma_f32_16x16x32_bf16 v[106:109], v[166:169], v[198:201], v[106:109]
	v_mfma_f32_16x16x32_bf16 v[94:97], v[158:161], v[206:209], v[94:97]
	v_mfma_f32_16x16x32_bf16 v[90:93], v[166:169], v[206:209], v[90:93]
	v_mfma_f32_16x16x32_bf16 v[78:81], v[158:161], v[214:217], v[78:81]
	v_mfma_f32_16x16x32_bf16 v[74:77], v[166:169], v[214:217], v[74:77]
	v_mfma_f32_16x16x32_bf16 v[118:121], v[170:173], v[186:189], v[118:121]
	v_mfma_f32_16x16x32_bf16 v[114:117], v[178:181], v[186:189], v[114:117]
	v_mfma_f32_16x16x32_bf16 v[102:105], v[170:173], v[194:197], v[102:105]
	v_mfma_f32_16x16x32_bf16 v[98:101], v[178:181], v[194:197], v[98:101]
	v_mfma_f32_16x16x32_bf16 v[86:89], v[170:173], v[202:205], v[86:89]
	v_mfma_f32_16x16x32_bf16 v[82:85], v[178:181], v[202:205], v[82:85]
	v_mfma_f32_16x16x32_bf16 v[70:73], v[170:173], v[210:213], v[70:73]
	v_mfma_f32_16x16x32_bf16 v[66:69], v[178:181], v[210:213], v[66:69]
	v_mfma_f32_16x16x32_bf16 v[118:121], v[174:177], v[190:193], v[118:121]
	v_mfma_f32_16x16x32_bf16 v[114:117], v[182:185], v[190:193], v[114:117]
	v_mfma_f32_16x16x32_bf16 v[102:105], v[174:177], v[198:201], v[102:105]
	v_mfma_f32_16x16x32_bf16 v[98:101], v[182:185], v[198:201], v[98:101]
	v_mfma_f32_16x16x32_bf16 v[86:89], v[174:177], v[206:209], v[86:89]
	v_mfma_f32_16x16x32_bf16 v[82:85], v[182:185], v[206:209], v[82:85]
	v_mfma_f32_16x16x32_bf16 v[70:73], v[174:177], v[214:217], v[70:73]
	v_mfma_f32_16x16x32_bf16 v[66:69], v[182:185], v[214:217], v[66:69]
	s_barrier
	s_add_i32 s53, s75, s57
	v_lshl_add_u64 v[144:145], s[86:87], 0, v[132:133]
	s_mov_b32 m0, s53
	ds_read_b128 v[186:189], v152 offset:16384
	ds_read_b128 v[190:193], v152 offset:17408
	ds_read_b128 v[194:197], v152 offset:18432
	ds_read_b128 v[198:201], v152 offset:19456
	ds_read_b128 v[202:205], v152 offset:20480
	ds_read_b128 v[206:209], v152 offset:21504
	ds_read_b128 v[210:213], v152 offset:22528
	ds_read_b128 v[214:217], v152 offset:23552
	global_load_lds_dwordx4 v[144:145], off
	s_add_i32 m0, s53, 0x2000
	v_lshl_add_u64 v[218:219], s[86:87], 0, v[136:137]
	s_add_u32 s86, s86, s10
	s_addc_u32 s87, s87, s11
	s_add_i32 s53, s76, s57
	global_load_lds_dwordx4 v[218:219], off
	v_lshl_add_u64 v[220:221], s[86:87], 0, v[132:133]
	s_mov_b32 m0, s53
	v_lshl_add_u64 v[222:223], s[86:87], 0, v[136:137]
	global_load_lds_dwordx4 v[220:221], off
	s_add_i32 m0, s53, 0x2000
	v_lshl_add_u64 v[224:225], s[50:51], 0, v[130:131]
	global_load_lds_dwordx4 v[222:223], off
	s_mov_b32 m0, s58
	v_lshl_add_u64 v[226:227], s[50:51], 0, v[134:135]
	global_load_lds_dwordx4 v[224:225], off
	s_mov_b32 m0, s59
	s_nop 0
	global_load_lds_dwordx4 v[226:227], off
	s_waitcnt vmcnt(8)
	s_waitcnt lgkmcnt(0)
	s_barrier
; #define PG8_STAGE(bufoff, gbase, voff) do { _Pragma("unroll") for (int _i = 0; _i < 2; ++_i) \
;         __builtin_amdgcn_global_load_lds((const unsigned*)((const char*)(gbase) + (voff)[_i]), (PG8_LAS unsigned*)(lds + (bufoff) + ldsw + _i * 8192), 16, 0, 0); } while (0)
; #define PG8_LDA(dst, b, h) do { _Pragma("unroll") for (int m = 0; m < 4; ++m) _Pragma("unroll") for (int k = 0; k < 2; ++k) dst[m][k] = *(const PG8_LAS bf16x8*)(lds + PG8_SA(b, h) + aoff + m * 2048 + k * 1024); } while (0)
; #define PG8_LDB(dst, b, h) do { _Pragma("unroll") for (int n = 0; n < 2; ++n) _Pragma("unroll") for (int k = 0; k < 2; ++k) dst[n][k] = *(const PG8_LAS bf16x8*)(lds + PG8_SB(b, h) + boff + n * 2048 + k * 1024); } while (0)
; #define PG8_MMA(ai, bj, At, Bt) do { __builtin_amdgcn_s_setprio(1); _Pragma("unroll") for (int m = 0; m < 4; ++m) _Pragma("unroll") for (int n = 0; n < 2; ++n) _Pragma("unroll") for (int k = 0; k < 2; ++k) \
;         acc[ai][bj][m][n] = __builtin_amdgcn_mfma_f32_16x16x32_bf16(Bt[n][k], At[m][k], acc[ai][bj][m][n], 0, 0, 0); __builtin_amdgcn_s_setprio(0); } while (0)
; #define PG8_WAIT_V(n) asm volatile("s_waitcnt vmcnt(" #n ")" ::: "memory")
; #define PG8_WAIT_L(n) asm volatile("s_waitcnt lgkmcnt(" #n ")" ::: "memory")
; #define PG8_BAR __builtin_amdgcn_s_barrier()
; #define PG8_SCHED __builtin_amdgcn_sched_barrier(0)
; template <class Epi, class Sched, bool ALIGN_EPI = false, bool SP2 = false>
; __device__ __forceinline__ void gemm_phase(PG8_LAS unsigned char* lds, const Gemm g, const Sched& S, const Epi& E) {
;     ...
;             PG8_WAIT_V(8); PG8_WAIT_L(0); PG8_BAR; PG8_MMA(1, 0, At, B0); PG8_MMA(1, 1, At, B1); PG8_BAR; PG8_SCHED;
;             PG8_LDB(B0, 1, 0); PG8_LDB(B1, 1, 1); PG8_SCHED; PG8_LDA(At, 1, 0); PG8_STAGE(PG8_SA(0, 1), a2 + hstepA, voffA);
;             PG8_WAIT_V(8); PG8_WAIT_L(0); PG8_BAR; PG8_MMA(0, 0, At, B0); PG8_MMA(0, 1, At, B1); PG8_BAR; PG8_SCHED;
	s_waitcnt lgkmcnt(0)
	v_mfma_f32_16x16x32_bf16 v[62:65], v[154:157], v[186:189], v[62:65]
	v_mfma_f32_16x16x32_bf16 v[58:61], v[162:165], v[186:189], v[58:61]
	v_mfma_f32_16x16x32_bf16 v[46:49], v[154:157], v[194:197], v[46:49]
	v_mfma_f32_16x16x32_bf16 v[42:45], v[162:165], v[194:197], v[42:45]
	v_mfma_f32_16x16x32_bf16 v[30:33], v[154:157], v[202:205], v[30:33]
	v_mfma_f32_16x16x32_bf16 v[26:29], v[162:165], v[202:205], v[26:29]
	v_mfma_f32_16x16x32_bf16 v[14:17], v[154:157], v[210:213], v[14:17]
	v_mfma_f32_16x16x32_bf16 v[10:13], v[162:165], v[210:213], v[10:13]
	v_mfma_f32_16x16x32_bf16 v[62:65], v[158:161], v[190:193], v[62:65]
	v_mfma_f32_16x16x32_bf16 v[58:61], v[166:169], v[190:193], v[58:61]
	v_mfma_f32_16x16x32_bf16 v[46:49], v[158:161], v[198:201], v[46:49]
	v_mfma_f32_16x16x32_bf16 v[42:45], v[166:169], v[198:201], v[42:45]
	v_mfma_f32_16x16x32_bf16 v[30:33], v[158:161], v[206:209], v[30:33]
	v_mfma_f32_16x16x32_bf16 v[26:29], v[166:169], v[206:209], v[26:29]
	v_mfma_f32_16x16x32_bf16 v[14:17], v[158:161], v[214:217], v[14:17]
	v_mfma_f32_16x16x32_bf16 v[10:13], v[166:169], v[214:217], v[10:13]
	v_mfma_f32_16x16x32_bf16 v[54:57], v[170:173], v[186:189], v[54:57]
	v_mfma_f32_16x16x32_bf16 v[50:53], v[178:181], v[186:189], v[50:53]
	v_mfma_f32_16x16x32_bf16 v[38:41], v[170:173], v[194:197], v[38:41]
	v_mfma_f32_16x16x32_bf16 v[34:37], v[178:181], v[194:197], v[34:37]
	v_mfma_f32_16x16x32_bf16 v[22:25], v[170:173], v[202:205], v[22:25]
	v_mfma_f32_16x16x32_bf16 v[18:21], v[178:181], v[202:205], v[18:21]
	v_mfma_f32_16x16x32_bf16 v[6:9], v[170:173], v[210:213], v[6:9]
	v_mfma_f32_16x16x32_bf16 v[2:5], v[178:181], v[210:213], v[2:5]
	v_mfma_f32_16x16x32_bf16 v[54:57], v[174:177], v[190:193], v[54:57]
	v_mfma_f32_16x16x32_bf16 v[50:53], v[182:185], v[190:193], v[50:53]
	v_mfma_f32_16x16x32_bf16 v[38:41], v[174:177], v[198:201], v[38:41]
	v_mfma_f32_16x16x32_bf16 v[34:37], v[182:185], v[198:201], v[34:37]
	v_mfma_f32_16x16x32_bf16 v[22:25], v[174:177], v[206:209], v[22:25]
	v_mfma_f32_16x16x32_bf16 v[18:21], v[182:185], v[206:209], v[18:21]
	v_mfma_f32_16x16x32_bf16 v[6:9], v[174:177], v[214:217], v[6:9]
	v_mfma_f32_16x16x32_bf16 v[2:5], v[182:185], v[214:217], v[2:5]
	s_barrier
	s_add_i32 s53, 0, 0x18000
	v_add_u32_e32 v153, s53, v147
	s_add_i32 s85, 0, 0x1c000
	ds_read_b128 v[154:157], v153
	ds_read_b128 v[158:161], v153 offset:1024
	ds_read_b128 v[162:165], v153 offset:2048
	ds_read_b128 v[166:169], v153 offset:3072
	v_add_u32_e32 v153, s85, v147
	ds_read_b128 v[170:173], v153
	ds_read_b128 v[174:177], v153 offset:1024
	ds_read_b128 v[178:181], v153 offset:2048
	ds_read_b128 v[182:185], v153 offset:3072
	s_add_u32 s50, s50, s8
	s_addc_u32 s51, s51, s9
	s_mov_b32 m0, s60
	v_lshl_add_u64 v[228:229], s[50:51], 0, v[130:131]
	ds_read_b128 v[186:189], v152 offset:32768
	ds_read_b128 v[190:193], v152 offset:33792
	ds_read_b128 v[194:197], v152 offset:34816
	ds_read_b128 v[198:201], v152 offset:35840
	ds_read_b128 v[202:205], v152 offset:36864
	ds_read_b128 v[206:209], v152 offset:37888
	ds_read_b128 v[210:213], v152 offset:38912
	ds_read_b128 v[214:217], v152 offset:39936
	global_load_lds_dwordx4 v[228:229], off
	v_lshl_add_u64 v[228:229], s[50:51], 0, v[134:135]
	s_mov_b32 m0, s61
	s_nop 0
	global_load_lds_dwordx4 v[228:229], off
	s_waitcnt vmcnt(8)
	s_waitcnt lgkmcnt(0)
	s_barrier
	s_waitcnt lgkmcnt(0)
	v_mfma_f32_16x16x32_bf16 v[122:125], v[154:157], v[186:189], v[122:125]
	v_mfma_f32_16x16x32_bf16 v[126:129], v[162:165], v[186:189], v[126:129]
	v_mfma_f32_16x16x32_bf16 v[110:113], v[154:157], v[194:197], v[110:113]
	v_mfma_f32_16x16x32_bf16 v[106:109], v[162:165], v[194:197], v[106:109]
	v_mfma_f32_16x16x32_bf16 v[94:97], v[154:157], v[202:205], v[94:97]
	v_mfma_f32_16x16x32_bf16 v[90:93], v[162:165], v[202:205], v[90:93]
	v_mfma_f32_16x16x32_bf16 v[78:81], v[154:157], v[210:213], v[78:81]
	v_mfma_f32_16x16x32_bf16 v[74:77], v[162:165], v[210:213], v[74:77]
	v_mfma_f32_16x16x32_bf16 v[122:125], v[158:161], v[190:193], v[122:125]
	v_mfma_f32_16x16x32_bf16 v[126:129], v[166:169], v[190:193], v[126:129]
	v_mfma_f32_16x16x32_bf16 v[110:113], v[158:161], v[198:201], v[110:113]
	v_mfma_f32_16x16x32_bf16 v[106:109], v[166:169], v[198:201], v[106:109]
	v_mfma_f32_16x16x32_bf16 v[94:97], v[158:161], v[206:209], v[94:97]
	v_mfma_f32_16x16x32_bf16 v[90:93], v[166:169], v[206:209], v[90:93]
	v_mfma_f32_16x16x32_bf16 v[78:81], v[158:161], v[214:217], v[78:81]
	v_mfma_f32_16x16x32_bf16 v[74:77], v[166:169], v[214:217], v[74:77]
	v_mfma_f32_16x16x32_bf16 v[118:121], v[170:173], v[186:189], v[118:121]
	v_mfma_f32_16x16x32_bf16 v[114:117], v[178:181], v[186:189], v[114:117]
	v_mfma_f32_16x16x32_bf16 v[102:105], v[170:173], v[194:197], v[102:105]
	v_mfma_f32_16x16x32_bf16 v[98:101], v[178:181], v[194:197], v[98:101]
	v_mfma_f32_16x16x32_bf16 v[86:89], v[170:173], v[202:205], v[86:89]
	v_mfma_f32_16x16x32_bf16 v[82:85], v[178:181], v[202:205], v[82:85]
	v_mfma_f32_16x16x32_bf16 v[70:73], v[170:173], v[210:213], v[70:73]
	v_mfma_f32_16x16x32_bf16 v[66:69], v[178:181], v[210:213], v[66:69]
	v_mfma_f32_16x16x32_bf16 v[118:121], v[174:177], v[190:193], v[118:121]
	v_mfma_f32_16x16x32_bf16 v[114:117], v[182:185], v[190:193], v[114:117]
	v_mfma_f32_16x16x32_bf16 v[102:105], v[174:177], v[198:201], v[102:105]
	v_mfma_f32_16x16x32_bf16 v[98:101], v[182:185], v[198:201], v[98:101]
	v_mfma_f32_16x16x32_bf16 v[86:89], v[174:177], v[206:209], v[86:89]
	v_mfma_f32_16x16x32_bf16 v[82:85], v[182:185], v[206:209], v[82:85]
	v_mfma_f32_16x16x32_bf16 v[70:73], v[174:177], v[214:217], v[70:73]
	v_mfma_f32_16x16x32_bf16 v[66:69], v[182:185], v[214:217], v[66:69]
	s_barrier
; #define PG8_STAGE(bufoff, gbase, voff) do { _Pragma("unroll") for (int _i = 0; _i < 2; ++_i) \
;         __builtin_amdgcn_global_load_lds((const unsigned*)((const char*)(gbase) + (voff)[_i]), (PG8_LAS unsigned*)(lds + (bufoff) + ldsw + _i * 8192), 16, 0, 0); } while (0)
; #define PG8_LDA(dst, b, h) do { _Pragma("unroll") for (int m = 0; m < 4; ++m) _Pragma("unroll") for (int k = 0; k < 2; ++k) dst[m][k] = *(const PG8_LAS bf16x8*)(lds + PG8_SA(b, h) + aoff + m * 2048 + k * 1024); } while (0)
; #define PG8_MMA(ai, bj, At, Bt) do { __builtin_amdgcn_s_setprio(1); _Pragma("unroll") for (int m = 0; m < 4; ++m) _Pragma("unroll") for (int n = 0; n < 2; ++n) _Pragma("unroll") for (int k = 0; k < 2; ++k) \
;         acc[ai][bj][m][n] = __builtin_amdgcn_mfma_f32_16x16x32_bf16(Bt[n][k], At[m][k], acc[ai][bj][m][n], 0, 0, 0); __builtin_amdgcn_s_setprio(0); } while (0)
; #define PG8_WAIT_V(n) asm volatile("s_waitcnt vmcnt(" #n ")" ::: "memory")
; #define PG8_WAIT_L(n) asm volatile("s_waitcnt lgkmcnt(" #n ")" ::: "memory")
; #define PG8_BAR __builtin_amdgcn_s_barrier()
; #define PG8_SCHED __builtin_amdgcn_sched_barrier(0)
; template <class Epi, class Sched, bool ALIGN_EPI = false, bool SP2 = false>
; __device__ __forceinline__ void gemm_phase(PG8_LAS unsigned char* lds, const Gemm g, const Sched& S, const Epi& E) {
;     ...
;         for (int t = 0; t < nt; t += 2) {
;     ...
;             PG8_LDA(At, 1, 1); PG8_STAGE(PG8_SB(1, 0), b3, voffB); PG8_STAGE(PG8_SB(1, 1), b3 + hstepB, voffB); PG8_STAGE(PG8_SA(1, 0), a3, voffA);
;             PG8_WAIT_V(8); PG8_WAIT_L(0); PG8_BAR; PG8_MMA(1, 0, At, B0); PG8_MMA(1, 1, At, B1); PG8_BAR; PG8_SCHED;
	s_add_i32 s50, s53, s57
	v_lshl_add_u64 v[144:145], v[144:145], 0, s[38:39]
	s_mov_b32 m0, s50
	ds_read_b128 v[186:189], v152 offset:49152
	ds_read_b128 v[190:193], v152 offset:50176
	ds_read_b128 v[194:197], v152 offset:51200
	ds_read_b128 v[198:201], v152 offset:52224
	ds_read_b128 v[202:205], v152 offset:53248
	ds_read_b128 v[206:209], v152 offset:54272
	ds_read_b128 v[210:213], v152 offset:55296
	ds_read_b128 v[214:217], v152 offset:56320
	global_load_lds_dwordx4 v[144:145], off
	v_lshl_add_u64 v[144:145], v[218:219], 0, s[38:39]
	s_add_i32 m0, s50, 0x2000
	s_add_i32 s50, s85, s57
	global_load_lds_dwordx4 v[144:145], off
	v_lshl_add_u64 v[144:145], v[220:221], 0, s[38:39]
	s_mov_b32 m0, s50
	s_nop 0
	global_load_lds_dwordx4 v[144:145], off
	v_lshl_add_u64 v[144:145], v[222:223], 0, s[38:39]
	s_add_i32 m0, s50, 0x2000
	s_nop 0
	global_load_lds_dwordx4 v[144:145], off
	v_lshl_add_u64 v[144:145], v[224:225], 0, s[38:39]
	s_mov_b32 m0, s63
	s_nop 0
	global_load_lds_dwordx4 v[144:145], off
	v_lshl_add_u64 v[144:145], v[226:227], 0, s[38:39]
	s_mov_b32 m0, s64
	s_nop 0
	global_load_lds_dwordx4 v[144:145], off
	s_waitcnt vmcnt(8)
	s_waitcnt lgkmcnt(0)
	s_barrier
	s_waitcnt lgkmcnt(0)
	v_mfma_f32_16x16x32_bf16 v[62:65], v[154:157], v[186:189], v[62:65]
	v_mfma_f32_16x16x32_bf16 v[58:61], v[162:165], v[186:189], v[58:61]
	v_mfma_f32_16x16x32_bf16 v[46:49], v[154:157], v[194:197], v[46:49]
	v_mfma_f32_16x16x32_bf16 v[42:45], v[162:165], v[194:197], v[42:45]
	v_mfma_f32_16x16x32_bf16 v[30:33], v[154:157], v[202:205], v[30:33]
	v_mfma_f32_16x16x32_bf16 v[26:29], v[162:165], v[202:205], v[26:29]
	v_mfma_f32_16x16x32_bf16 v[14:17], v[154:157], v[210:213], v[14:17]
	v_mfma_f32_16x16x32_bf16 v[10:13], v[162:165], v[210:213], v[10:13]
	v_mfma_f32_16x16x32_bf16 v[62:65], v[158:161], v[190:193], v[62:65]
	v_mfma_f32_16x16x32_bf16 v[58:61], v[166:169], v[190:193], v[58:61]
	v_mfma_f32_16x16x32_bf16 v[46:49], v[158:161], v[198:201], v[46:49]
	v_mfma_f32_16x16x32_bf16 v[42:45], v[166:169], v[198:201], v[42:45]
	v_mfma_f32_16x16x32_bf16 v[30:33], v[158:161], v[206:209], v[30:33]
	v_mfma_f32_16x16x32_bf16 v[26:29], v[166:169], v[206:209], v[26:29]
	v_mfma_f32_16x16x32_bf16 v[14:17], v[158:161], v[214:217], v[14:17]
	v_mfma_f32_16x16x32_bf16 v[10:13], v[166:169], v[214:217], v[10:13]
	v_mfma_f32_16x16x32_bf16 v[54:57], v[170:173], v[186:189], v[54:57]
	v_mfma_f32_16x16x32_bf16 v[50:53], v[178:181], v[186:189], v[50:53]
	v_mfma_f32_16x16x32_bf16 v[38:41], v[170:173], v[194:197], v[38:41]
	v_mfma_f32_16x16x32_bf16 v[34:37], v[178:181], v[194:197], v[34:37]
	v_mfma_f32_16x16x32_bf16 v[22:25], v[170:173], v[202:205], v[22:25]
	v_mfma_f32_16x16x32_bf16 v[18:21], v[178:181], v[202:205], v[18:21]
	v_mfma_f32_16x16x32_bf16 v[6:9], v[170:173], v[210:213], v[6:9]
	v_mfma_f32_16x16x32_bf16 v[2:5], v[178:181], v[210:213], v[2:5]
	v_mfma_f32_16x16x32_bf16 v[54:57], v[174:177], v[190:193], v[54:57]
	v_mfma_f32_16x16x32_bf16 v[50:53], v[182:185], v[190:193], v[50:53]
	v_mfma_f32_16x16x32_bf16 v[38:41], v[174:177], v[198:201], v[38:41]
	v_mfma_f32_16x16x32_bf16 v[34:37], v[182:185], v[198:201], v[34:37]
	v_mfma_f32_16x16x32_bf16 v[22:25], v[174:177], v[206:209], v[22:25]
	v_mfma_f32_16x16x32_bf16 v[18:21], v[182:185], v[206:209], v[18:21]
	v_mfma_f32_16x16x32_bf16 v[6:9], v[174:177], v[214:217], v[6:9]
	v_mfma_f32_16x16x32_bf16 v[2:5], v[182:185], v[214:217], v[2:5]
	s_barrier
	s_add_u32 s83, s83, 0x100
	s_addc_u32 s84, s84, 0
	s_add_u32 s6, s6, 0x100
	s_addc_u32 s7, s7, 0
	s_cmp_ge_i32 s52, s65
	s_mov_b32 s50, s52
	s_cbranch_scc0 .LBB0_369

; #define PG8_STAGE(bufoff, gbase, voff) do { _Pragma("unroll") for (int _i = 0; _i < 2; ++_i) \
;         __builtin_amdgcn_global_load_lds((const unsigned*)((const char*)(gbase) + (voff)[_i]), (PG8_LAS unsigned*)(lds + (bufoff) + ldsw + _i * 8192), 16, 0, 0); } while (0)
; #define PG8_LDA(dst, b, h) do { _Pragma("unroll") for (int m = 0; m < 4; ++m) _Pragma("unroll") for (int k = 0; k < 2; ++k) dst[m][k] = *(const PG8_LAS bf16x8*)(lds + PG8_SA(b, h) + aoff + m * 2048 + k * 1024); } while (0)
; #define PG8_LDB(dst, b, h) do { _Pragma("unroll") for (int n = 0; n < 2; ++n) _Pragma("unroll") for (int k = 0; k < 2; ++k) dst[n][k] = *(const PG8_LAS bf16x8*)(lds + PG8_SB(b, h) + boff + n * 2048 + k * 1024); } while (0)
; #define PG8_MMA(ai, bj, At, Bt) do { __builtin_amdgcn_s_setprio(1); _Pragma("unroll") for (int m = 0; m < 4; ++m) _Pragma("unroll") for (int n = 0; n < 2; ++n) _Pragma("unroll") for (int k = 0; k < 2; ++k) \
;         acc[ai][bj][m][n] = __builtin_amdgcn_mfma_f32_16x16x32_bf16(Bt[n][k], At[m][k], acc[ai][bj][m][n], 0, 0, 0); __builtin_amdgcn_s_setprio(0); } while (0)
; #define PG8_WAIT_V(n) asm volatile("s_waitcnt vmcnt(" #n ")" ::: "memory")
; #define PG8_WAIT_L(n) asm volatile("s_waitcnt lgkmcnt(" #n ")" ::: "memory")
; #define PG8_BAR __builtin_amdgcn_s_barrier()
; #define PG8_SCHED __builtin_amdgcn_sched_barrier(0)
; template <class Epi, class Sched, bool ALIGN_EPI = false, bool SP2 = false>
; __device__ __forceinline__ void gemm_phase(PG8_LAS unsigned char* lds, const Gemm g, const Sched& S, const Epi& E) {
;     ...
;             PG8_LDB(B0, 0, 0); PG8_LDB(B1, 0, 1); PG8_SCHED; PG8_LDA(At, 0, 0); PG8_STAGE(PG8_SA(1, 1), a1 + hstepA, voffA);
;             PG8_WAIT_V(8); PG8_WAIT_L(0); PG8_BAR; PG8_MMA(0, 0, At, B0); PG8_MMA(0, 1, At, B1); PG8_BAR; PG8_SCHED;
;             PG8_LDA(At, 0, 1); PG8_STAGE(PG8_SB(0, 0), b2, voffB); PG8_STAGE(PG8_SB(0, 1), b2 + hstepB, voffB); PG8_STAGE(PG8_SA(0, 0), a2, voffA);
.LBB0_424:
	ds_read_b128 v[144:147], v154
	ds_read_b128 v[158:161], v154 offset:1024
	ds_read_b128 v[162:165], v154 offset:2048
	ds_read_b128 v[166:169], v154 offset:3072
	ds_read_b128 v[170:173], v155
	ds_read_b128 v[174:177], v155 offset:1024
	ds_read_b128 v[178:181], v155 offset:2048
	ds_read_b128 v[182:185], v155 offset:3072
	s_add_i32 s52, s50, 2
	s_add_u32 s53, s6, 0x80
	s_addc_u32 s51, s7, 0
	s_cmp_eq_u32 s67, s50
	s_cselect_b32 s50, s46, s53
	s_cselect_b32 s51, s47, s51
	s_cselect_b32 s85, s49, s83
	s_cselect_b32 s84, s48, s82
	v_lshl_add_u64 v[148:149], s[6:7], 0, v[140:141]
	s_add_i32 m0, s58, 0xc000
	ds_read_b128 v[186:189], v156
	ds_read_b128 v[190:193], v156 offset:1024
	ds_read_b128 v[194:197], v156 offset:2048
	ds_read_b128 v[198:201], v156 offset:3072
	ds_read_b128 v[202:205], v156 offset:4096
	ds_read_b128 v[206:209], v156 offset:5120
	ds_read_b128 v[210:213], v156 offset:6144
	ds_read_b128 v[214:217], v156 offset:7168
	global_load_lds_dwordx4 v[148:149], off
	v_lshl_add_u64 v[148:149], s[6:7], 0, v[138:139]
	s_add_i32 m0, s58, 0xe000
	s_nop 0
	global_load_lds_dwordx4 v[148:149], off
	s_waitcnt vmcnt(8)
	s_waitcnt lgkmcnt(0)
	s_barrier
	s_waitcnt lgkmcnt(0)
	v_mfma_f32_16x16x32_bf16 v[122:125], v[144:147], v[186:189], v[122:125]
	v_mfma_f32_16x16x32_bf16 v[126:129], v[162:165], v[186:189], v[126:129]
	v_mfma_f32_16x16x32_bf16 v[110:113], v[144:147], v[194:197], v[110:113]
	v_mfma_f32_16x16x32_bf16 v[106:109], v[162:165], v[194:197], v[106:109]
	v_mfma_f32_16x16x32_bf16 v[94:97], v[144:147], v[202:205], v[94:97]
	v_mfma_f32_16x16x32_bf16 v[90:93], v[162:165], v[202:205], v[90:93]
	v_mfma_f32_16x16x32_bf16 v[78:81], v[144:147], v[210:213], v[78:81]
	v_mfma_f32_16x16x32_bf16 v[74:77], v[162:165], v[210:213], v[74:77]
	v_mfma_f32_16x16x32_bf16 v[122:125], v[158:161], v[190:193], v[122:125]
	v_mfma_f32_16x16x32_bf16 v[126:129], v[166:169], v[190:193], v[126:129]
	v_mfma_f32_16x16x32_bf16 v[110:113], v[158:161], v[198:201], v[110:113]
	v_mfma_f32_16x16x32_bf16 v[106:109], v[166:169], v[198:201], v[106:109]
	v_mfma_f32_16x16x32_bf16 v[94:97], v[158:161], v[206:209], v[94:97]
	v_mfma_f32_16x16x32_bf16 v[90:93], v[166:169], v[206:209], v[90:93]
	v_mfma_f32_16x16x32_bf16 v[78:81], v[158:161], v[214:217], v[78:81]
	v_mfma_f32_16x16x32_bf16 v[74:77], v[166:169], v[214:217], v[74:77]
	v_mfma_f32_16x16x32_bf16 v[118:121], v[170:173], v[186:189], v[118:121]
	v_mfma_f32_16x16x32_bf16 v[114:117], v[178:181], v[186:189], v[114:117]
	v_mfma_f32_16x16x32_bf16 v[102:105], v[170:173], v[194:197], v[102:105]
	v_mfma_f32_16x16x32_bf16 v[98:101], v[178:181], v[194:197], v[98:101]
	v_mfma_f32_16x16x32_bf16 v[86:89], v[170:173], v[202:205], v[86:89]
	v_mfma_f32_16x16x32_bf16 v[82:85], v[178:181], v[202:205], v[82:85]
	v_mfma_f32_16x16x32_bf16 v[70:73], v[170:173], v[210:213], v[70:73]
	v_mfma_f32_16x16x32_bf16 v[66:69], v[178:181], v[210:213], v[66:69]
	v_mfma_f32_16x16x32_bf16 v[118:121], v[174:177], v[190:193], v[118:121]
	v_mfma_f32_16x16x32_bf16 v[114:117], v[182:185], v[190:193], v[114:117]
	v_mfma_f32_16x16x32_bf16 v[102:105], v[174:177], v[198:201], v[102:105]
	v_mfma_f32_16x16x32_bf16 v[98:101], v[182:185], v[198:201], v[98:101]
	v_mfma_f32_16x16x32_bf16 v[86:89], v[174:177], v[206:209], v[86:89]
	v_mfma_f32_16x16x32_bf16 v[82:85], v[182:185], v[206:209], v[82:85]
	v_mfma_f32_16x16x32_bf16 v[70:73], v[174:177], v[214:217], v[70:73]
	v_mfma_f32_16x16x32_bf16 v[66:69], v[182:185], v[214:217], v[66:69]
	s_barrier
	s_add_i32 s53, s76, s57
	v_lshl_add_u64 v[148:149], s[84:85], 0, v[132:133]
	s_mov_b32 m0, s53
	ds_read_b128 v[186:189], v156 offset:16384
	ds_read_b128 v[190:193], v156 offset:17408
	ds_read_b128 v[194:197], v156 offset:18432
	ds_read_b128 v[198:201], v156 offset:19456
	ds_read_b128 v[202:205], v156 offset:20480
	ds_read_b128 v[206:209], v156 offset:21504
	ds_read_b128 v[210:213], v156 offset:22528
	ds_read_b128 v[214:217], v156 offset:23552
	global_load_lds_dwordx4 v[148:149], off
	s_add_i32 m0, s53, 0x2000
	v_lshl_add_u64 v[218:219], s[84:85], 0, v[136:137]
	s_add_u32 s84, s84, s10
	s_addc_u32 s85, s85, s11
	s_add_i32 s53, s77, s57
	global_load_lds_dwordx4 v[218:219], off
	v_lshl_add_u64 v[220:221], s[84:85], 0, v[132:133]
	s_mov_b32 m0, s53
	v_lshl_add_u64 v[222:223], s[84:85], 0, v[136:137]
	global_load_lds_dwordx4 v[220:221], off
	s_add_i32 m0, s53, 0x2000
	v_lshl_add_u64 v[224:225], s[50:51], 0, v[130:131]
	global_load_lds_dwordx4 v[222:223], off
	s_mov_b32 m0, s58
	v_lshl_add_u64 v[226:227], s[50:51], 0, v[134:135]
	global_load_lds_dwordx4 v[224:225], off
	s_mov_b32 m0, s59
	s_nop 0
	global_load_lds_dwordx4 v[226:227], off
	s_waitcnt vmcnt(8)
	s_waitcnt lgkmcnt(0)
	s_barrier
; #define PG8_STAGE(bufoff, gbase, voff) do { _Pragma("unroll") for (int _i = 0; _i < 2; ++_i) \
;         __builtin_amdgcn_global_load_lds((const unsigned*)((const char*)(gbase) + (voff)[_i]), (PG8_LAS unsigned*)(lds + (bufoff) + ldsw + _i * 8192), 16, 0, 0); } while (0)
; #define PG8_LDA(dst, b, h) do { _Pragma("unroll") for (int m = 0; m < 4; ++m) _Pragma("unroll") for (int k = 0; k < 2; ++k) dst[m][k] = *(const PG8_LAS bf16x8*)(lds + PG8_SA(b, h) + aoff + m * 2048 + k * 1024); } while (0)
; #define PG8_LDB(dst, b, h) do { _Pragma("unroll") for (int n = 0; n < 2; ++n) _Pragma("unroll") for (int k = 0; k < 2; ++k) dst[n][k] = *(const PG8_LAS bf16x8*)(lds + PG8_SB(b, h) + boff + n * 2048 + k * 1024); } while (0)
; #define PG8_MMA(ai, bj, At, Bt) do { __builtin_amdgcn_s_setprio(1); _Pragma("unroll") for (int m = 0; m < 4; ++m) _Pragma("unroll") for (int n = 0; n < 2; ++n) _Pragma("unroll") for (int k = 0; k < 2; ++k) \
;         acc[ai][bj][m][n] = __builtin_amdgcn_mfma_f32_16x16x32_bf16(Bt[n][k], At[m][k], acc[ai][bj][m][n], 0, 0, 0); __builtin_amdgcn_s_setprio(0); } while (0)
; #define PG8_WAIT_V(n) asm volatile("s_waitcnt vmcnt(" #n ")" ::: "memory")
; #define PG8_WAIT_L(n) asm volatile("s_waitcnt lgkmcnt(" #n ")" ::: "memory")
; #define PG8_BAR __builtin_amdgcn_s_barrier()
; #define PG8_SCHED __builtin_amdgcn_sched_barrier(0)
; template <class Epi, class Sched, bool ALIGN_EPI = false, bool SP2 = false>
; __device__ __forceinline__ void gemm_phase(PG8_LAS unsigned char* lds, const Gemm g, const Sched& S, const Epi& E) {
;     ...
;             PG8_WAIT_V(8); PG8_WAIT_L(0); PG8_BAR; PG8_MMA(1, 0, At, B0); PG8_MMA(1, 1, At, B1); PG8_BAR; PG8_SCHED;
;             PG8_LDB(B0, 1, 0); PG8_LDB(B1, 1, 1); PG8_SCHED; PG8_LDA(At, 1, 0); PG8_STAGE(PG8_SA(0, 1), a2 + hstepA, voffA);
;             PG8_WAIT_V(8); PG8_WAIT_L(0); PG8_BAR; PG8_MMA(0, 0, At, B0); PG8_MMA(0, 1, At, B1); PG8_BAR; PG8_SCHED;
	s_waitcnt lgkmcnt(0)
	v_mfma_f32_16x16x32_bf16 v[62:65], v[144:147], v[186:189], v[62:65]
	v_mfma_f32_16x16x32_bf16 v[58:61], v[162:165], v[186:189], v[58:61]
	v_mfma_f32_16x16x32_bf16 v[46:49], v[144:147], v[194:197], v[46:49]
	v_mfma_f32_16x16x32_bf16 v[42:45], v[162:165], v[194:197], v[42:45]
	v_mfma_f32_16x16x32_bf16 v[30:33], v[144:147], v[202:205], v[30:33]
	v_mfma_f32_16x16x32_bf16 v[26:29], v[162:165], v[202:205], v[26:29]
	v_mfma_f32_16x16x32_bf16 v[14:17], v[144:147], v[210:213], v[14:17]
	v_mfma_f32_16x16x32_bf16 v[10:13], v[162:165], v[210:213], v[10:13]
	v_mfma_f32_16x16x32_bf16 v[62:65], v[158:161], v[190:193], v[62:65]
	v_mfma_f32_16x16x32_bf16 v[58:61], v[166:169], v[190:193], v[58:61]
	v_mfma_f32_16x16x32_bf16 v[46:49], v[158:161], v[198:201], v[46:49]
	v_mfma_f32_16x16x32_bf16 v[42:45], v[166:169], v[198:201], v[42:45]
	v_mfma_f32_16x16x32_bf16 v[30:33], v[158:161], v[206:209], v[30:33]
	v_mfma_f32_16x16x32_bf16 v[26:29], v[166:169], v[206:209], v[26:29]
	v_mfma_f32_16x16x32_bf16 v[14:17], v[158:161], v[214:217], v[14:17]
	v_mfma_f32_16x16x32_bf16 v[10:13], v[166:169], v[214:217], v[10:13]
	v_mfma_f32_16x16x32_bf16 v[54:57], v[170:173], v[186:189], v[54:57]
	v_mfma_f32_16x16x32_bf16 v[50:53], v[178:181], v[186:189], v[50:53]
	v_mfma_f32_16x16x32_bf16 v[38:41], v[170:173], v[194:197], v[38:41]
	v_mfma_f32_16x16x32_bf16 v[34:37], v[178:181], v[194:197], v[34:37]
	v_mfma_f32_16x16x32_bf16 v[22:25], v[170:173], v[202:205], v[22:25]
	v_mfma_f32_16x16x32_bf16 v[18:21], v[178:181], v[202:205], v[18:21]
	v_mfma_f32_16x16x32_bf16 v[6:9], v[170:173], v[210:213], v[6:9]
	v_mfma_f32_16x16x32_bf16 v[2:5], v[178:181], v[210:213], v[2:5]
	v_mfma_f32_16x16x32_bf16 v[54:57], v[174:177], v[190:193], v[54:57]
	v_mfma_f32_16x16x32_bf16 v[50:53], v[182:185], v[190:193], v[50:53]
	v_mfma_f32_16x16x32_bf16 v[38:41], v[174:177], v[198:201], v[38:41]
	v_mfma_f32_16x16x32_bf16 v[34:37], v[182:185], v[198:201], v[34:37]
	v_mfma_f32_16x16x32_bf16 v[22:25], v[174:177], v[206:209], v[22:25]
	v_mfma_f32_16x16x32_bf16 v[18:21], v[182:185], v[206:209], v[18:21]
	v_mfma_f32_16x16x32_bf16 v[6:9], v[174:177], v[214:217], v[6:9]
	v_mfma_f32_16x16x32_bf16 v[2:5], v[182:185], v[214:217], v[2:5]
	s_barrier
	s_add_i32 s53, 0, 0x18000
	v_add_u32_e32 v157, s53, v152
	s_add_i32 s84, 0, 0x1c000
	ds_read_b128 v[144:147], v157
	ds_read_b128 v[158:161], v157 offset:1024
	ds_read_b128 v[162:165], v157 offset:2048
	ds_read_b128 v[166:169], v157 offset:3072
	v_add_u32_e32 v157, s84, v152
	ds_read_b128 v[170:173], v157
	ds_read_b128 v[174:177], v157 offset:1024
	ds_read_b128 v[178:181], v157 offset:2048
	ds_read_b128 v[182:185], v157 offset:3072
	s_add_u32 s50, s50, s8
	s_addc_u32 s51, s51, s9
	s_mov_b32 m0, s60
	v_lshl_add_u64 v[228:229], s[50:51], 0, v[130:131]
	ds_read_b128 v[186:189], v156 offset:32768
	ds_read_b128 v[190:193], v156 offset:33792
	ds_read_b128 v[194:197], v156 offset:34816
	ds_read_b128 v[198:201], v156 offset:35840
	ds_read_b128 v[202:205], v156 offset:36864
	ds_read_b128 v[206:209], v156 offset:37888
	ds_read_b128 v[210:213], v156 offset:38912
	ds_read_b128 v[214:217], v156 offset:39936
	global_load_lds_dwordx4 v[228:229], off
	v_lshl_add_u64 v[228:229], s[50:51], 0, v[134:135]
	s_mov_b32 m0, s61
	s_nop 0
	global_load_lds_dwordx4 v[228:229], off
	s_waitcnt vmcnt(8)
	s_waitcnt lgkmcnt(0)
	s_barrier
	s_waitcnt lgkmcnt(0)
	v_mfma_f32_16x16x32_bf16 v[122:125], v[144:147], v[186:189], v[122:125]
	v_mfma_f32_16x16x32_bf16 v[126:129], v[162:165], v[186:189], v[126:129]
	v_mfma_f32_16x16x32_bf16 v[110:113], v[144:147], v[194:197], v[110:113]
	v_mfma_f32_16x16x32_bf16 v[106:109], v[162:165], v[194:197], v[106:109]
	v_mfma_f32_16x16x32_bf16 v[94:97], v[144:147], v[202:205], v[94:97]
	v_mfma_f32_16x16x32_bf16 v[90:93], v[162:165], v[202:205], v[90:93]
	v_mfma_f32_16x16x32_bf16 v[78:81], v[144:147], v[210:213], v[78:81]
	v_mfma_f32_16x16x32_bf16 v[74:77], v[162:165], v[210:213], v[74:77]
	v_mfma_f32_16x16x32_bf16 v[122:125], v[158:161], v[190:193], v[122:125]
	v_mfma_f32_16x16x32_bf16 v[126:129], v[166:169], v[190:193], v[126:129]
	v_mfma_f32_16x16x32_bf16 v[110:113], v[158:161], v[198:201], v[110:113]
	v_mfma_f32_16x16x32_bf16 v[106:109], v[166:169], v[198:201], v[106:109]
	v_mfma_f32_16x16x32_bf16 v[94:97], v[158:161], v[206:209], v[94:97]
	v_mfma_f32_16x16x32_bf16 v[90:93], v[166:169], v[206:209], v[90:93]
	v_mfma_f32_16x16x32_bf16 v[78:81], v[158:161], v[214:217], v[78:81]
	v_mfma_f32_16x16x32_bf16 v[74:77], v[166:169], v[214:217], v[74:77]
	v_mfma_f32_16x16x32_bf16 v[118:121], v[170:173], v[186:189], v[118:121]
	v_mfma_f32_16x16x32_bf16 v[114:117], v[178:181], v[186:189], v[114:117]
	v_mfma_f32_16x16x32_bf16 v[102:105], v[170:173], v[194:197], v[102:105]
	v_mfma_f32_16x16x32_bf16 v[98:101], v[178:181], v[194:197], v[98:101]
	v_mfma_f32_16x16x32_bf16 v[86:89], v[170:173], v[202:205], v[86:89]
	v_mfma_f32_16x16x32_bf16 v[82:85], v[178:181], v[202:205], v[82:85]
	v_mfma_f32_16x16x32_bf16 v[70:73], v[170:173], v[210:213], v[70:73]
	v_mfma_f32_16x16x32_bf16 v[66:69], v[178:181], v[210:213], v[66:69]
	v_mfma_f32_16x16x32_bf16 v[118:121], v[174:177], v[190:193], v[118:121]
	v_mfma_f32_16x16x32_bf16 v[114:117], v[182:185], v[190:193], v[114:117]
	v_mfma_f32_16x16x32_bf16 v[102:105], v[174:177], v[198:201], v[102:105]
	v_mfma_f32_16x16x32_bf16 v[98:101], v[182:185], v[198:201], v[98:101]
	v_mfma_f32_16x16x32_bf16 v[86:89], v[174:177], v[206:209], v[86:89]
	v_mfma_f32_16x16x32_bf16 v[82:85], v[182:185], v[206:209], v[82:85]
	v_mfma_f32_16x16x32_bf16 v[70:73], v[174:177], v[214:217], v[70:73]
	v_mfma_f32_16x16x32_bf16 v[66:69], v[182:185], v[214:217], v[66:69]
	s_barrier
; #define PG8_STAGE(bufoff, gbase, voff) do { _Pragma("unroll") for (int _i = 0; _i < 2; ++_i) \
;         __builtin_amdgcn_global_load_lds((const unsigned*)((const char*)(gbase) + (voff)[_i]), (PG8_LAS unsigned*)(lds + (bufoff) + ldsw + _i * 8192), 16, 0, 0); } while (0)
; #define PG8_LDA(dst, b, h) do { _Pragma("unroll") for (int m = 0; m < 4; ++m) _Pragma("unroll") for (int k = 0; k < 2; ++k) dst[m][k] = *(const PG8_LAS bf16x8*)(lds + PG8_SA(b, h) + aoff + m * 2048 + k * 1024); } while (0)
; #define PG8_MMA(ai, bj, At, Bt) do { __builtin_amdgcn_s_setprio(1); _Pragma("unroll") for (int m = 0; m < 4; ++m) _Pragma("unroll") for (int n = 0; n < 2; ++n) _Pragma("unroll") for (int k = 0; k < 2; ++k) \
;         acc[ai][bj][m][n] = __builtin_amdgcn_mfma_f32_16x16x32_bf16(Bt[n][k], At[m][k], acc[ai][bj][m][n], 0, 0, 0); __builtin_amdgcn_s_setprio(0); } while (0)
; #define PG8_WAIT_V(n) asm volatile("s_waitcnt vmcnt(" #n ")" ::: "memory")
; #define PG8_WAIT_L(n) asm volatile("s_waitcnt lgkmcnt(" #n ")" ::: "memory")
; #define PG8_BAR __builtin_amdgcn_s_barrier()
; #define PG8_SCHED __builtin_amdgcn_sched_barrier(0)
; template <class Epi, class Sched, bool ALIGN_EPI = false, bool SP2 = false>
; __device__ __forceinline__ void gemm_phase(PG8_LAS unsigned char* lds, const Gemm g, const Sched& S, const Epi& E) {
;     ...
;         for (int t = 0; t < nt; t += 2) {
;     ...
;             PG8_LDA(At, 1, 1); PG8_STAGE(PG8_SB(1, 0), b3, voffB); PG8_STAGE(PG8_SB(1, 1), b3 + hstepB, voffB); PG8_STAGE(PG8_SA(1, 0), a3, voffA);
;             PG8_WAIT_V(8); PG8_WAIT_L(0); PG8_BAR; PG8_MMA(1, 0, At, B0); PG8_MMA(1, 1, At, B1); PG8_BAR; PG8_SCHED;
	s_add_i32 s50, s53, s57
	v_lshl_add_u64 v[148:149], v[148:149], 0, s[38:39]
	s_mov_b32 m0, s50
	ds_read_b128 v[186:189], v156 offset:49152
	ds_read_b128 v[190:193], v156 offset:50176
	ds_read_b128 v[194:197], v156 offset:51200
	ds_read_b128 v[198:201], v156 offset:52224
	ds_read_b128 v[202:205], v156 offset:53248
	ds_read_b128 v[206:209], v156 offset:54272
	ds_read_b128 v[210:213], v156 offset:55296
	ds_read_b128 v[214:217], v156 offset:56320
	global_load_lds_dwordx4 v[148:149], off
	v_lshl_add_u64 v[148:149], v[218:219], 0, s[38:39]
	s_add_i32 m0, s50, 0x2000
	s_add_i32 s50, s84, s57
	global_load_lds_dwordx4 v[148:149], off
	v_lshl_add_u64 v[148:149], v[220:221], 0, s[38:39]
	s_mov_b32 m0, s50
	s_nop 0
	global_load_lds_dwordx4 v[148:149], off
	v_lshl_add_u64 v[148:149], v[222:223], 0, s[38:39]
	s_add_i32 m0, s50, 0x2000
	s_nop 0
	global_load_lds_dwordx4 v[148:149], off
	v_lshl_add_u64 v[148:149], v[224:225], 0, s[38:39]
	s_mov_b32 m0, s65
	s_nop 0
	global_load_lds_dwordx4 v[148:149], off
	v_lshl_add_u64 v[148:149], v[226:227], 0, s[38:39]
	s_mov_b32 m0, s66
	s_nop 0
	global_load_lds_dwordx4 v[148:149], off
	s_waitcnt vmcnt(8)
	s_waitcnt lgkmcnt(0)
	s_barrier
	s_waitcnt lgkmcnt(0)
	v_mfma_f32_16x16x32_bf16 v[62:65], v[144:147], v[186:189], v[62:65]
	v_mfma_f32_16x16x32_bf16 v[58:61], v[162:165], v[186:189], v[58:61]
	v_mfma_f32_16x16x32_bf16 v[46:49], v[144:147], v[194:197], v[46:49]
	v_mfma_f32_16x16x32_bf16 v[42:45], v[162:165], v[194:197], v[42:45]
	v_mfma_f32_16x16x32_bf16 v[30:33], v[144:147], v[202:205], v[30:33]
	v_mfma_f32_16x16x32_bf16 v[26:29], v[162:165], v[202:205], v[26:29]
	v_mfma_f32_16x16x32_bf16 v[14:17], v[144:147], v[210:213], v[14:17]
	v_mfma_f32_16x16x32_bf16 v[10:13], v[162:165], v[210:213], v[10:13]
	v_mfma_f32_16x16x32_bf16 v[62:65], v[158:161], v[190:193], v[62:65]
	v_mfma_f32_16x16x32_bf16 v[58:61], v[166:169], v[190:193], v[58:61]
	v_mfma_f32_16x16x32_bf16 v[46:49], v[158:161], v[198:201], v[46:49]
	v_mfma_f32_16x16x32_bf16 v[42:45], v[166:169], v[198:201], v[42:45]
	v_mfma_f32_16x16x32_bf16 v[30:33], v[158:161], v[206:209], v[30:33]
	v_mfma_f32_16x16x32_bf16 v[26:29], v[166:169], v[206:209], v[26:29]
	v_mfma_f32_16x16x32_bf16 v[14:17], v[158:161], v[214:217], v[14:17]
	v_mfma_f32_16x16x32_bf16 v[10:13], v[166:169], v[214:217], v[10:13]
	v_mfma_f32_16x16x32_bf16 v[54:57], v[170:173], v[186:189], v[54:57]
	v_mfma_f32_16x16x32_bf16 v[50:53], v[178:181], v[186:189], v[50:53]
	v_mfma_f32_16x16x32_bf16 v[38:41], v[170:173], v[194:197], v[38:41]
	v_mfma_f32_16x16x32_bf16 v[34:37], v[178:181], v[194:197], v[34:37]
	v_mfma_f32_16x16x32_bf16 v[22:25], v[170:173], v[202:205], v[22:25]
	v_mfma_f32_16x16x32_bf16 v[18:21], v[178:181], v[202:205], v[18:21]
	v_mfma_f32_16x16x32_bf16 v[6:9], v[170:173], v[210:213], v[6:9]
	v_mfma_f32_16x16x32_bf16 v[2:5], v[178:181], v[210:213], v[2:5]
	v_mfma_f32_16x16x32_bf16 v[54:57], v[174:177], v[190:193], v[54:57]
	v_mfma_f32_16x16x32_bf16 v[50:53], v[182:185], v[190:193], v[50:53]
	v_mfma_f32_16x16x32_bf16 v[38:41], v[174:177], v[198:201], v[38:41]
	v_mfma_f32_16x16x32_bf16 v[34:37], v[182:185], v[198:201], v[34:37]
	v_mfma_f32_16x16x32_bf16 v[22:25], v[174:177], v[206:209], v[22:25]
	v_mfma_f32_16x16x32_bf16 v[18:21], v[182:185], v[206:209], v[18:21]
	v_mfma_f32_16x16x32_bf16 v[6:9], v[174:177], v[214:217], v[6:9]
	v_mfma_f32_16x16x32_bf16 v[2:5], v[182:185], v[214:217], v[2:5]
	s_barrier
	s_add_u32 s82, s82, 0x100
	s_addc_u32 s83, s83, 0
	s_add_u32 s6, s6, 0x100
	s_addc_u32 s7, s7, 0
	s_cmp_ge_i32 s52, s64
	s_mov_b32 s50, s52
	s_cbranch_scc0 .LBB0_424

; #define PG8_STAGE(bufoff, gbase, voff) do { _Pragma("unroll") for (int _i = 0; _i < 2; ++_i) \
;         __builtin_amdgcn_global_load_lds((const unsigned*)((const char*)(gbase) + (voff)[_i]), (PG8_LAS unsigned*)(lds + (bufoff) + ldsw + _i * 8192), 16, 0, 0); } while (0)
; #define PG8_LDA(dst, b, h) do { _Pragma("unroll") for (int m = 0; m < 4; ++m) _Pragma("unroll") for (int k = 0; k < 2; ++k) dst[m][k] = *(const PG8_LAS bf16x8*)(lds + PG8_SA(b, h) + aoff + m * 2048 + k * 1024); } while (0)
; #define PG8_LDB(dst, b, h) do { _Pragma("unroll") for (int n = 0; n < 2; ++n) _Pragma("unroll") for (int k = 0; k < 2; ++k) dst[n][k] = *(const PG8_LAS bf16x8*)(lds + PG8_SB(b, h) + boff + n * 2048 + k * 1024); } while (0)
; #define PG8_MMA(ai, bj, At, Bt) do { __builtin_amdgcn_s_setprio(1); _Pragma("unroll") for (int m = 0; m < 4; ++m) _Pragma("unroll") for (int n = 0; n < 2; ++n) _Pragma("unroll") for (int k = 0; k < 2; ++k) \
;         acc[ai][bj][m][n] = __builtin_amdgcn_mfma_f32_16x16x32_bf16(Bt[n][k], At[m][k], acc[ai][bj][m][n], 0, 0, 0); __builtin_amdgcn_s_setprio(0); } while (0)
; #define PG8_WAIT_V(n) asm volatile("s_waitcnt vmcnt(" #n ")" ::: "memory")
; #define PG8_WAIT_L(n) asm volatile("s_waitcnt lgkmcnt(" #n ")" ::: "memory")
; #define PG8_BAR __builtin_amdgcn_s_barrier()
; #define PG8_SCHED __builtin_amdgcn_sched_barrier(0)
; template <class Epi, class Sched, bool ALIGN_EPI = false, bool SP2 = false>
; __device__ __forceinline__ void gemm_phase(PG8_LAS unsigned char* lds, const Gemm g, const Sched& S, const Epi& E) {
;     ...
;             PG8_LDB(B0, 0, 0); PG8_LDB(B1, 0, 1); PG8_SCHED; PG8_LDA(At, 0, 0); PG8_STAGE(PG8_SA(1, 1), a1 + hstepA, voffA);
;             PG8_WAIT_V(8); PG8_WAIT_L(0); PG8_BAR; PG8_MMA(0, 0, At, B0); PG8_MMA(0, 1, At, B1); PG8_BAR; PG8_SCHED;
;             PG8_LDA(At, 0, 1); PG8_STAGE(PG8_SB(0, 0), b2, voffB); PG8_STAGE(PG8_SB(0, 1), b2 + hstepB, voffB); PG8_STAGE(PG8_SA(0, 0), a2, voffA);
.LBB0_676:
	ds_read_b128 v[152:155], v149
	ds_read_b128 v[156:159], v149 offset:1024
	ds_read_b128 v[160:163], v149 offset:2048
	ds_read_b128 v[164:167], v149 offset:3072
	ds_read_b128 v[168:171], v150
	ds_read_b128 v[172:175], v150 offset:1024
	ds_read_b128 v[176:179], v150 offset:2048
	ds_read_b128 v[180:183], v150 offset:3072
	s_add_i32 s83, s52, 2
	s_add_u32 s84, s50, 0x80
	s_addc_u32 s53, s51, 0
	s_cmp_eq_u32 s71, s52
	s_cselect_b32 s52, s6, s84
	s_cselect_b32 s53, s7, s53
	s_cselect_b32 s85, s49, s82
	s_cselect_b32 s84, s48, s81
	v_lshl_add_u64 v[144:145], s[50:51], 0, v[140:141]
	s_add_i32 m0, s63, 0xc000
	ds_read_b128 v[184:187], v151
	ds_read_b128 v[188:191], v151 offset:1024
	ds_read_b128 v[192:195], v151 offset:2048
	ds_read_b128 v[196:199], v151 offset:3072
	ds_read_b128 v[200:203], v151 offset:4096
	ds_read_b128 v[204:207], v151 offset:5120
	ds_read_b128 v[208:211], v151 offset:6144
	ds_read_b128 v[212:215], v151 offset:7168
	global_load_lds_dwordx4 v[144:145], off
	v_lshl_add_u64 v[144:145], s[50:51], 0, v[138:139]
	s_add_i32 m0, s63, 0xe000
	s_nop 0
	global_load_lds_dwordx4 v[144:145], off
	s_waitcnt vmcnt(8)
	s_waitcnt lgkmcnt(0)
	s_barrier
	s_waitcnt lgkmcnt(0)
	v_mfma_f32_16x16x32_bf16 v[118:121], v[152:155], v[184:187], v[118:121]
	v_mfma_f32_16x16x32_bf16 v[114:117], v[160:163], v[184:187], v[114:117]
	v_mfma_f32_16x16x32_bf16 v[102:105], v[152:155], v[192:195], v[102:105]
	v_mfma_f32_16x16x32_bf16 v[98:101], v[160:163], v[192:195], v[98:101]
	v_mfma_f32_16x16x32_bf16 v[86:89], v[152:155], v[200:203], v[86:89]
	v_mfma_f32_16x16x32_bf16 v[82:85], v[160:163], v[200:203], v[82:85]
	v_mfma_f32_16x16x32_bf16 v[70:73], v[152:155], v[208:211], v[70:73]
	v_mfma_f32_16x16x32_bf16 v[66:69], v[160:163], v[208:211], v[66:69]
	v_mfma_f32_16x16x32_bf16 v[118:121], v[156:159], v[188:191], v[118:121]
	v_mfma_f32_16x16x32_bf16 v[114:117], v[164:167], v[188:191], v[114:117]
	v_mfma_f32_16x16x32_bf16 v[102:105], v[156:159], v[196:199], v[102:105]
	v_mfma_f32_16x16x32_bf16 v[98:101], v[164:167], v[196:199], v[98:101]
	v_mfma_f32_16x16x32_bf16 v[86:89], v[156:159], v[204:207], v[86:89]
	v_mfma_f32_16x16x32_bf16 v[82:85], v[164:167], v[204:207], v[82:85]
	v_mfma_f32_16x16x32_bf16 v[70:73], v[156:159], v[212:215], v[70:73]
	v_mfma_f32_16x16x32_bf16 v[66:69], v[164:167], v[212:215], v[66:69]
	v_mfma_f32_16x16x32_bf16 v[126:129], v[168:171], v[184:187], v[126:129]
	v_mfma_f32_16x16x32_bf16 v[122:125], v[176:179], v[184:187], v[122:125]
	v_mfma_f32_16x16x32_bf16 v[110:113], v[168:171], v[192:195], v[110:113]
	v_mfma_f32_16x16x32_bf16 v[106:109], v[176:179], v[192:195], v[106:109]
	v_mfma_f32_16x16x32_bf16 v[94:97], v[168:171], v[200:203], v[94:97]
	v_mfma_f32_16x16x32_bf16 v[90:93], v[176:179], v[200:203], v[90:93]
	v_mfma_f32_16x16x32_bf16 v[78:81], v[168:171], v[208:211], v[78:81]
	v_mfma_f32_16x16x32_bf16 v[74:77], v[176:179], v[208:211], v[74:77]
	v_mfma_f32_16x16x32_bf16 v[126:129], v[172:175], v[188:191], v[126:129]
	v_mfma_f32_16x16x32_bf16 v[122:125], v[180:183], v[188:191], v[122:125]
	v_mfma_f32_16x16x32_bf16 v[110:113], v[172:175], v[196:199], v[110:113]
	v_mfma_f32_16x16x32_bf16 v[106:109], v[180:183], v[196:199], v[106:109]
	v_mfma_f32_16x16x32_bf16 v[94:97], v[172:175], v[204:207], v[94:97]
	v_mfma_f32_16x16x32_bf16 v[90:93], v[180:183], v[204:207], v[90:93]
	v_mfma_f32_16x16x32_bf16 v[78:81], v[172:175], v[212:215], v[78:81]
	v_mfma_f32_16x16x32_bf16 v[74:77], v[180:183], v[212:215], v[74:77]
	s_barrier
	s_add_i32 s86, s75, s56
	v_lshl_add_u64 v[144:145], s[84:85], 0, v[134:135]
	s_mov_b32 m0, s86
	ds_read_b128 v[184:187], v151 offset:16384
	ds_read_b128 v[188:191], v151 offset:17408
	ds_read_b128 v[192:195], v151 offset:18432
	ds_read_b128 v[196:199], v151 offset:19456
	ds_read_b128 v[200:203], v151 offset:20480
	ds_read_b128 v[204:207], v151 offset:21504
	ds_read_b128 v[208:211], v151 offset:22528
	ds_read_b128 v[212:215], v151 offset:23552
	global_load_lds_dwordx4 v[144:145], off
	s_add_i32 m0, s86, 0x2000
	v_lshl_add_u64 v[216:217], s[84:85], 0, v[130:131]
	s_add_u32 s84, s84, s10
	s_addc_u32 s85, s85, s11
	s_add_i32 s86, s76, s56
	global_load_lds_dwordx4 v[216:217], off
	v_lshl_add_u64 v[218:219], s[84:85], 0, v[134:135]
	s_mov_b32 m0, s86
	v_lshl_add_u64 v[220:221], s[84:85], 0, v[130:131]
	global_load_lds_dwordx4 v[218:219], off
	s_add_i32 m0, s86, 0x2000
	v_lshl_add_u64 v[222:223], s[52:53], 0, v[136:137]
	global_load_lds_dwordx4 v[220:221], off
	s_mov_b32 m0, s63
	v_lshl_add_u64 v[224:225], s[52:53], 0, v[132:133]
	global_load_lds_dwordx4 v[222:223], off
	s_mov_b32 m0, s64
	s_nop 0
	global_load_lds_dwordx4 v[224:225], off
	s_waitcnt vmcnt(8)
	s_waitcnt lgkmcnt(0)
	s_barrier
; #define PG8_STAGE(bufoff, gbase, voff) do { _Pragma("unroll") for (int _i = 0; _i < 2; ++_i) \
;         __builtin_amdgcn_global_load_lds((const unsigned*)((const char*)(gbase) + (voff)[_i]), (PG8_LAS unsigned*)(lds + (bufoff) + ldsw + _i * 8192), 16, 0, 0); } while (0)
; #define PG8_LDA(dst, b, h) do { _Pragma("unroll") for (int m = 0; m < 4; ++m) _Pragma("unroll") for (int k = 0; k < 2; ++k) dst[m][k] = *(const PG8_LAS bf16x8*)(lds + PG8_SA(b, h) + aoff + m * 2048 + k * 1024); } while (0)
; #define PG8_LDB(dst, b, h) do { _Pragma("unroll") for (int n = 0; n < 2; ++n) _Pragma("unroll") for (int k = 0; k < 2; ++k) dst[n][k] = *(const PG8_LAS bf16x8*)(lds + PG8_SB(b, h) + boff + n * 2048 + k * 1024); } while (0)
; #define PG8_MMA(ai, bj, At, Bt) do { __builtin_amdgcn_s_setprio(1); _Pragma("unroll") for (int m = 0; m < 4; ++m) _Pragma("unroll") for (int n = 0; n < 2; ++n) _Pragma("unroll") for (int k = 0; k < 2; ++k) \
;         acc[ai][bj][m][n] = __builtin_amdgcn_mfma_f32_16x16x32_bf16(Bt[n][k], At[m][k], acc[ai][bj][m][n], 0, 0, 0); __builtin_amdgcn_s_setprio(0); } while (0)
; #define PG8_WAIT_V(n) asm volatile("s_waitcnt vmcnt(" #n ")" ::: "memory")
; #define PG8_WAIT_L(n) asm volatile("s_waitcnt lgkmcnt(" #n ")" ::: "memory")
; #define PG8_BAR __builtin_amdgcn_s_barrier()
; #define PG8_SCHED __builtin_amdgcn_sched_barrier(0)
; template <class Epi, class Sched, bool ALIGN_EPI = false, bool SP2 = false>
; __device__ __forceinline__ void gemm_phase(PG8_LAS unsigned char* lds, const Gemm g, const Sched& S, const Epi& E) {
;     ...
;             PG8_WAIT_V(8); PG8_WAIT_L(0); PG8_BAR; PG8_MMA(1, 0, At, B0); PG8_MMA(1, 1, At, B1); PG8_BAR; PG8_SCHED;
;             PG8_LDB(B0, 1, 0); PG8_LDB(B1, 1, 1); PG8_SCHED; PG8_LDA(At, 1, 0); PG8_STAGE(PG8_SA(0, 1), a2 + hstepA, voffA);
;             PG8_WAIT_V(8); PG8_WAIT_L(0); PG8_BAR; PG8_MMA(0, 0, At, B0); PG8_MMA(0, 1, At, B1); PG8_BAR; PG8_SCHED;
	s_waitcnt lgkmcnt(0)
	v_mfma_f32_16x16x32_bf16 v[54:57], v[152:155], v[184:187], v[54:57]
	v_mfma_f32_16x16x32_bf16 v[50:53], v[160:163], v[184:187], v[50:53]
	v_mfma_f32_16x16x32_bf16 v[38:41], v[152:155], v[192:195], v[38:41]
	v_mfma_f32_16x16x32_bf16 v[34:37], v[160:163], v[192:195], v[34:37]
	v_mfma_f32_16x16x32_bf16 v[22:25], v[152:155], v[200:203], v[22:25]
	v_mfma_f32_16x16x32_bf16 v[18:21], v[160:163], v[200:203], v[18:21]
	v_mfma_f32_16x16x32_bf16 v[6:9], v[152:155], v[208:211], v[6:9]
	v_mfma_f32_16x16x32_bf16 v[2:5], v[160:163], v[208:211], v[2:5]
	v_mfma_f32_16x16x32_bf16 v[54:57], v[156:159], v[188:191], v[54:57]
	v_mfma_f32_16x16x32_bf16 v[50:53], v[164:167], v[188:191], v[50:53]
	v_mfma_f32_16x16x32_bf16 v[38:41], v[156:159], v[196:199], v[38:41]
	v_mfma_f32_16x16x32_bf16 v[34:37], v[164:167], v[196:199], v[34:37]
	v_mfma_f32_16x16x32_bf16 v[22:25], v[156:159], v[204:207], v[22:25]
	v_mfma_f32_16x16x32_bf16 v[18:21], v[164:167], v[204:207], v[18:21]
	v_mfma_f32_16x16x32_bf16 v[6:9], v[156:159], v[212:215], v[6:9]
	v_mfma_f32_16x16x32_bf16 v[2:5], v[164:167], v[212:215], v[2:5]
	v_mfma_f32_16x16x32_bf16 v[62:65], v[168:171], v[184:187], v[62:65]
	v_mfma_f32_16x16x32_bf16 v[58:61], v[176:179], v[184:187], v[58:61]
	v_mfma_f32_16x16x32_bf16 v[46:49], v[168:171], v[192:195], v[46:49]
	v_mfma_f32_16x16x32_bf16 v[42:45], v[176:179], v[192:195], v[42:45]
	v_mfma_f32_16x16x32_bf16 v[30:33], v[168:171], v[200:203], v[30:33]
	v_mfma_f32_16x16x32_bf16 v[26:29], v[176:179], v[200:203], v[26:29]
	v_mfma_f32_16x16x32_bf16 v[14:17], v[168:171], v[208:211], v[14:17]
	v_mfma_f32_16x16x32_bf16 v[10:13], v[176:179], v[208:211], v[10:13]
	v_mfma_f32_16x16x32_bf16 v[62:65], v[172:175], v[188:191], v[62:65]
	v_mfma_f32_16x16x32_bf16 v[58:61], v[180:183], v[188:191], v[58:61]
	v_mfma_f32_16x16x32_bf16 v[46:49], v[172:175], v[196:199], v[46:49]
	v_mfma_f32_16x16x32_bf16 v[42:45], v[180:183], v[196:199], v[42:45]
	v_mfma_f32_16x16x32_bf16 v[30:33], v[172:175], v[204:207], v[30:33]
	v_mfma_f32_16x16x32_bf16 v[26:29], v[180:183], v[204:207], v[26:29]
	v_mfma_f32_16x16x32_bf16 v[14:17], v[172:175], v[212:215], v[14:17]
	v_mfma_f32_16x16x32_bf16 v[10:13], v[180:183], v[212:215], v[10:13]
	s_barrier
	s_add_i32 s84, 0, 0x18000
	s_add_i32 s85, 0, 0x1c000
	v_add_u32_e32 v164, s84, v147
	v_add_u32_e32 v180, s85, v147
	ds_read_b128 v[152:155], v164
	ds_read_b128 v[156:159], v164 offset:1024
	ds_read_b128 v[160:163], v164 offset:2048
	ds_read_b128 v[164:167], v164 offset:3072
	ds_read_b128 v[168:171], v180
	ds_read_b128 v[172:175], v180 offset:1024
	ds_read_b128 v[176:179], v180 offset:2048
	ds_read_b128 v[180:183], v180 offset:3072
	s_add_u32 s52, s52, s8
	s_addc_u32 s53, s53, s9
	s_mov_b32 m0, s65
	v_lshl_add_u64 v[226:227], s[52:53], 0, v[136:137]
	ds_read_b128 v[184:187], v151 offset:32768
	ds_read_b128 v[188:191], v151 offset:33792
	ds_read_b128 v[192:195], v151 offset:34816
	ds_read_b128 v[196:199], v151 offset:35840
	ds_read_b128 v[200:203], v151 offset:36864
	ds_read_b128 v[204:207], v151 offset:37888
	ds_read_b128 v[208:211], v151 offset:38912
	ds_read_b128 v[212:215], v151 offset:39936
	global_load_lds_dwordx4 v[226:227], off
	v_lshl_add_u64 v[226:227], s[52:53], 0, v[132:133]
	s_mov_b32 m0, s66
	s_nop 0
	global_load_lds_dwordx4 v[226:227], off
	s_waitcnt vmcnt(8)
	s_waitcnt lgkmcnt(0)
	s_barrier
	s_waitcnt lgkmcnt(0)
	v_mfma_f32_16x16x32_bf16 v[118:121], v[152:155], v[184:187], v[118:121]
	v_mfma_f32_16x16x32_bf16 v[114:117], v[160:163], v[184:187], v[114:117]
	v_mfma_f32_16x16x32_bf16 v[102:105], v[152:155], v[192:195], v[102:105]
	v_mfma_f32_16x16x32_bf16 v[98:101], v[160:163], v[192:195], v[98:101]
	v_mfma_f32_16x16x32_bf16 v[86:89], v[152:155], v[200:203], v[86:89]
	v_mfma_f32_16x16x32_bf16 v[82:85], v[160:163], v[200:203], v[82:85]
	v_mfma_f32_16x16x32_bf16 v[70:73], v[152:155], v[208:211], v[70:73]
	v_mfma_f32_16x16x32_bf16 v[66:69], v[160:163], v[208:211], v[66:69]
	v_mfma_f32_16x16x32_bf16 v[118:121], v[156:159], v[188:191], v[118:121]
	v_mfma_f32_16x16x32_bf16 v[114:117], v[164:167], v[188:191], v[114:117]
	v_mfma_f32_16x16x32_bf16 v[102:105], v[156:159], v[196:199], v[102:105]
	v_mfma_f32_16x16x32_bf16 v[98:101], v[164:167], v[196:199], v[98:101]
	v_mfma_f32_16x16x32_bf16 v[86:89], v[156:159], v[204:207], v[86:89]
	v_mfma_f32_16x16x32_bf16 v[82:85], v[164:167], v[204:207], v[82:85]
	v_mfma_f32_16x16x32_bf16 v[70:73], v[156:159], v[212:215], v[70:73]
	v_mfma_f32_16x16x32_bf16 v[66:69], v[164:167], v[212:215], v[66:69]
	v_mfma_f32_16x16x32_bf16 v[126:129], v[168:171], v[184:187], v[126:129]
	v_mfma_f32_16x16x32_bf16 v[122:125], v[176:179], v[184:187], v[122:125]
	v_mfma_f32_16x16x32_bf16 v[110:113], v[168:171], v[192:195], v[110:113]
	v_mfma_f32_16x16x32_bf16 v[106:109], v[176:179], v[192:195], v[106:109]
	v_mfma_f32_16x16x32_bf16 v[94:97], v[168:171], v[200:203], v[94:97]
	v_mfma_f32_16x16x32_bf16 v[90:93], v[176:179], v[200:203], v[90:93]
	v_mfma_f32_16x16x32_bf16 v[78:81], v[168:171], v[208:211], v[78:81]
	v_mfma_f32_16x16x32_bf16 v[74:77], v[176:179], v[208:211], v[74:77]
	v_mfma_f32_16x16x32_bf16 v[126:129], v[172:175], v[188:191], v[126:129]
	v_mfma_f32_16x16x32_bf16 v[122:125], v[180:183], v[188:191], v[122:125]
	v_mfma_f32_16x16x32_bf16 v[110:113], v[172:175], v[196:199], v[110:113]
	v_mfma_f32_16x16x32_bf16 v[106:109], v[180:183], v[196:199], v[106:109]
	v_mfma_f32_16x16x32_bf16 v[94:97], v[172:175], v[204:207], v[94:97]
	v_mfma_f32_16x16x32_bf16 v[90:93], v[180:183], v[204:207], v[90:93]
	v_mfma_f32_16x16x32_bf16 v[78:81], v[172:175], v[212:215], v[78:81]
	v_mfma_f32_16x16x32_bf16 v[74:77], v[180:183], v[212:215], v[74:77]
	s_barrier
; #define PG8_STAGE(bufoff, gbase, voff) do { _Pragma("unroll") for (int _i = 0; _i < 2; ++_i) \
;         __builtin_amdgcn_global_load_lds((const unsigned*)((const char*)(gbase) + (voff)[_i]), (PG8_LAS unsigned*)(lds + (bufoff) + ldsw + _i * 8192), 16, 0, 0); } while (0)
; #define PG8_LDA(dst, b, h) do { _Pragma("unroll") for (int m = 0; m < 4; ++m) _Pragma("unroll") for (int k = 0; k < 2; ++k) dst[m][k] = *(const PG8_LAS bf16x8*)(lds + PG8_SA(b, h) + aoff + m * 2048 + k * 1024); } while (0)
; #define PG8_MMA(ai, bj, At, Bt) do { __builtin_amdgcn_s_setprio(1); _Pragma("unroll") for (int m = 0; m < 4; ++m) _Pragma("unroll") for (int n = 0; n < 2; ++n) _Pragma("unroll") for (int k = 0; k < 2; ++k) \
;         acc[ai][bj][m][n] = __builtin_amdgcn_mfma_f32_16x16x32_bf16(Bt[n][k], At[m][k], acc[ai][bj][m][n], 0, 0, 0); __builtin_amdgcn_s_setprio(0); } while (0)
; #define PG8_WAIT_V(n) asm volatile("s_waitcnt vmcnt(" #n ")" ::: "memory")
; #define PG8_WAIT_L(n) asm volatile("s_waitcnt lgkmcnt(" #n ")" ::: "memory")
; #define PG8_BAR __builtin_amdgcn_s_barrier()
; #define PG8_SCHED __builtin_amdgcn_sched_barrier(0)
; template <class Epi, class Sched, bool ALIGN_EPI = false, bool SP2 = false>
; __device__ __forceinline__ void gemm_phase(PG8_LAS unsigned char* lds, const Gemm g, const Sched& S, const Epi& E) {
;     ...
;         for (int t = 0; t < nt; t += 2) {
;     ...
;             PG8_LDA(At, 1, 1); PG8_STAGE(PG8_SB(1, 0), b3, voffB); PG8_STAGE(PG8_SB(1, 1), b3 + hstepB, voffB); PG8_STAGE(PG8_SA(1, 0), a3, voffA);
;             PG8_WAIT_V(8); PG8_WAIT_L(0); PG8_BAR; PG8_MMA(1, 0, At, B0); PG8_MMA(1, 1, At, B1); PG8_BAR; PG8_SCHED;
	s_add_i32 s52, s84, s56
	v_lshl_add_u64 v[144:145], v[144:145], 0, s[34:35]
	s_mov_b32 m0, s52
	ds_read_b128 v[184:187], v151 offset:49152
	ds_read_b128 v[188:191], v151 offset:50176
	ds_read_b128 v[192:195], v151 offset:51200
	ds_read_b128 v[196:199], v151 offset:52224
	ds_read_b128 v[200:203], v151 offset:53248
	ds_read_b128 v[204:207], v151 offset:54272
	ds_read_b128 v[208:211], v151 offset:55296
	ds_read_b128 v[212:215], v151 offset:56320
	global_load_lds_dwordx4 v[144:145], off
	v_lshl_add_u64 v[144:145], v[216:217], 0, s[34:35]
	s_add_i32 m0, s52, 0x2000
	s_add_i32 s52, s85, s56
	global_load_lds_dwordx4 v[144:145], off
	v_lshl_add_u64 v[144:145], v[218:219], 0, s[34:35]
	s_mov_b32 m0, s52
	s_nop 0
	global_load_lds_dwordx4 v[144:145], off
	v_lshl_add_u64 v[144:145], v[220:221], 0, s[34:35]
	s_add_i32 m0, s52, 0x2000
	s_nop 0
	global_load_lds_dwordx4 v[144:145], off
	v_lshl_add_u64 v[144:145], v[222:223], 0, s[34:35]
	s_mov_b32 m0, s68
	s_nop 0
	global_load_lds_dwordx4 v[144:145], off
	v_lshl_add_u64 v[144:145], v[224:225], 0, s[34:35]
	s_mov_b32 m0, s69
	s_nop 0
	global_load_lds_dwordx4 v[144:145], off
	s_waitcnt vmcnt(8)
	s_waitcnt lgkmcnt(0)
	s_barrier
	s_waitcnt lgkmcnt(0)
	v_mfma_f32_16x16x32_bf16 v[54:57], v[152:155], v[184:187], v[54:57]
	v_mfma_f32_16x16x32_bf16 v[50:53], v[160:163], v[184:187], v[50:53]
	v_mfma_f32_16x16x32_bf16 v[38:41], v[152:155], v[192:195], v[38:41]
	v_mfma_f32_16x16x32_bf16 v[34:37], v[160:163], v[192:195], v[34:37]
	v_mfma_f32_16x16x32_bf16 v[22:25], v[152:155], v[200:203], v[22:25]
	v_mfma_f32_16x16x32_bf16 v[18:21], v[160:163], v[200:203], v[18:21]
	v_mfma_f32_16x16x32_bf16 v[6:9], v[152:155], v[208:211], v[6:9]
	v_mfma_f32_16x16x32_bf16 v[2:5], v[160:163], v[208:211], v[2:5]
	v_mfma_f32_16x16x32_bf16 v[54:57], v[156:159], v[188:191], v[54:57]
	v_mfma_f32_16x16x32_bf16 v[50:53], v[164:167], v[188:191], v[50:53]
	v_mfma_f32_16x16x32_bf16 v[38:41], v[156:159], v[196:199], v[38:41]
	v_mfma_f32_16x16x32_bf16 v[34:37], v[164:167], v[196:199], v[34:37]
	v_mfma_f32_16x16x32_bf16 v[22:25], v[156:159], v[204:207], v[22:25]
	v_mfma_f32_16x16x32_bf16 v[18:21], v[164:167], v[204:207], v[18:21]
	v_mfma_f32_16x16x32_bf16 v[6:9], v[156:159], v[212:215], v[6:9]
	v_mfma_f32_16x16x32_bf16 v[2:5], v[164:167], v[212:215], v[2:5]
	v_mfma_f32_16x16x32_bf16 v[62:65], v[168:171], v[184:187], v[62:65]
	v_mfma_f32_16x16x32_bf16 v[58:61], v[176:179], v[184:187], v[58:61]
	v_mfma_f32_16x16x32_bf16 v[46:49], v[168:171], v[192:195], v[46:49]
	v_mfma_f32_16x16x32_bf16 v[42:45], v[176:179], v[192:195], v[42:45]
	v_mfma_f32_16x16x32_bf16 v[30:33], v[168:171], v[200:203], v[30:33]
	v_mfma_f32_16x16x32_bf16 v[26:29], v[176:179], v[200:203], v[26:29]
	v_mfma_f32_16x16x32_bf16 v[14:17], v[168:171], v[208:211], v[14:17]
	v_mfma_f32_16x16x32_bf16 v[10:13], v[176:179], v[208:211], v[10:13]
	v_mfma_f32_16x16x32_bf16 v[62:65], v[172:175], v[188:191], v[62:65]
	v_mfma_f32_16x16x32_bf16 v[58:61], v[180:183], v[188:191], v[58:61]
	v_mfma_f32_16x16x32_bf16 v[46:49], v[172:175], v[196:199], v[46:49]
	v_mfma_f32_16x16x32_bf16 v[42:45], v[180:183], v[196:199], v[42:45]
	v_mfma_f32_16x16x32_bf16 v[30:33], v[172:175], v[204:207], v[30:33]
	v_mfma_f32_16x16x32_bf16 v[26:29], v[180:183], v[204:207], v[26:29]
	v_mfma_f32_16x16x32_bf16 v[14:17], v[172:175], v[212:215], v[14:17]
	v_mfma_f32_16x16x32_bf16 v[10:13], v[180:183], v[212:215], v[10:13]
	s_barrier
	s_add_u32 s81, s81, 0x100
	s_addc_u32 s82, s82, 0
	s_add_u32 s50, s50, 0x100
	s_addc_u32 s51, s51, 0
	s_cmp_ge_i32 s83, s70
	s_mov_b32 s52, s83
	s_cbranch_scc0 .LBB0_676

; #define PG8_STAGE(bufoff, gbase, voff) do { _Pragma("unroll") for (int _i = 0; _i < 2; ++_i) \
;         __builtin_amdgcn_global_load_lds((const unsigned*)((const char*)(gbase) + (voff)[_i]), (PG8_LAS unsigned*)(lds + (bufoff) + ldsw + _i * 8192), 16, 0, 0); } while (0)
; #define PG8_LDA(dst, b, h) do { _Pragma("unroll") for (int m = 0; m < 4; ++m) _Pragma("unroll") for (int k = 0; k < 2; ++k) dst[m][k] = *(const PG8_LAS bf16x8*)(lds + PG8_SA(b, h) + aoff + m * 2048 + k * 1024); } while (0)
; #define PG8_LDB(dst, b, h) do { _Pragma("unroll") for (int n = 0; n < 2; ++n) _Pragma("unroll") for (int k = 0; k < 2; ++k) dst[n][k] = *(const PG8_LAS bf16x8*)(lds + PG8_SB(b, h) + boff + n * 2048 + k * 1024); } while (0)
; #define PG8_MMA(ai, bj, At, Bt) do { __builtin_amdgcn_s_setprio(1); _Pragma("unroll") for (int m = 0; m < 4; ++m) _Pragma("unroll") for (int n = 0; n < 2; ++n) _Pragma("unroll") for (int k = 0; k < 2; ++k) \
;         acc[ai][bj][m][n] = __builtin_amdgcn_mfma_f32_16x16x32_bf16(Bt[n][k], At[m][k], acc[ai][bj][m][n], 0, 0, 0); __builtin_amdgcn_s_setprio(0); } while (0)
; #define PG8_WAIT_V(n) asm volatile("s_waitcnt vmcnt(" #n ")" ::: "memory")
; #define PG8_WAIT_L(n) asm volatile("s_waitcnt lgkmcnt(" #n ")" ::: "memory")
; #define PG8_BAR __builtin_amdgcn_s_barrier()
; #define PG8_SCHED __builtin_amdgcn_sched_barrier(0)
; template <class Epi, class Sched, bool ALIGN_EPI = false, bool SP2 = false>
; __device__ __forceinline__ void gemm_phase(PG8_LAS unsigned char* lds, const Gemm g, const Sched& S, const Epi& E) {
;     ...
;             PG8_LDB(B0, 0, 0); PG8_LDB(B1, 0, 1); PG8_SCHED; PG8_LDA(At, 0, 0); PG8_STAGE(PG8_SA(1, 1), a1 + hstepA, voffA);
;             PG8_WAIT_V(8); PG8_WAIT_L(0); PG8_BAR; PG8_MMA(0, 0, At, B0); PG8_MMA(0, 1, At, B1); PG8_BAR; PG8_SCHED;
;             PG8_LDA(At, 0, 1); PG8_STAGE(PG8_SB(0, 0), b2, voffB); PG8_STAGE(PG8_SB(0, 1), b2 + hstepB, voffB); PG8_STAGE(PG8_SA(0, 0), a2, voffA);
.LBB0_775:
	s_add_i32 s54, s52, 2
	s_add_u32 s55, s6, 0x80
	s_addc_u32 s53, s7, 0
	s_add_i32 s96, 0, 0x10000
	s_cmp_eq_u32 s82, s52
	s_cselect_b32 s53, s49, s53
	s_cselect_b32 s52, s48, s55
	v_add_u32_e32 v146, s96, v150
	s_cselect_b32 s95, s51, s93
	s_cselect_b32 s94, s50, s92
	s_add_i32 s55, 0, 0x14000
	ds_read_b128 v[142:145], v146
	ds_read_b128 v[154:157], v146 offset:1024
	ds_read_b128 v[158:161], v146 offset:2048
	ds_read_b128 v[162:165], v146 offset:3072
	v_add_u32_e32 v146, s55, v150
	ds_read_b128 v[166:169], v146
	ds_read_b128 v[170:173], v146 offset:1024
	ds_read_b128 v[174:177], v146 offset:2048
	ds_read_b128 v[178:181], v146 offset:3072
	v_lshl_add_u64 v[146:147], s[6:7], 0, v[140:141]
	s_add_i32 m0, s75, 0xc000
	ds_read_b128 v[182:185], v152
	ds_read_b128 v[186:189], v152 offset:1024
	ds_read_b128 v[190:193], v152 offset:2048
	ds_read_b128 v[194:197], v152 offset:3072
	ds_read_b128 v[198:201], v152 offset:4096
	ds_read_b128 v[202:205], v152 offset:5120
	ds_read_b128 v[206:209], v152 offset:6144
	ds_read_b128 v[210:213], v152 offset:7168
	global_load_lds_dwordx4 v[146:147], off
	v_lshl_add_u64 v[146:147], s[6:7], 0, v[138:139]
	s_add_i32 m0, s75, 0xe000
	s_nop 0
	global_load_lds_dwordx4 v[146:147], off
	s_waitcnt vmcnt(8)
	s_waitcnt lgkmcnt(0)
	s_barrier
	s_waitcnt lgkmcnt(0)
	v_mfma_f32_16x16x32_bf16 v[126:129], v[142:145], v[182:185], v[126:129]
	v_mfma_f32_16x16x32_bf16 v[122:125], v[158:161], v[182:185], v[122:125]
	v_mfma_f32_16x16x32_bf16 v[110:113], v[142:145], v[190:193], v[110:113]
	v_mfma_f32_16x16x32_bf16 v[106:109], v[158:161], v[190:193], v[106:109]
	v_mfma_f32_16x16x32_bf16 v[94:97], v[142:145], v[198:201], v[94:97]
	v_mfma_f32_16x16x32_bf16 v[90:93], v[158:161], v[198:201], v[90:93]
	v_mfma_f32_16x16x32_bf16 v[78:81], v[142:145], v[206:209], v[78:81]
	v_mfma_f32_16x16x32_bf16 v[74:77], v[158:161], v[206:209], v[74:77]
	v_mfma_f32_16x16x32_bf16 v[126:129], v[154:157], v[186:189], v[126:129]
	v_mfma_f32_16x16x32_bf16 v[122:125], v[162:165], v[186:189], v[122:125]
	v_mfma_f32_16x16x32_bf16 v[110:113], v[154:157], v[194:197], v[110:113]
	v_mfma_f32_16x16x32_bf16 v[106:109], v[162:165], v[194:197], v[106:109]
	v_mfma_f32_16x16x32_bf16 v[94:97], v[154:157], v[202:205], v[94:97]
	v_mfma_f32_16x16x32_bf16 v[90:93], v[162:165], v[202:205], v[90:93]
	v_mfma_f32_16x16x32_bf16 v[78:81], v[154:157], v[210:213], v[78:81]
	v_mfma_f32_16x16x32_bf16 v[74:77], v[162:165], v[210:213], v[74:77]
	v_mfma_f32_16x16x32_bf16 v[118:121], v[166:169], v[182:185], v[118:121]
	v_mfma_f32_16x16x32_bf16 v[114:117], v[174:177], v[182:185], v[114:117]
	v_mfma_f32_16x16x32_bf16 v[102:105], v[166:169], v[190:193], v[102:105]
	v_mfma_f32_16x16x32_bf16 v[98:101], v[174:177], v[190:193], v[98:101]
	v_mfma_f32_16x16x32_bf16 v[86:89], v[166:169], v[198:201], v[86:89]
	v_mfma_f32_16x16x32_bf16 v[82:85], v[174:177], v[198:201], v[82:85]
	v_mfma_f32_16x16x32_bf16 v[70:73], v[166:169], v[206:209], v[70:73]
	v_mfma_f32_16x16x32_bf16 v[66:69], v[174:177], v[206:209], v[66:69]
	v_mfma_f32_16x16x32_bf16 v[118:121], v[170:173], v[186:189], v[118:121]
	v_mfma_f32_16x16x32_bf16 v[114:117], v[178:181], v[186:189], v[114:117]
	v_mfma_f32_16x16x32_bf16 v[102:105], v[170:173], v[194:197], v[102:105]
	v_mfma_f32_16x16x32_bf16 v[98:101], v[178:181], v[194:197], v[98:101]
	v_mfma_f32_16x16x32_bf16 v[86:89], v[170:173], v[202:205], v[86:89]
	v_mfma_f32_16x16x32_bf16 v[82:85], v[178:181], v[202:205], v[82:85]
	v_mfma_f32_16x16x32_bf16 v[70:73], v[170:173], v[210:213], v[70:73]
	v_mfma_f32_16x16x32_bf16 v[66:69], v[178:181], v[210:213], v[66:69]
	s_barrier
	s_add_i32 s96, s96, s74
	v_lshl_add_u64 v[146:147], s[94:95], 0, v[130:131]
	s_mov_b32 m0, s96
	ds_read_b128 v[182:185], v152 offset:16384
	ds_read_b128 v[186:189], v152 offset:17408
	ds_read_b128 v[190:193], v152 offset:18432
	ds_read_b128 v[194:197], v152 offset:19456
	ds_read_b128 v[198:201], v152 offset:20480
	ds_read_b128 v[202:205], v152 offset:21504
	ds_read_b128 v[206:209], v152 offset:22528
	ds_read_b128 v[210:213], v152 offset:23552
	global_load_lds_dwordx4 v[146:147], off
	s_add_i32 m0, s96, 0x2000
	v_lshl_add_u64 v[214:215], s[94:95], 0, v[136:137]
	s_add_u32 s94, s94, s36
	s_addc_u32 s95, s95, s37
	s_add_i32 s55, s55, s74
	global_load_lds_dwordx4 v[214:215], off
	v_lshl_add_u64 v[216:217], s[94:95], 0, v[130:131]
	s_mov_b32 m0, s55
	v_lshl_add_u64 v[218:219], s[94:95], 0, v[136:137]
	global_load_lds_dwordx4 v[216:217], off
	s_add_i32 m0, s55, 0x2000
	v_lshl_add_u64 v[220:221], s[52:53], 0, v[132:133]
	global_load_lds_dwordx4 v[218:219], off
	s_mov_b32 m0, s75
	v_lshl_add_u64 v[222:223], s[52:53], 0, v[134:135]
	global_load_lds_dwordx4 v[220:221], off
	s_mov_b32 m0, s76
	s_nop 0
	global_load_lds_dwordx4 v[222:223], off
	s_waitcnt vmcnt(8)
	s_waitcnt lgkmcnt(0)
	s_barrier
; #define PG8_STAGE(bufoff, gbase, voff) do { _Pragma("unroll") for (int _i = 0; _i < 2; ++_i) \
;         __builtin_amdgcn_global_load_lds((const unsigned*)((const char*)(gbase) + (voff)[_i]), (PG8_LAS unsigned*)(lds + (bufoff) + ldsw + _i * 8192), 16, 0, 0); } while (0)
; #define PG8_LDA(dst, b, h) do { _Pragma("unroll") for (int m = 0; m < 4; ++m) _Pragma("unroll") for (int k = 0; k < 2; ++k) dst[m][k] = *(const PG8_LAS bf16x8*)(lds + PG8_SA(b, h) + aoff + m * 2048 + k * 1024); } while (0)
; #define PG8_LDB(dst, b, h) do { _Pragma("unroll") for (int n = 0; n < 2; ++n) _Pragma("unroll") for (int k = 0; k < 2; ++k) dst[n][k] = *(const PG8_LAS bf16x8*)(lds + PG8_SB(b, h) + boff + n * 2048 + k * 1024); } while (0)
; #define PG8_MMA(ai, bj, At, Bt) do { __builtin_amdgcn_s_setprio(1); _Pragma("unroll") for (int m = 0; m < 4; ++m) _Pragma("unroll") for (int n = 0; n < 2; ++n) _Pragma("unroll") for (int k = 0; k < 2; ++k) \
;         acc[ai][bj][m][n] = __builtin_amdgcn_mfma_f32_16x16x32_bf16(Bt[n][k], At[m][k], acc[ai][bj][m][n], 0, 0, 0); __builtin_amdgcn_s_setprio(0); } while (0)
; #define PG8_WAIT_V(n) asm volatile("s_waitcnt vmcnt(" #n ")" ::: "memory")
; #define PG8_WAIT_L(n) asm volatile("s_waitcnt lgkmcnt(" #n ")" ::: "memory")
; #define PG8_BAR __builtin_amdgcn_s_barrier()
; #define PG8_SCHED __builtin_amdgcn_sched_barrier(0)
; template <class Epi, class Sched, bool ALIGN_EPI = false, bool SP2 = false>
; __device__ __forceinline__ void gemm_phase(PG8_LAS unsigned char* lds, const Gemm g, const Sched& S, const Epi& E) {
;     ...
;             PG8_WAIT_V(8); PG8_WAIT_L(0); PG8_BAR; PG8_MMA(1, 0, At, B0); PG8_MMA(1, 1, At, B1); PG8_BAR; PG8_SCHED;
;             PG8_LDB(B0, 1, 0); PG8_LDB(B1, 1, 1); PG8_SCHED; PG8_LDA(At, 1, 0); PG8_STAGE(PG8_SA(0, 1), a2 + hstepA, voffA);
;             PG8_WAIT_V(8); PG8_WAIT_L(0); PG8_BAR; PG8_MMA(0, 0, At, B0); PG8_MMA(0, 1, At, B1); PG8_BAR; PG8_SCHED;
	s_waitcnt lgkmcnt(0)
	v_mfma_f32_16x16x32_bf16 v[62:65], v[142:145], v[182:185], v[62:65]
	v_mfma_f32_16x16x32_bf16 v[58:61], v[158:161], v[182:185], v[58:61]
	v_mfma_f32_16x16x32_bf16 v[46:49], v[142:145], v[190:193], v[46:49]
	v_mfma_f32_16x16x32_bf16 v[42:45], v[158:161], v[190:193], v[42:45]
	v_mfma_f32_16x16x32_bf16 v[30:33], v[142:145], v[198:201], v[30:33]
	v_mfma_f32_16x16x32_bf16 v[26:29], v[158:161], v[198:201], v[26:29]
	v_mfma_f32_16x16x32_bf16 v[14:17], v[142:145], v[206:209], v[14:17]
	v_mfma_f32_16x16x32_bf16 v[10:13], v[158:161], v[206:209], v[10:13]
	v_mfma_f32_16x16x32_bf16 v[62:65], v[154:157], v[186:189], v[62:65]
	v_mfma_f32_16x16x32_bf16 v[58:61], v[162:165], v[186:189], v[58:61]
	v_mfma_f32_16x16x32_bf16 v[46:49], v[154:157], v[194:197], v[46:49]
	v_mfma_f32_16x16x32_bf16 v[42:45], v[162:165], v[194:197], v[42:45]
	v_mfma_f32_16x16x32_bf16 v[30:33], v[154:157], v[202:205], v[30:33]
	v_mfma_f32_16x16x32_bf16 v[26:29], v[162:165], v[202:205], v[26:29]
	v_mfma_f32_16x16x32_bf16 v[14:17], v[154:157], v[210:213], v[14:17]
	v_mfma_f32_16x16x32_bf16 v[10:13], v[162:165], v[210:213], v[10:13]
	v_mfma_f32_16x16x32_bf16 v[54:57], v[166:169], v[182:185], v[54:57]
	v_mfma_f32_16x16x32_bf16 v[50:53], v[174:177], v[182:185], v[50:53]
	v_mfma_f32_16x16x32_bf16 v[38:41], v[166:169], v[190:193], v[38:41]
	v_mfma_f32_16x16x32_bf16 v[34:37], v[174:177], v[190:193], v[34:37]
	v_mfma_f32_16x16x32_bf16 v[22:25], v[166:169], v[198:201], v[22:25]
	v_mfma_f32_16x16x32_bf16 v[18:21], v[174:177], v[198:201], v[18:21]
	v_mfma_f32_16x16x32_bf16 v[6:9], v[166:169], v[206:209], v[6:9]
	v_mfma_f32_16x16x32_bf16 v[2:5], v[174:177], v[206:209], v[2:5]
	v_mfma_f32_16x16x32_bf16 v[54:57], v[170:173], v[186:189], v[54:57]
	v_mfma_f32_16x16x32_bf16 v[50:53], v[178:181], v[186:189], v[50:53]
	v_mfma_f32_16x16x32_bf16 v[38:41], v[170:173], v[194:197], v[38:41]
	v_mfma_f32_16x16x32_bf16 v[34:37], v[178:181], v[194:197], v[34:37]
	v_mfma_f32_16x16x32_bf16 v[22:25], v[170:173], v[202:205], v[22:25]
	v_mfma_f32_16x16x32_bf16 v[18:21], v[178:181], v[202:205], v[18:21]
	v_mfma_f32_16x16x32_bf16 v[6:9], v[170:173], v[210:213], v[6:9]
	v_mfma_f32_16x16x32_bf16 v[2:5], v[178:181], v[210:213], v[2:5]
	s_barrier
	s_add_i32 s55, 0, 0x18000
	v_add_u32_e32 v153, s55, v150
	s_add_i32 s94, 0, 0x1c000
	ds_read_b128 v[142:145], v153
	ds_read_b128 v[154:157], v153 offset:1024
	ds_read_b128 v[158:161], v153 offset:2048
	ds_read_b128 v[162:165], v153 offset:3072
	v_add_u32_e32 v153, s94, v150
	ds_read_b128 v[166:169], v153
	ds_read_b128 v[170:173], v153 offset:1024
	ds_read_b128 v[174:177], v153 offset:2048
	ds_read_b128 v[178:181], v153 offset:3072
	s_add_u32 s52, s52, s34
	s_addc_u32 s53, s53, s35
	s_mov_b32 m0, s77
	v_lshl_add_u64 v[224:225], s[52:53], 0, v[132:133]
	ds_read_b128 v[182:185], v152 offset:32768
	ds_read_b128 v[186:189], v152 offset:33792
	ds_read_b128 v[190:193], v152 offset:34816
	ds_read_b128 v[194:197], v152 offset:35840
	ds_read_b128 v[198:201], v152 offset:36864
	ds_read_b128 v[202:205], v152 offset:37888
	ds_read_b128 v[206:209], v152 offset:38912
	ds_read_b128 v[210:213], v152 offset:39936
	global_load_lds_dwordx4 v[224:225], off
	v_lshl_add_u64 v[224:225], s[52:53], 0, v[134:135]
	s_mov_b32 m0, s78
	s_nop 0
	global_load_lds_dwordx4 v[224:225], off
	s_waitcnt vmcnt(8)
	s_waitcnt lgkmcnt(0)
	s_barrier
	s_waitcnt lgkmcnt(0)
	v_mfma_f32_16x16x32_bf16 v[126:129], v[142:145], v[182:185], v[126:129]
	v_mfma_f32_16x16x32_bf16 v[122:125], v[158:161], v[182:185], v[122:125]
	v_mfma_f32_16x16x32_bf16 v[110:113], v[142:145], v[190:193], v[110:113]
	v_mfma_f32_16x16x32_bf16 v[106:109], v[158:161], v[190:193], v[106:109]
	v_mfma_f32_16x16x32_bf16 v[94:97], v[142:145], v[198:201], v[94:97]
	v_mfma_f32_16x16x32_bf16 v[90:93], v[158:161], v[198:201], v[90:93]
	v_mfma_f32_16x16x32_bf16 v[78:81], v[142:145], v[206:209], v[78:81]
	v_mfma_f32_16x16x32_bf16 v[74:77], v[158:161], v[206:209], v[74:77]
	v_mfma_f32_16x16x32_bf16 v[126:129], v[154:157], v[186:189], v[126:129]
	v_mfma_f32_16x16x32_bf16 v[122:125], v[162:165], v[186:189], v[122:125]
	v_mfma_f32_16x16x32_bf16 v[110:113], v[154:157], v[194:197], v[110:113]
	v_mfma_f32_16x16x32_bf16 v[106:109], v[162:165], v[194:197], v[106:109]
	v_mfma_f32_16x16x32_bf16 v[94:97], v[154:157], v[202:205], v[94:97]
	v_mfma_f32_16x16x32_bf16 v[90:93], v[162:165], v[202:205], v[90:93]
	v_mfma_f32_16x16x32_bf16 v[78:81], v[154:157], v[210:213], v[78:81]
	v_mfma_f32_16x16x32_bf16 v[74:77], v[162:165], v[210:213], v[74:77]
	v_mfma_f32_16x16x32_bf16 v[118:121], v[166:169], v[182:185], v[118:121]
	v_mfma_f32_16x16x32_bf16 v[114:117], v[174:177], v[182:185], v[114:117]
	v_mfma_f32_16x16x32_bf16 v[102:105], v[166:169], v[190:193], v[102:105]
	v_mfma_f32_16x16x32_bf16 v[98:101], v[174:177], v[190:193], v[98:101]
	v_mfma_f32_16x16x32_bf16 v[86:89], v[166:169], v[198:201], v[86:89]
	v_mfma_f32_16x16x32_bf16 v[82:85], v[174:177], v[198:201], v[82:85]
	v_mfma_f32_16x16x32_bf16 v[70:73], v[166:169], v[206:209], v[70:73]
	v_mfma_f32_16x16x32_bf16 v[66:69], v[174:177], v[206:209], v[66:69]
	v_mfma_f32_16x16x32_bf16 v[118:121], v[170:173], v[186:189], v[118:121]
	v_mfma_f32_16x16x32_bf16 v[114:117], v[178:181], v[186:189], v[114:117]
	v_mfma_f32_16x16x32_bf16 v[102:105], v[170:173], v[194:197], v[102:105]
	v_mfma_f32_16x16x32_bf16 v[98:101], v[178:181], v[194:197], v[98:101]
	v_mfma_f32_16x16x32_bf16 v[86:89], v[170:173], v[202:205], v[86:89]
	v_mfma_f32_16x16x32_bf16 v[82:85], v[178:181], v[202:205], v[82:85]
	v_mfma_f32_16x16x32_bf16 v[70:73], v[170:173], v[210:213], v[70:73]
	v_mfma_f32_16x16x32_bf16 v[66:69], v[178:181], v[210:213], v[66:69]
	s_barrier
; #define PG8_STAGE(bufoff, gbase, voff) do { _Pragma("unroll") for (int _i = 0; _i < 2; ++_i) \
;         __builtin_amdgcn_global_load_lds((const unsigned*)((const char*)(gbase) + (voff)[_i]), (PG8_LAS unsigned*)(lds + (bufoff) + ldsw + _i * 8192), 16, 0, 0); } while (0)
; #define PG8_LDA(dst, b, h) do { _Pragma("unroll") for (int m = 0; m < 4; ++m) _Pragma("unroll") for (int k = 0; k < 2; ++k) dst[m][k] = *(const PG8_LAS bf16x8*)(lds + PG8_SA(b, h) + aoff + m * 2048 + k * 1024); } while (0)
; #define PG8_MMA(ai, bj, At, Bt) do { __builtin_amdgcn_s_setprio(1); _Pragma("unroll") for (int m = 0; m < 4; ++m) _Pragma("unroll") for (int n = 0; n < 2; ++n) _Pragma("unroll") for (int k = 0; k < 2; ++k) \
;         acc[ai][bj][m][n] = __builtin_amdgcn_mfma_f32_16x16x32_bf16(Bt[n][k], At[m][k], acc[ai][bj][m][n], 0, 0, 0); __builtin_amdgcn_s_setprio(0); } while (0)
; #define PG8_WAIT_V(n) asm volatile("s_waitcnt vmcnt(" #n ")" ::: "memory")
; #define PG8_WAIT_L(n) asm volatile("s_waitcnt lgkmcnt(" #n ")" ::: "memory")
; #define PG8_BAR __builtin_amdgcn_s_barrier()
; #define PG8_SCHED __builtin_amdgcn_sched_barrier(0)
; template <class Epi, class Sched, bool ALIGN_EPI = false, bool SP2 = false>
; __device__ __forceinline__ void gemm_phase(PG8_LAS unsigned char* lds, const Gemm g, const Sched& S, const Epi& E) {
;     ...
;         for (int t = 0; t < nt; t += 2) {
;     ...
;             PG8_LDA(At, 1, 1); PG8_STAGE(PG8_SB(1, 0), b3, voffB); PG8_STAGE(PG8_SB(1, 1), b3 + hstepB, voffB); PG8_STAGE(PG8_SA(1, 0), a3, voffA);
;             PG8_WAIT_V(8); PG8_WAIT_L(0); PG8_BAR; PG8_MMA(1, 0, At, B0); PG8_MMA(1, 1, At, B1); PG8_BAR; PG8_SCHED;
	s_add_i32 s52, s55, s74
	v_lshl_add_u64 v[146:147], v[146:147], 0, s[18:19]
	s_mov_b32 m0, s52
	ds_read_b128 v[182:185], v152 offset:49152
	ds_read_b128 v[186:189], v152 offset:50176
	ds_read_b128 v[190:193], v152 offset:51200
	ds_read_b128 v[194:197], v152 offset:52224
	ds_read_b128 v[198:201], v152 offset:53248
	ds_read_b128 v[202:205], v152 offset:54272
	ds_read_b128 v[206:209], v152 offset:55296
	ds_read_b128 v[210:213], v152 offset:56320
	global_load_lds_dwordx4 v[146:147], off
	v_lshl_add_u64 v[146:147], v[214:215], 0, s[18:19]
	s_add_i32 m0, s52, 0x2000
	s_add_i32 s52, s94, s74
	global_load_lds_dwordx4 v[146:147], off
	v_lshl_add_u64 v[146:147], v[216:217], 0, s[18:19]
	s_mov_b32 m0, s52
	s_nop 0
	global_load_lds_dwordx4 v[146:147], off
	v_lshl_add_u64 v[146:147], v[218:219], 0, s[18:19]
	s_add_i32 m0, s52, 0x2000
	s_nop 0
	global_load_lds_dwordx4 v[146:147], off
	v_lshl_add_u64 v[146:147], v[220:221], 0, s[18:19]
	s_mov_b32 m0, s79
	s_nop 0
	global_load_lds_dwordx4 v[146:147], off
	v_lshl_add_u64 v[146:147], v[222:223], 0, s[18:19]
	s_mov_b32 m0, s80
	s_nop 0
	global_load_lds_dwordx4 v[146:147], off
	s_waitcnt vmcnt(8)
	s_waitcnt lgkmcnt(0)
	s_barrier
	s_waitcnt lgkmcnt(0)
	v_mfma_f32_16x16x32_bf16 v[62:65], v[142:145], v[182:185], v[62:65]
	v_mfma_f32_16x16x32_bf16 v[58:61], v[158:161], v[182:185], v[58:61]
	v_mfma_f32_16x16x32_bf16 v[46:49], v[142:145], v[190:193], v[46:49]
	v_mfma_f32_16x16x32_bf16 v[42:45], v[158:161], v[190:193], v[42:45]
	v_mfma_f32_16x16x32_bf16 v[30:33], v[142:145], v[198:201], v[30:33]
	v_mfma_f32_16x16x32_bf16 v[26:29], v[158:161], v[198:201], v[26:29]
	v_mfma_f32_16x16x32_bf16 v[14:17], v[142:145], v[206:209], v[14:17]
	v_mfma_f32_16x16x32_bf16 v[10:13], v[158:161], v[206:209], v[10:13]
	v_mfma_f32_16x16x32_bf16 v[62:65], v[154:157], v[186:189], v[62:65]
	v_mfma_f32_16x16x32_bf16 v[58:61], v[162:165], v[186:189], v[58:61]
	v_mfma_f32_16x16x32_bf16 v[46:49], v[154:157], v[194:197], v[46:49]
	v_mfma_f32_16x16x32_bf16 v[42:45], v[162:165], v[194:197], v[42:45]
	v_mfma_f32_16x16x32_bf16 v[30:33], v[154:157], v[202:205], v[30:33]
	v_mfma_f32_16x16x32_bf16 v[26:29], v[162:165], v[202:205], v[26:29]
	v_mfma_f32_16x16x32_bf16 v[14:17], v[154:157], v[210:213], v[14:17]
	v_mfma_f32_16x16x32_bf16 v[10:13], v[162:165], v[210:213], v[10:13]
	v_mfma_f32_16x16x32_bf16 v[54:57], v[166:169], v[182:185], v[54:57]
	v_mfma_f32_16x16x32_bf16 v[50:53], v[174:177], v[182:185], v[50:53]
	v_mfma_f32_16x16x32_bf16 v[38:41], v[166:169], v[190:193], v[38:41]
	v_mfma_f32_16x16x32_bf16 v[34:37], v[174:177], v[190:193], v[34:37]
	v_mfma_f32_16x16x32_bf16 v[22:25], v[166:169], v[198:201], v[22:25]
	v_mfma_f32_16x16x32_bf16 v[18:21], v[174:177], v[198:201], v[18:21]
	v_mfma_f32_16x16x32_bf16 v[6:9], v[166:169], v[206:209], v[6:9]
	v_mfma_f32_16x16x32_bf16 v[2:5], v[174:177], v[206:209], v[2:5]
	v_mfma_f32_16x16x32_bf16 v[54:57], v[170:173], v[186:189], v[54:57]
	v_mfma_f32_16x16x32_bf16 v[50:53], v[178:181], v[186:189], v[50:53]
	v_mfma_f32_16x16x32_bf16 v[38:41], v[170:173], v[194:197], v[38:41]
	v_mfma_f32_16x16x32_bf16 v[34:37], v[178:181], v[194:197], v[34:37]
	v_mfma_f32_16x16x32_bf16 v[22:25], v[170:173], v[202:205], v[22:25]
	v_mfma_f32_16x16x32_bf16 v[18:21], v[178:181], v[202:205], v[18:21]
	v_mfma_f32_16x16x32_bf16 v[6:9], v[170:173], v[210:213], v[6:9]
	v_mfma_f32_16x16x32_bf16 v[2:5], v[178:181], v[210:213], v[2:5]
	s_barrier
	s_add_u32 s92, s92, 0x100
	s_addc_u32 s93, s93, 0
	s_add_u32 s6, s6, 0x100
	s_addc_u32 s7, s7, 0
	s_cmp_ge_i32 s54, s81
	s_mov_b32 s52, s54
	s_cbranch_scc0 .LBB0_775

; #define PG8_STAGE(bufoff, gbase, voff) do { _Pragma("unroll") for (int _i = 0; _i < 2; ++_i) \
;         __builtin_amdgcn_global_load_lds((const unsigned*)((const char*)(gbase) + (voff)[_i]), (PG8_LAS unsigned*)(lds + (bufoff) + ldsw + _i * 8192), 16, 0, 0); } while (0)
; #define PG8_LDA(dst, b, h) do { _Pragma("unroll") for (int m = 0; m < 4; ++m) _Pragma("unroll") for (int k = 0; k < 2; ++k) dst[m][k] = *(const PG8_LAS bf16x8*)(lds + PG8_SA(b, h) + aoff + m * 2048 + k * 1024); } while (0)
; #define PG8_LDB(dst, b, h) do { _Pragma("unroll") for (int n = 0; n < 2; ++n) _Pragma("unroll") for (int k = 0; k < 2; ++k) dst[n][k] = *(const PG8_LAS bf16x8*)(lds + PG8_SB(b, h) + boff + n * 2048 + k * 1024); } while (0)
; #define PG8_MMA(ai, bj, At, Bt) do { __builtin_amdgcn_s_setprio(1); _Pragma("unroll") for (int m = 0; m < 4; ++m) _Pragma("unroll") for (int n = 0; n < 2; ++n) _Pragma("unroll") for (int k = 0; k < 2; ++k) \
;         acc[ai][bj][m][n] = __builtin_amdgcn_mfma_f32_16x16x32_bf16(Bt[n][k], At[m][k], acc[ai][bj][m][n], 0, 0, 0); __builtin_amdgcn_s_setprio(0); } while (0)
; #define PG8_WAIT_V(n) asm volatile("s_waitcnt vmcnt(" #n ")" ::: "memory")
; #define PG8_WAIT_L(n) asm volatile("s_waitcnt lgkmcnt(" #n ")" ::: "memory")
; #define PG8_BAR __builtin_amdgcn_s_barrier()
; #define PG8_SCHED __builtin_amdgcn_sched_barrier(0)
; template <class Epi, class Sched, bool ALIGN_EPI = false, bool SP2 = false>
; __device__ __forceinline__ void gemm_phase(PG8_LAS unsigned char* lds, const Gemm g, const Sched& S, const Epi& E) {
;     ...
;             PG8_LDB(B0, 0, 0); PG8_LDB(B1, 0, 1); PG8_SCHED; PG8_LDA(At, 0, 0); PG8_STAGE(PG8_SA(1, 1), a1 + hstepA, voffA);
;             PG8_WAIT_V(8); PG8_WAIT_L(0); PG8_BAR; PG8_MMA(0, 0, At, B0); PG8_MMA(0, 1, At, B1); PG8_BAR; PG8_SCHED;
;             PG8_LDA(At, 0, 1); PG8_STAGE(PG8_SB(0, 0), b2, voffB); PG8_STAGE(PG8_SB(0, 1), b2 + hstepB, voffB); PG8_STAGE(PG8_SA(0, 0), a2, voffA);
.LBB0_827:
	s_add_i32 s50, s48, 2
	s_add_u32 s51, s6, 0x80
	s_addc_u32 s49, s7, 0
	s_add_i32 s92, 0, 0x10000
	s_cmp_eq_u32 s78, s48
	s_cselect_b32 s49, s45, s49
	s_cselect_b32 s48, s44, s51
	v_add_u32_e32 v144, s92, v147
	s_cselect_b32 s91, s47, s89
	s_cselect_b32 s90, s46, s88
	s_add_i32 s51, 0, 0x14000
	ds_read_b128 v[152:155], v144
	ds_read_b128 v[156:159], v144 offset:1024
	ds_read_b128 v[160:163], v144 offset:2048
	ds_read_b128 v[164:167], v144 offset:3072
	v_add_u32_e32 v144, s51, v147
	ds_read_b128 v[168:171], v144
	ds_read_b128 v[172:175], v144 offset:1024
	ds_read_b128 v[176:179], v144 offset:2048
	ds_read_b128 v[180:183], v144 offset:3072
	v_lshl_add_u64 v[144:145], s[6:7], 0, v[140:141]
	s_add_i32 m0, s55, 0xc000
	ds_read_b128 v[184:187], v150
	ds_read_b128 v[188:191], v150 offset:1024
	ds_read_b128 v[192:195], v150 offset:2048
	ds_read_b128 v[196:199], v150 offset:3072
	ds_read_b128 v[200:203], v150 offset:4096
	ds_read_b128 v[204:207], v150 offset:5120
	ds_read_b128 v[208:211], v150 offset:6144
	ds_read_b128 v[212:215], v150 offset:7168
	global_load_lds_dwordx4 v[144:145], off
	v_lshl_add_u64 v[144:145], s[6:7], 0, v[138:139]
	s_add_i32 m0, s55, 0xe000
	s_nop 0
	global_load_lds_dwordx4 v[144:145], off
	s_waitcnt vmcnt(8)
	s_waitcnt lgkmcnt(0)
	s_barrier
	s_waitcnt lgkmcnt(0)
	v_mfma_f32_16x16x32_bf16 v[126:129], v[152:155], v[184:187], v[126:129]
	v_mfma_f32_16x16x32_bf16 v[122:125], v[160:163], v[184:187], v[122:125]
	v_mfma_f32_16x16x32_bf16 v[110:113], v[152:155], v[192:195], v[110:113]
	v_mfma_f32_16x16x32_bf16 v[106:109], v[160:163], v[192:195], v[106:109]
	v_mfma_f32_16x16x32_bf16 v[94:97], v[152:155], v[200:203], v[94:97]
	v_mfma_f32_16x16x32_bf16 v[90:93], v[160:163], v[200:203], v[90:93]
	v_mfma_f32_16x16x32_bf16 v[78:81], v[152:155], v[208:211], v[78:81]
	v_mfma_f32_16x16x32_bf16 v[74:77], v[160:163], v[208:211], v[74:77]
	v_mfma_f32_16x16x32_bf16 v[126:129], v[156:159], v[188:191], v[126:129]
	v_mfma_f32_16x16x32_bf16 v[122:125], v[164:167], v[188:191], v[122:125]
	v_mfma_f32_16x16x32_bf16 v[110:113], v[156:159], v[196:199], v[110:113]
	v_mfma_f32_16x16x32_bf16 v[106:109], v[164:167], v[196:199], v[106:109]
	v_mfma_f32_16x16x32_bf16 v[94:97], v[156:159], v[204:207], v[94:97]
	v_mfma_f32_16x16x32_bf16 v[90:93], v[164:167], v[204:207], v[90:93]
	v_mfma_f32_16x16x32_bf16 v[78:81], v[156:159], v[212:215], v[78:81]
	v_mfma_f32_16x16x32_bf16 v[74:77], v[164:167], v[212:215], v[74:77]
	v_mfma_f32_16x16x32_bf16 v[118:121], v[168:171], v[184:187], v[118:121]
	v_mfma_f32_16x16x32_bf16 v[114:117], v[176:179], v[184:187], v[114:117]
	v_mfma_f32_16x16x32_bf16 v[102:105], v[168:171], v[192:195], v[102:105]
	v_mfma_f32_16x16x32_bf16 v[98:101], v[176:179], v[192:195], v[98:101]
	v_mfma_f32_16x16x32_bf16 v[86:89], v[168:171], v[200:203], v[86:89]
	v_mfma_f32_16x16x32_bf16 v[82:85], v[176:179], v[200:203], v[82:85]
	v_mfma_f32_16x16x32_bf16 v[70:73], v[168:171], v[208:211], v[70:73]
	v_mfma_f32_16x16x32_bf16 v[66:69], v[176:179], v[208:211], v[66:69]
	v_mfma_f32_16x16x32_bf16 v[118:121], v[172:175], v[188:191], v[118:121]
	v_mfma_f32_16x16x32_bf16 v[114:117], v[180:183], v[188:191], v[114:117]
	v_mfma_f32_16x16x32_bf16 v[102:105], v[172:175], v[196:199], v[102:105]
	v_mfma_f32_16x16x32_bf16 v[98:101], v[180:183], v[196:199], v[98:101]
	v_mfma_f32_16x16x32_bf16 v[86:89], v[172:175], v[204:207], v[86:89]
	v_mfma_f32_16x16x32_bf16 v[82:85], v[180:183], v[204:207], v[82:85]
	v_mfma_f32_16x16x32_bf16 v[70:73], v[172:175], v[212:215], v[70:73]
	v_mfma_f32_16x16x32_bf16 v[66:69], v[180:183], v[212:215], v[66:69]
	s_barrier
	s_add_i32 s92, s92, s54
	v_lshl_add_u64 v[144:145], s[90:91], 0, v[130:131]
	s_mov_b32 m0, s92
	ds_read_b128 v[184:187], v150 offset:16384
	ds_read_b128 v[188:191], v150 offset:17408
	ds_read_b128 v[192:195], v150 offset:18432
	ds_read_b128 v[196:199], v150 offset:19456
	ds_read_b128 v[200:203], v150 offset:20480
	ds_read_b128 v[204:207], v150 offset:21504
	ds_read_b128 v[208:211], v150 offset:22528
	ds_read_b128 v[212:215], v150 offset:23552
	global_load_lds_dwordx4 v[144:145], off
	s_add_i32 m0, s92, 0x2000
	v_lshl_add_u64 v[216:217], s[90:91], 0, v[136:137]
	s_add_u32 s90, s90, s22
	s_addc_u32 s91, s91, s23
	s_add_i32 s51, s51, s54
	global_load_lds_dwordx4 v[216:217], off
	v_lshl_add_u64 v[218:219], s[90:91], 0, v[130:131]
	s_mov_b32 m0, s51
	v_lshl_add_u64 v[220:221], s[90:91], 0, v[136:137]
	global_load_lds_dwordx4 v[218:219], off
	s_add_i32 m0, s51, 0x2000
	v_lshl_add_u64 v[222:223], s[48:49], 0, v[132:133]
	global_load_lds_dwordx4 v[220:221], off
	s_mov_b32 m0, s55
	v_lshl_add_u64 v[224:225], s[48:49], 0, v[134:135]
	global_load_lds_dwordx4 v[222:223], off
	s_mov_b32 m0, s70
	s_nop 0
	global_load_lds_dwordx4 v[224:225], off
	s_waitcnt vmcnt(8)
	s_waitcnt lgkmcnt(0)
	s_barrier
; #define PG8_STAGE(bufoff, gbase, voff) do { _Pragma("unroll") for (int _i = 0; _i < 2; ++_i) \
;         __builtin_amdgcn_global_load_lds((const unsigned*)((const char*)(gbase) + (voff)[_i]), (PG8_LAS unsigned*)(lds + (bufoff) + ldsw + _i * 8192), 16, 0, 0); } while (0)
; #define PG8_LDA(dst, b, h) do { _Pragma("unroll") for (int m = 0; m < 4; ++m) _Pragma("unroll") for (int k = 0; k < 2; ++k) dst[m][k] = *(const PG8_LAS bf16x8*)(lds + PG8_SA(b, h) + aoff + m * 2048 + k * 1024); } while (0)
; #define PG8_LDB(dst, b, h) do { _Pragma("unroll") for (int n = 0; n < 2; ++n) _Pragma("unroll") for (int k = 0; k < 2; ++k) dst[n][k] = *(const PG8_LAS bf16x8*)(lds + PG8_SB(b, h) + boff + n * 2048 + k * 1024); } while (0)
; #define PG8_MMA(ai, bj, At, Bt) do { __builtin_amdgcn_s_setprio(1); _Pragma("unroll") for (int m = 0; m < 4; ++m) _Pragma("unroll") for (int n = 0; n < 2; ++n) _Pragma("unroll") for (int k = 0; k < 2; ++k) \
;         acc[ai][bj][m][n] = __builtin_amdgcn_mfma_f32_16x16x32_bf16(Bt[n][k], At[m][k], acc[ai][bj][m][n], 0, 0, 0); __builtin_amdgcn_s_setprio(0); } while (0)
; #define PG8_WAIT_V(n) asm volatile("s_waitcnt vmcnt(" #n ")" ::: "memory")
; #define PG8_WAIT_L(n) asm volatile("s_waitcnt lgkmcnt(" #n ")" ::: "memory")
; #define PG8_BAR __builtin_amdgcn_s_barrier()
; #define PG8_SCHED __builtin_amdgcn_sched_barrier(0)
; template <class Epi, class Sched, bool ALIGN_EPI = false, bool SP2 = false>
; __device__ __forceinline__ void gemm_phase(PG8_LAS unsigned char* lds, const Gemm g, const Sched& S, const Epi& E) {
;     ...
;             PG8_WAIT_V(8); PG8_WAIT_L(0); PG8_BAR; PG8_MMA(1, 0, At, B0); PG8_MMA(1, 1, At, B1); PG8_BAR; PG8_SCHED;
;             PG8_LDB(B0, 1, 0); PG8_LDB(B1, 1, 1); PG8_SCHED; PG8_LDA(At, 1, 0); PG8_STAGE(PG8_SA(0, 1), a2 + hstepA, voffA);
;             PG8_WAIT_V(8); PG8_WAIT_L(0); PG8_BAR; PG8_MMA(0, 0, At, B0); PG8_MMA(0, 1, At, B1); PG8_BAR; PG8_SCHED;
	s_waitcnt lgkmcnt(0)
	v_mfma_f32_16x16x32_bf16 v[62:65], v[152:155], v[184:187], v[62:65]
	v_mfma_f32_16x16x32_bf16 v[58:61], v[160:163], v[184:187], v[58:61]
	v_mfma_f32_16x16x32_bf16 v[46:49], v[152:155], v[192:195], v[46:49]
	v_mfma_f32_16x16x32_bf16 v[42:45], v[160:163], v[192:195], v[42:45]
	v_mfma_f32_16x16x32_bf16 v[30:33], v[152:155], v[200:203], v[30:33]
	v_mfma_f32_16x16x32_bf16 v[26:29], v[160:163], v[200:203], v[26:29]
	v_mfma_f32_16x16x32_bf16 v[14:17], v[152:155], v[208:211], v[14:17]
	v_mfma_f32_16x16x32_bf16 v[10:13], v[160:163], v[208:211], v[10:13]
	v_mfma_f32_16x16x32_bf16 v[62:65], v[156:159], v[188:191], v[62:65]
	v_mfma_f32_16x16x32_bf16 v[58:61], v[164:167], v[188:191], v[58:61]
	v_mfma_f32_16x16x32_bf16 v[46:49], v[156:159], v[196:199], v[46:49]
	v_mfma_f32_16x16x32_bf16 v[42:45], v[164:167], v[196:199], v[42:45]
	v_mfma_f32_16x16x32_bf16 v[30:33], v[156:159], v[204:207], v[30:33]
	v_mfma_f32_16x16x32_bf16 v[26:29], v[164:167], v[204:207], v[26:29]
	v_mfma_f32_16x16x32_bf16 v[14:17], v[156:159], v[212:215], v[14:17]
	v_mfma_f32_16x16x32_bf16 v[10:13], v[164:167], v[212:215], v[10:13]
	v_mfma_f32_16x16x32_bf16 v[54:57], v[168:171], v[184:187], v[54:57]
	v_mfma_f32_16x16x32_bf16 v[50:53], v[176:179], v[184:187], v[50:53]
	v_mfma_f32_16x16x32_bf16 v[38:41], v[168:171], v[192:195], v[38:41]
	v_mfma_f32_16x16x32_bf16 v[34:37], v[176:179], v[192:195], v[34:37]
	v_mfma_f32_16x16x32_bf16 v[22:25], v[168:171], v[200:203], v[22:25]
	v_mfma_f32_16x16x32_bf16 v[18:21], v[176:179], v[200:203], v[18:21]
	v_mfma_f32_16x16x32_bf16 v[6:9], v[168:171], v[208:211], v[6:9]
	v_mfma_f32_16x16x32_bf16 v[2:5], v[176:179], v[208:211], v[2:5]
	v_mfma_f32_16x16x32_bf16 v[54:57], v[172:175], v[188:191], v[54:57]
	v_mfma_f32_16x16x32_bf16 v[50:53], v[180:183], v[188:191], v[50:53]
	v_mfma_f32_16x16x32_bf16 v[38:41], v[172:175], v[196:199], v[38:41]
	v_mfma_f32_16x16x32_bf16 v[34:37], v[180:183], v[196:199], v[34:37]
	v_mfma_f32_16x16x32_bf16 v[22:25], v[172:175], v[204:207], v[22:25]
	v_mfma_f32_16x16x32_bf16 v[18:21], v[180:183], v[204:207], v[18:21]
	v_mfma_f32_16x16x32_bf16 v[6:9], v[172:175], v[212:215], v[6:9]
	v_mfma_f32_16x16x32_bf16 v[2:5], v[180:183], v[212:215], v[2:5]
	s_barrier
	s_add_i32 s51, 0, 0x18000
	v_add_u32_e32 v151, s51, v147
	s_add_i32 s90, 0, 0x1c000
	ds_read_b128 v[152:155], v151
	ds_read_b128 v[156:159], v151 offset:1024
	ds_read_b128 v[160:163], v151 offset:2048
	ds_read_b128 v[164:167], v151 offset:3072
	v_add_u32_e32 v151, s90, v147
	ds_read_b128 v[168:171], v151
	ds_read_b128 v[172:175], v151 offset:1024
	ds_read_b128 v[176:179], v151 offset:2048
	ds_read_b128 v[180:183], v151 offset:3072
	s_add_u32 s48, s48, s20
	s_addc_u32 s49, s49, s21
	s_mov_b32 m0, s71
	v_lshl_add_u64 v[226:227], s[48:49], 0, v[132:133]
	ds_read_b128 v[184:187], v150 offset:32768
	ds_read_b128 v[188:191], v150 offset:33792
	ds_read_b128 v[192:195], v150 offset:34816
	ds_read_b128 v[196:199], v150 offset:35840
	ds_read_b128 v[200:203], v150 offset:36864
	ds_read_b128 v[204:207], v150 offset:37888
	ds_read_b128 v[208:211], v150 offset:38912
	ds_read_b128 v[212:215], v150 offset:39936
	global_load_lds_dwordx4 v[226:227], off
	v_lshl_add_u64 v[226:227], s[48:49], 0, v[134:135]
	s_mov_b32 m0, s74
	s_nop 0
	global_load_lds_dwordx4 v[226:227], off
	s_waitcnt vmcnt(8)
	s_waitcnt lgkmcnt(0)
	s_barrier
	s_waitcnt lgkmcnt(0)
	v_mfma_f32_16x16x32_bf16 v[126:129], v[152:155], v[184:187], v[126:129]
	v_mfma_f32_16x16x32_bf16 v[122:125], v[160:163], v[184:187], v[122:125]
	v_mfma_f32_16x16x32_bf16 v[110:113], v[152:155], v[192:195], v[110:113]
	v_mfma_f32_16x16x32_bf16 v[106:109], v[160:163], v[192:195], v[106:109]
	v_mfma_f32_16x16x32_bf16 v[94:97], v[152:155], v[200:203], v[94:97]
	v_mfma_f32_16x16x32_bf16 v[90:93], v[160:163], v[200:203], v[90:93]
	v_mfma_f32_16x16x32_bf16 v[78:81], v[152:155], v[208:211], v[78:81]
	v_mfma_f32_16x16x32_bf16 v[74:77], v[160:163], v[208:211], v[74:77]
	v_mfma_f32_16x16x32_bf16 v[126:129], v[156:159], v[188:191], v[126:129]
	v_mfma_f32_16x16x32_bf16 v[122:125], v[164:167], v[188:191], v[122:125]
	v_mfma_f32_16x16x32_bf16 v[110:113], v[156:159], v[196:199], v[110:113]
	v_mfma_f32_16x16x32_bf16 v[106:109], v[164:167], v[196:199], v[106:109]
	v_mfma_f32_16x16x32_bf16 v[94:97], v[156:159], v[204:207], v[94:97]
	v_mfma_f32_16x16x32_bf16 v[90:93], v[164:167], v[204:207], v[90:93]
	v_mfma_f32_16x16x32_bf16 v[78:81], v[156:159], v[212:215], v[78:81]
	v_mfma_f32_16x16x32_bf16 v[74:77], v[164:167], v[212:215], v[74:77]
	v_mfma_f32_16x16x32_bf16 v[118:121], v[168:171], v[184:187], v[118:121]
	v_mfma_f32_16x16x32_bf16 v[114:117], v[176:179], v[184:187], v[114:117]
	v_mfma_f32_16x16x32_bf16 v[102:105], v[168:171], v[192:195], v[102:105]
	v_mfma_f32_16x16x32_bf16 v[98:101], v[176:179], v[192:195], v[98:101]
	v_mfma_f32_16x16x32_bf16 v[86:89], v[168:171], v[200:203], v[86:89]
	v_mfma_f32_16x16x32_bf16 v[82:85], v[176:179], v[200:203], v[82:85]
	v_mfma_f32_16x16x32_bf16 v[70:73], v[168:171], v[208:211], v[70:73]
	v_mfma_f32_16x16x32_bf16 v[66:69], v[176:179], v[208:211], v[66:69]
	v_mfma_f32_16x16x32_bf16 v[118:121], v[172:175], v[188:191], v[118:121]
	v_mfma_f32_16x16x32_bf16 v[114:117], v[180:183], v[188:191], v[114:117]
	v_mfma_f32_16x16x32_bf16 v[102:105], v[172:175], v[196:199], v[102:105]
	v_mfma_f32_16x16x32_bf16 v[98:101], v[180:183], v[196:199], v[98:101]
	v_mfma_f32_16x16x32_bf16 v[86:89], v[172:175], v[204:207], v[86:89]
	v_mfma_f32_16x16x32_bf16 v[82:85], v[180:183], v[204:207], v[82:85]
	v_mfma_f32_16x16x32_bf16 v[70:73], v[172:175], v[212:215], v[70:73]
	v_mfma_f32_16x16x32_bf16 v[66:69], v[180:183], v[212:215], v[66:69]
	s_barrier
; #define PG8_STAGE(bufoff, gbase, voff) do { _Pragma("unroll") for (int _i = 0; _i < 2; ++_i) \
;         __builtin_amdgcn_global_load_lds((const unsigned*)((const char*)(gbase) + (voff)[_i]), (PG8_LAS unsigned*)(lds + (bufoff) + ldsw + _i * 8192), 16, 0, 0); } while (0)
; #define PG8_LDA(dst, b, h) do { _Pragma("unroll") for (int m = 0; m < 4; ++m) _Pragma("unroll") for (int k = 0; k < 2; ++k) dst[m][k] = *(const PG8_LAS bf16x8*)(lds + PG8_SA(b, h) + aoff + m * 2048 + k * 1024); } while (0)
; #define PG8_MMA(ai, bj, At, Bt) do { __builtin_amdgcn_s_setprio(1); _Pragma("unroll") for (int m = 0; m < 4; ++m) _Pragma("unroll") for (int n = 0; n < 2; ++n) _Pragma("unroll") for (int k = 0; k < 2; ++k) \
;         acc[ai][bj][m][n] = __builtin_amdgcn_mfma_f32_16x16x32_bf16(Bt[n][k], At[m][k], acc[ai][bj][m][n], 0, 0, 0); __builtin_amdgcn_s_setprio(0); } while (0)
; #define PG8_WAIT_V(n) asm volatile("s_waitcnt vmcnt(" #n ")" ::: "memory")
; #define PG8_WAIT_L(n) asm volatile("s_waitcnt lgkmcnt(" #n ")" ::: "memory")
; #define PG8_BAR __builtin_amdgcn_s_barrier()
; #define PG8_SCHED __builtin_amdgcn_sched_barrier(0)
; template <class Epi, class Sched, bool ALIGN_EPI = false, bool SP2 = false>
; __device__ __forceinline__ void gemm_phase(PG8_LAS unsigned char* lds, const Gemm g, const Sched& S, const Epi& E) {
;     ...
;         for (int t = 0; t < nt; t += 2) {
;     ...
;             PG8_LDA(At, 1, 1); PG8_STAGE(PG8_SB(1, 0), b3, voffB); PG8_STAGE(PG8_SB(1, 1), b3 + hstepB, voffB); PG8_STAGE(PG8_SA(1, 0), a3, voffA);
;             PG8_WAIT_V(8); PG8_WAIT_L(0); PG8_BAR; PG8_MMA(1, 0, At, B0); PG8_MMA(1, 1, At, B1); PG8_BAR; PG8_SCHED;
	s_add_i32 s48, s51, s54
	v_lshl_add_u64 v[144:145], v[144:145], 0, s[18:19]
	s_mov_b32 m0, s48
	ds_read_b128 v[184:187], v150 offset:49152
	ds_read_b128 v[188:191], v150 offset:50176
	ds_read_b128 v[192:195], v150 offset:51200
	ds_read_b128 v[196:199], v150 offset:52224
	ds_read_b128 v[200:203], v150 offset:53248
	ds_read_b128 v[204:207], v150 offset:54272
	ds_read_b128 v[208:211], v150 offset:55296
	ds_read_b128 v[212:215], v150 offset:56320
	global_load_lds_dwordx4 v[144:145], off
	v_lshl_add_u64 v[144:145], v[216:217], 0, s[18:19]
	s_add_i32 m0, s48, 0x2000
	s_add_i32 s48, s90, s54
	global_load_lds_dwordx4 v[144:145], off
	v_lshl_add_u64 v[144:145], v[218:219], 0, s[18:19]
	s_mov_b32 m0, s48
	s_nop 0
	global_load_lds_dwordx4 v[144:145], off
	v_lshl_add_u64 v[144:145], v[220:221], 0, s[18:19]
	s_add_i32 m0, s48, 0x2000
	s_nop 0
	global_load_lds_dwordx4 v[144:145], off
	v_lshl_add_u64 v[144:145], v[222:223], 0, s[18:19]
	s_mov_b32 m0, s75
	s_nop 0
	global_load_lds_dwordx4 v[144:145], off
	v_lshl_add_u64 v[144:145], v[224:225], 0, s[18:19]
	s_mov_b32 m0, s76
	s_nop 0
	global_load_lds_dwordx4 v[144:145], off
	s_waitcnt vmcnt(8)
	s_waitcnt lgkmcnt(0)
	s_barrier
	s_waitcnt lgkmcnt(0)
	v_mfma_f32_16x16x32_bf16 v[62:65], v[152:155], v[184:187], v[62:65]
	v_mfma_f32_16x16x32_bf16 v[58:61], v[160:163], v[184:187], v[58:61]
	v_mfma_f32_16x16x32_bf16 v[46:49], v[152:155], v[192:195], v[46:49]
	v_mfma_f32_16x16x32_bf16 v[42:45], v[160:163], v[192:195], v[42:45]
	v_mfma_f32_16x16x32_bf16 v[30:33], v[152:155], v[200:203], v[30:33]
	v_mfma_f32_16x16x32_bf16 v[26:29], v[160:163], v[200:203], v[26:29]
	v_mfma_f32_16x16x32_bf16 v[14:17], v[152:155], v[208:211], v[14:17]
	v_mfma_f32_16x16x32_bf16 v[10:13], v[160:163], v[208:211], v[10:13]
	v_mfma_f32_16x16x32_bf16 v[62:65], v[156:159], v[188:191], v[62:65]
	v_mfma_f32_16x16x32_bf16 v[58:61], v[164:167], v[188:191], v[58:61]
	v_mfma_f32_16x16x32_bf16 v[46:49], v[156:159], v[196:199], v[46:49]
	v_mfma_f32_16x16x32_bf16 v[42:45], v[164:167], v[196:199], v[42:45]
	v_mfma_f32_16x16x32_bf16 v[30:33], v[156:159], v[204:207], v[30:33]
	v_mfma_f32_16x16x32_bf16 v[26:29], v[164:167], v[204:207], v[26:29]
	v_mfma_f32_16x16x32_bf16 v[14:17], v[156:159], v[212:215], v[14:17]
	v_mfma_f32_16x16x32_bf16 v[10:13], v[164:167], v[212:215], v[10:13]
	v_mfma_f32_16x16x32_bf16 v[54:57], v[168:171], v[184:187], v[54:57]
	v_mfma_f32_16x16x32_bf16 v[50:53], v[176:179], v[184:187], v[50:53]
	v_mfma_f32_16x16x32_bf16 v[38:41], v[168:171], v[192:195], v[38:41]
	v_mfma_f32_16x16x32_bf16 v[34:37], v[176:179], v[192:195], v[34:37]
	v_mfma_f32_16x16x32_bf16 v[22:25], v[168:171], v[200:203], v[22:25]
	v_mfma_f32_16x16x32_bf16 v[18:21], v[176:179], v[200:203], v[18:21]
	v_mfma_f32_16x16x32_bf16 v[6:9], v[168:171], v[208:211], v[6:9]
	v_mfma_f32_16x16x32_bf16 v[2:5], v[176:179], v[208:211], v[2:5]
	v_mfma_f32_16x16x32_bf16 v[54:57], v[172:175], v[188:191], v[54:57]
	v_mfma_f32_16x16x32_bf16 v[50:53], v[180:183], v[188:191], v[50:53]
	v_mfma_f32_16x16x32_bf16 v[38:41], v[172:175], v[196:199], v[38:41]
	v_mfma_f32_16x16x32_bf16 v[34:37], v[180:183], v[196:199], v[34:37]
	v_mfma_f32_16x16x32_bf16 v[22:25], v[172:175], v[204:207], v[22:25]
	v_mfma_f32_16x16x32_bf16 v[18:21], v[180:183], v[204:207], v[18:21]
	v_mfma_f32_16x16x32_bf16 v[6:9], v[172:175], v[212:215], v[6:9]
	v_mfma_f32_16x16x32_bf16 v[2:5], v[180:183], v[212:215], v[2:5]
	s_barrier
	s_add_u32 s88, s88, 0x100
	s_addc_u32 s89, s89, 0
	s_add_u32 s6, s6, 0x100
	s_addc_u32 s7, s7, 0
	s_cmp_ge_i32 s50, s77
	s_mov_b32 s48, s50
	s_cbranch_scc0 .LBB0_827

; #define PG8_STAGE(bufoff, gbase, voff) do { _Pragma("unroll") for (int _i = 0; _i < 2; ++_i) \
;         __builtin_amdgcn_global_load_lds((const unsigned*)((const char*)(gbase) + (voff)[_i]), (PG8_LAS unsigned*)(lds + (bufoff) + ldsw + _i * 8192), 16, 0, 0); } while (0)
; #define PG8_LDA(dst, b, h) do { _Pragma("unroll") for (int m = 0; m < 4; ++m) _Pragma("unroll") for (int k = 0; k < 2; ++k) dst[m][k] = *(const PG8_LAS bf16x8*)(lds + PG8_SA(b, h) + aoff + m * 2048 + k * 1024); } while (0)
; #define PG8_LDB(dst, b, h) do { _Pragma("unroll") for (int n = 0; n < 2; ++n) _Pragma("unroll") for (int k = 0; k < 2; ++k) dst[n][k] = *(const PG8_LAS bf16x8*)(lds + PG8_SB(b, h) + boff + n * 2048 + k * 1024); } while (0)
; #define PG8_MMA(ai, bj, At, Bt) do { __builtin_amdgcn_s_setprio(1); _Pragma("unroll") for (int m = 0; m < 4; ++m) _Pragma("unroll") for (int n = 0; n < 2; ++n) _Pragma("unroll") for (int k = 0; k < 2; ++k) \
;         acc[ai][bj][m][n] = __builtin_amdgcn_mfma_f32_16x16x32_bf16(Bt[n][k], At[m][k], acc[ai][bj][m][n], 0, 0, 0); __builtin_amdgcn_s_setprio(0); } while (0)
; #define PG8_WAIT_V(n) asm volatile("s_waitcnt vmcnt(" #n ")" ::: "memory")
; #define PG8_WAIT_L(n) asm volatile("s_waitcnt lgkmcnt(" #n ")" ::: "memory")
; #define PG8_BAR __builtin_amdgcn_s_barrier()
; #define PG8_SCHED __builtin_amdgcn_sched_barrier(0)
; template <class Epi, class Sched, bool ALIGN_EPI = false, bool SP2 = false>
; __device__ __forceinline__ void gemm_phase(PG8_LAS unsigned char* lds, const Gemm g, const Sched& S, const Epi& E) {
;     ...
;             PG8_LDB(B0, 0, 0); PG8_LDB(B1, 0, 1); PG8_SCHED; PG8_LDA(At, 0, 0); PG8_STAGE(PG8_SA(1, 1), a1 + hstepA, voffA);
;             PG8_WAIT_V(8); PG8_WAIT_L(0); PG8_BAR; PG8_MMA(0, 0, At, B0); PG8_MMA(0, 1, At, B1); PG8_BAR; PG8_SCHED;
;             PG8_LDA(At, 0, 1); PG8_STAGE(PG8_SB(0, 0), b2, voffB); PG8_STAGE(PG8_SB(0, 1), b2 + hstepB, voffB); PG8_STAGE(PG8_SA(0, 0), a2, voffA);
.LBB0_886:
	s_add_i32 s54, s52, 2
	s_add_u32 s55, s6, 0x80
	s_addc_u32 s53, s7, 0
	s_add_i32 s94, 0, 0x10000
	s_cmp_eq_u32 s80, s52
	s_cselect_b32 s53, s49, s53
	s_cselect_b32 s52, s48, s55
	v_add_u32_e32 v146, s94, v150
	s_cselect_b32 s93, s51, s91
	s_cselect_b32 s92, s50, s90
	s_add_i32 s55, 0, 0x14000
	ds_read_b128 v[142:145], v146
	ds_read_b128 v[154:157], v146 offset:1024
	ds_read_b128 v[158:161], v146 offset:2048
	ds_read_b128 v[162:165], v146 offset:3072
	v_add_u32_e32 v146, s55, v150
	ds_read_b128 v[166:169], v146
	ds_read_b128 v[170:173], v146 offset:1024
	ds_read_b128 v[174:177], v146 offset:2048
	ds_read_b128 v[178:181], v146 offset:3072
	v_lshl_add_u64 v[146:147], s[6:7], 0, v[140:141]
	s_add_i32 m0, s71, 0xc000
	ds_read_b128 v[182:185], v152
	ds_read_b128 v[186:189], v152 offset:1024
	ds_read_b128 v[190:193], v152 offset:2048
	ds_read_b128 v[194:197], v152 offset:3072
	ds_read_b128 v[198:201], v152 offset:4096
	ds_read_b128 v[202:205], v152 offset:5120
	ds_read_b128 v[206:209], v152 offset:6144
	ds_read_b128 v[210:213], v152 offset:7168
	global_load_lds_dwordx4 v[146:147], off
	v_lshl_add_u64 v[146:147], s[6:7], 0, v[138:139]
	s_add_i32 m0, s71, 0xe000
	s_nop 0
	global_load_lds_dwordx4 v[146:147], off
	s_waitcnt vmcnt(8)
	s_waitcnt lgkmcnt(0)
	s_barrier
	s_waitcnt lgkmcnt(0)
	v_mfma_f32_16x16x32_bf16 v[126:129], v[142:145], v[182:185], v[126:129]
	v_mfma_f32_16x16x32_bf16 v[122:125], v[158:161], v[182:185], v[122:125]
	v_mfma_f32_16x16x32_bf16 v[110:113], v[142:145], v[190:193], v[110:113]
	v_mfma_f32_16x16x32_bf16 v[106:109], v[158:161], v[190:193], v[106:109]
	v_mfma_f32_16x16x32_bf16 v[94:97], v[142:145], v[198:201], v[94:97]
	v_mfma_f32_16x16x32_bf16 v[90:93], v[158:161], v[198:201], v[90:93]
	v_mfma_f32_16x16x32_bf16 v[78:81], v[142:145], v[206:209], v[78:81]
	v_mfma_f32_16x16x32_bf16 v[74:77], v[158:161], v[206:209], v[74:77]
	v_mfma_f32_16x16x32_bf16 v[126:129], v[154:157], v[186:189], v[126:129]
	v_mfma_f32_16x16x32_bf16 v[122:125], v[162:165], v[186:189], v[122:125]
	v_mfma_f32_16x16x32_bf16 v[110:113], v[154:157], v[194:197], v[110:113]
	v_mfma_f32_16x16x32_bf16 v[106:109], v[162:165], v[194:197], v[106:109]
	v_mfma_f32_16x16x32_bf16 v[94:97], v[154:157], v[202:205], v[94:97]
	v_mfma_f32_16x16x32_bf16 v[90:93], v[162:165], v[202:205], v[90:93]
	v_mfma_f32_16x16x32_bf16 v[78:81], v[154:157], v[210:213], v[78:81]
	v_mfma_f32_16x16x32_bf16 v[74:77], v[162:165], v[210:213], v[74:77]
	v_mfma_f32_16x16x32_bf16 v[118:121], v[166:169], v[182:185], v[118:121]
	v_mfma_f32_16x16x32_bf16 v[114:117], v[174:177], v[182:185], v[114:117]
	v_mfma_f32_16x16x32_bf16 v[102:105], v[166:169], v[190:193], v[102:105]
	v_mfma_f32_16x16x32_bf16 v[98:101], v[174:177], v[190:193], v[98:101]
	v_mfma_f32_16x16x32_bf16 v[86:89], v[166:169], v[198:201], v[86:89]
	v_mfma_f32_16x16x32_bf16 v[82:85], v[174:177], v[198:201], v[82:85]
	v_mfma_f32_16x16x32_bf16 v[70:73], v[166:169], v[206:209], v[70:73]
	v_mfma_f32_16x16x32_bf16 v[66:69], v[174:177], v[206:209], v[66:69]
	v_mfma_f32_16x16x32_bf16 v[118:121], v[170:173], v[186:189], v[118:121]
	v_mfma_f32_16x16x32_bf16 v[114:117], v[178:181], v[186:189], v[114:117]
	v_mfma_f32_16x16x32_bf16 v[102:105], v[170:173], v[194:197], v[102:105]
	v_mfma_f32_16x16x32_bf16 v[98:101], v[178:181], v[194:197], v[98:101]
	v_mfma_f32_16x16x32_bf16 v[86:89], v[170:173], v[202:205], v[86:89]
	v_mfma_f32_16x16x32_bf16 v[82:85], v[178:181], v[202:205], v[82:85]
	v_mfma_f32_16x16x32_bf16 v[70:73], v[170:173], v[210:213], v[70:73]
	v_mfma_f32_16x16x32_bf16 v[66:69], v[178:181], v[210:213], v[66:69]
	s_barrier
	s_add_i32 s94, s94, s70
	v_lshl_add_u64 v[146:147], s[92:93], 0, v[130:131]
	s_mov_b32 m0, s94
	ds_read_b128 v[182:185], v152 offset:16384
	ds_read_b128 v[186:189], v152 offset:17408
	ds_read_b128 v[190:193], v152 offset:18432
	ds_read_b128 v[194:197], v152 offset:19456
	ds_read_b128 v[198:201], v152 offset:20480
	ds_read_b128 v[202:205], v152 offset:21504
	ds_read_b128 v[206:209], v152 offset:22528
	ds_read_b128 v[210:213], v152 offset:23552
	global_load_lds_dwordx4 v[146:147], off
	s_add_i32 m0, s94, 0x2000
	v_lshl_add_u64 v[214:215], s[92:93], 0, v[136:137]
	s_add_u32 s92, s92, s36
	s_addc_u32 s93, s93, s37
	s_add_i32 s55, s55, s70
	global_load_lds_dwordx4 v[214:215], off
	v_lshl_add_u64 v[216:217], s[92:93], 0, v[130:131]
	s_mov_b32 m0, s55
	v_lshl_add_u64 v[218:219], s[92:93], 0, v[136:137]
	global_load_lds_dwordx4 v[216:217], off
	s_add_i32 m0, s55, 0x2000
	v_lshl_add_u64 v[220:221], s[52:53], 0, v[132:133]
	global_load_lds_dwordx4 v[218:219], off
	s_mov_b32 m0, s71
	v_lshl_add_u64 v[222:223], s[52:53], 0, v[134:135]
	global_load_lds_dwordx4 v[220:221], off
	s_mov_b32 m0, s74
	s_nop 0
	global_load_lds_dwordx4 v[222:223], off
	s_waitcnt vmcnt(8)
	s_waitcnt lgkmcnt(0)
	s_barrier
; #define PG8_STAGE(bufoff, gbase, voff) do { _Pragma("unroll") for (int _i = 0; _i < 2; ++_i) \
;         __builtin_amdgcn_global_load_lds((const unsigned*)((const char*)(gbase) + (voff)[_i]), (PG8_LAS unsigned*)(lds + (bufoff) + ldsw + _i * 8192), 16, 0, 0); } while (0)
; #define PG8_LDA(dst, b, h) do { _Pragma("unroll") for (int m = 0; m < 4; ++m) _Pragma("unroll") for (int k = 0; k < 2; ++k) dst[m][k] = *(const PG8_LAS bf16x8*)(lds + PG8_SA(b, h) + aoff + m * 2048 + k * 1024); } while (0)
; #define PG8_LDB(dst, b, h) do { _Pragma("unroll") for (int n = 0; n < 2; ++n) _Pragma("unroll") for (int k = 0; k < 2; ++k) dst[n][k] = *(const PG8_LAS bf16x8*)(lds + PG8_SB(b, h) + boff + n * 2048 + k * 1024); } while (0)
; #define PG8_MMA(ai, bj, At, Bt) do { __builtin_amdgcn_s_setprio(1); _Pragma("unroll") for (int m = 0; m < 4; ++m) _Pragma("unroll") for (int n = 0; n < 2; ++n) _Pragma("unroll") for (int k = 0; k < 2; ++k) \
;         acc[ai][bj][m][n] = __builtin_amdgcn_mfma_f32_16x16x32_bf16(Bt[n][k], At[m][k], acc[ai][bj][m][n], 0, 0, 0); __builtin_amdgcn_s_setprio(0); } while (0)
; #define PG8_WAIT_V(n) asm volatile("s_waitcnt vmcnt(" #n ")" ::: "memory")
; #define PG8_WAIT_L(n) asm volatile("s_waitcnt lgkmcnt(" #n ")" ::: "memory")
; #define PG8_BAR __builtin_amdgcn_s_barrier()
; #define PG8_SCHED __builtin_amdgcn_sched_barrier(0)
; template <class Epi, class Sched, bool ALIGN_EPI = false, bool SP2 = false>
; __device__ __forceinline__ void gemm_phase(PG8_LAS unsigned char* lds, const Gemm g, const Sched& S, const Epi& E) {
;     ...
;             PG8_WAIT_V(8); PG8_WAIT_L(0); PG8_BAR; PG8_MMA(1, 0, At, B0); PG8_MMA(1, 1, At, B1); PG8_BAR; PG8_SCHED;
;             PG8_LDB(B0, 1, 0); PG8_LDB(B1, 1, 1); PG8_SCHED; PG8_LDA(At, 1, 0); PG8_STAGE(PG8_SA(0, 1), a2 + hstepA, voffA);
;             PG8_WAIT_V(8); PG8_WAIT_L(0); PG8_BAR; PG8_MMA(0, 0, At, B0); PG8_MMA(0, 1, At, B1); PG8_BAR; PG8_SCHED;
	s_waitcnt lgkmcnt(0)
	v_mfma_f32_16x16x32_bf16 v[62:65], v[142:145], v[182:185], v[62:65]
	v_mfma_f32_16x16x32_bf16 v[58:61], v[158:161], v[182:185], v[58:61]
	v_mfma_f32_16x16x32_bf16 v[46:49], v[142:145], v[190:193], v[46:49]
	v_mfma_f32_16x16x32_bf16 v[42:45], v[158:161], v[190:193], v[42:45]
	v_mfma_f32_16x16x32_bf16 v[30:33], v[142:145], v[198:201], v[30:33]
	v_mfma_f32_16x16x32_bf16 v[26:29], v[158:161], v[198:201], v[26:29]
	v_mfma_f32_16x16x32_bf16 v[14:17], v[142:145], v[206:209], v[14:17]
	v_mfma_f32_16x16x32_bf16 v[10:13], v[158:161], v[206:209], v[10:13]
	v_mfma_f32_16x16x32_bf16 v[62:65], v[154:157], v[186:189], v[62:65]
	v_mfma_f32_16x16x32_bf16 v[58:61], v[162:165], v[186:189], v[58:61]
	v_mfma_f32_16x16x32_bf16 v[46:49], v[154:157], v[194:197], v[46:49]
	v_mfma_f32_16x16x32_bf16 v[42:45], v[162:165], v[194:197], v[42:45]
	v_mfma_f32_16x16x32_bf16 v[30:33], v[154:157], v[202:205], v[30:33]
	v_mfma_f32_16x16x32_bf16 v[26:29], v[162:165], v[202:205], v[26:29]
	v_mfma_f32_16x16x32_bf16 v[14:17], v[154:157], v[210:213], v[14:17]
	v_mfma_f32_16x16x32_bf16 v[10:13], v[162:165], v[210:213], v[10:13]
	v_mfma_f32_16x16x32_bf16 v[54:57], v[166:169], v[182:185], v[54:57]
	v_mfma_f32_16x16x32_bf16 v[50:53], v[174:177], v[182:185], v[50:53]
	v_mfma_f32_16x16x32_bf16 v[38:41], v[166:169], v[190:193], v[38:41]
	v_mfma_f32_16x16x32_bf16 v[34:37], v[174:177], v[190:193], v[34:37]
	v_mfma_f32_16x16x32_bf16 v[22:25], v[166:169], v[198:201], v[22:25]
	v_mfma_f32_16x16x32_bf16 v[18:21], v[174:177], v[198:201], v[18:21]
	v_mfma_f32_16x16x32_bf16 v[6:9], v[166:169], v[206:209], v[6:9]
	v_mfma_f32_16x16x32_bf16 v[2:5], v[174:177], v[206:209], v[2:5]
	v_mfma_f32_16x16x32_bf16 v[54:57], v[170:173], v[186:189], v[54:57]
	v_mfma_f32_16x16x32_bf16 v[50:53], v[178:181], v[186:189], v[50:53]
	v_mfma_f32_16x16x32_bf16 v[38:41], v[170:173], v[194:197], v[38:41]
	v_mfma_f32_16x16x32_bf16 v[34:37], v[178:181], v[194:197], v[34:37]
	v_mfma_f32_16x16x32_bf16 v[22:25], v[170:173], v[202:205], v[22:25]
	v_mfma_f32_16x16x32_bf16 v[18:21], v[178:181], v[202:205], v[18:21]
	v_mfma_f32_16x16x32_bf16 v[6:9], v[170:173], v[210:213], v[6:9]
	v_mfma_f32_16x16x32_bf16 v[2:5], v[178:181], v[210:213], v[2:5]
	s_barrier
	s_add_i32 s55, 0, 0x18000
	v_add_u32_e32 v153, s55, v150
	s_add_i32 s92, 0, 0x1c000
	ds_read_b128 v[142:145], v153
	ds_read_b128 v[154:157], v153 offset:1024
	ds_read_b128 v[158:161], v153 offset:2048
	ds_read_b128 v[162:165], v153 offset:3072
	v_add_u32_e32 v153, s92, v150
	ds_read_b128 v[166:169], v153
	ds_read_b128 v[170:173], v153 offset:1024
	ds_read_b128 v[174:177], v153 offset:2048
	ds_read_b128 v[178:181], v153 offset:3072
	s_add_u32 s52, s52, s34
	s_addc_u32 s53, s53, s35
	s_mov_b32 m0, s75
	v_lshl_add_u64 v[224:225], s[52:53], 0, v[132:133]
	ds_read_b128 v[182:185], v152 offset:32768
	ds_read_b128 v[186:189], v152 offset:33792
	ds_read_b128 v[190:193], v152 offset:34816
	ds_read_b128 v[194:197], v152 offset:35840
	ds_read_b128 v[198:201], v152 offset:36864
	ds_read_b128 v[202:205], v152 offset:37888
	ds_read_b128 v[206:209], v152 offset:38912
	ds_read_b128 v[210:213], v152 offset:39936
	global_load_lds_dwordx4 v[224:225], off
	v_lshl_add_u64 v[224:225], s[52:53], 0, v[134:135]
	s_mov_b32 m0, s76
	s_nop 0
	global_load_lds_dwordx4 v[224:225], off
	s_waitcnt vmcnt(8)
	s_waitcnt lgkmcnt(0)
	s_barrier
	s_waitcnt lgkmcnt(0)
	v_mfma_f32_16x16x32_bf16 v[126:129], v[142:145], v[182:185], v[126:129]
	v_mfma_f32_16x16x32_bf16 v[122:125], v[158:161], v[182:185], v[122:125]
	v_mfma_f32_16x16x32_bf16 v[110:113], v[142:145], v[190:193], v[110:113]
	v_mfma_f32_16x16x32_bf16 v[106:109], v[158:161], v[190:193], v[106:109]
	v_mfma_f32_16x16x32_bf16 v[94:97], v[142:145], v[198:201], v[94:97]
	v_mfma_f32_16x16x32_bf16 v[90:93], v[158:161], v[198:201], v[90:93]
	v_mfma_f32_16x16x32_bf16 v[78:81], v[142:145], v[206:209], v[78:81]
	v_mfma_f32_16x16x32_bf16 v[74:77], v[158:161], v[206:209], v[74:77]
	v_mfma_f32_16x16x32_bf16 v[126:129], v[154:157], v[186:189], v[126:129]
	v_mfma_f32_16x16x32_bf16 v[122:125], v[162:165], v[186:189], v[122:125]
	v_mfma_f32_16x16x32_bf16 v[110:113], v[154:157], v[194:197], v[110:113]
	v_mfma_f32_16x16x32_bf16 v[106:109], v[162:165], v[194:197], v[106:109]
	v_mfma_f32_16x16x32_bf16 v[94:97], v[154:157], v[202:205], v[94:97]
	v_mfma_f32_16x16x32_bf16 v[90:93], v[162:165], v[202:205], v[90:93]
	v_mfma_f32_16x16x32_bf16 v[78:81], v[154:157], v[210:213], v[78:81]
	v_mfma_f32_16x16x32_bf16 v[74:77], v[162:165], v[210:213], v[74:77]
	v_mfma_f32_16x16x32_bf16 v[118:121], v[166:169], v[182:185], v[118:121]
	v_mfma_f32_16x16x32_bf16 v[114:117], v[174:177], v[182:185], v[114:117]
	v_mfma_f32_16x16x32_bf16 v[102:105], v[166:169], v[190:193], v[102:105]
	v_mfma_f32_16x16x32_bf16 v[98:101], v[174:177], v[190:193], v[98:101]
	v_mfma_f32_16x16x32_bf16 v[86:89], v[166:169], v[198:201], v[86:89]
	v_mfma_f32_16x16x32_bf16 v[82:85], v[174:177], v[198:201], v[82:85]
	v_mfma_f32_16x16x32_bf16 v[70:73], v[166:169], v[206:209], v[70:73]
	v_mfma_f32_16x16x32_bf16 v[66:69], v[174:177], v[206:209], v[66:69]
	v_mfma_f32_16x16x32_bf16 v[118:121], v[170:173], v[186:189], v[118:121]
	v_mfma_f32_16x16x32_bf16 v[114:117], v[178:181], v[186:189], v[114:117]
	v_mfma_f32_16x16x32_bf16 v[102:105], v[170:173], v[194:197], v[102:105]
	v_mfma_f32_16x16x32_bf16 v[98:101], v[178:181], v[194:197], v[98:101]
	v_mfma_f32_16x16x32_bf16 v[86:89], v[170:173], v[202:205], v[86:89]
	v_mfma_f32_16x16x32_bf16 v[82:85], v[178:181], v[202:205], v[82:85]
	v_mfma_f32_16x16x32_bf16 v[70:73], v[170:173], v[210:213], v[70:73]
	v_mfma_f32_16x16x32_bf16 v[66:69], v[178:181], v[210:213], v[66:69]
	s_barrier
; #define PG8_STAGE(bufoff, gbase, voff) do { _Pragma("unroll") for (int _i = 0; _i < 2; ++_i) \
;         __builtin_amdgcn_global_load_lds((const unsigned*)((const char*)(gbase) + (voff)[_i]), (PG8_LAS unsigned*)(lds + (bufoff) + ldsw + _i * 8192), 16, 0, 0); } while (0)
; #define PG8_LDA(dst, b, h) do { _Pragma("unroll") for (int m = 0; m < 4; ++m) _Pragma("unroll") for (int k = 0; k < 2; ++k) dst[m][k] = *(const PG8_LAS bf16x8*)(lds + PG8_SA(b, h) + aoff + m * 2048 + k * 1024); } while (0)
; #define PG8_MMA(ai, bj, At, Bt) do { __builtin_amdgcn_s_setprio(1); _Pragma("unroll") for (int m = 0; m < 4; ++m) _Pragma("unroll") for (int n = 0; n < 2; ++n) _Pragma("unroll") for (int k = 0; k < 2; ++k) \
;         acc[ai][bj][m][n] = __builtin_amdgcn_mfma_f32_16x16x32_bf16(Bt[n][k], At[m][k], acc[ai][bj][m][n], 0, 0, 0); __builtin_amdgcn_s_setprio(0); } while (0)
; #define PG8_WAIT_V(n) asm volatile("s_waitcnt vmcnt(" #n ")" ::: "memory")
; #define PG8_WAIT_L(n) asm volatile("s_waitcnt lgkmcnt(" #n ")" ::: "memory")
; #define PG8_BAR __builtin_amdgcn_s_barrier()
; #define PG8_SCHED __builtin_amdgcn_sched_barrier(0)
; template <class Epi, class Sched, bool ALIGN_EPI = false, bool SP2 = false>
; __device__ __forceinline__ void gemm_phase(PG8_LAS unsigned char* lds, const Gemm g, const Sched& S, const Epi& E) {
;     ...
;         for (int t = 0; t < nt; t += 2) {
;     ...
;             PG8_LDA(At, 1, 1); PG8_STAGE(PG8_SB(1, 0), b3, voffB); PG8_STAGE(PG8_SB(1, 1), b3 + hstepB, voffB); PG8_STAGE(PG8_SA(1, 0), a3, voffA);
;             PG8_WAIT_V(8); PG8_WAIT_L(0); PG8_BAR; PG8_MMA(1, 0, At, B0); PG8_MMA(1, 1, At, B1); PG8_BAR; PG8_SCHED;
	s_add_i32 s52, s55, s70
	v_lshl_add_u64 v[146:147], v[146:147], 0, s[18:19]
	s_mov_b32 m0, s52
	ds_read_b128 v[182:185], v152 offset:49152
	ds_read_b128 v[186:189], v152 offset:50176
	ds_read_b128 v[190:193], v152 offset:51200
	ds_read_b128 v[194:197], v152 offset:52224
	ds_read_b128 v[198:201], v152 offset:53248
	ds_read_b128 v[202:205], v152 offset:54272
	ds_read_b128 v[206:209], v152 offset:55296
	ds_read_b128 v[210:213], v152 offset:56320
	global_load_lds_dwordx4 v[146:147], off
	v_lshl_add_u64 v[146:147], v[214:215], 0, s[18:19]
	s_add_i32 m0, s52, 0x2000
	s_add_i32 s52, s92, s70
	global_load_lds_dwordx4 v[146:147], off
	v_lshl_add_u64 v[146:147], v[216:217], 0, s[18:19]
	s_mov_b32 m0, s52
	s_nop 0
	global_load_lds_dwordx4 v[146:147], off
	v_lshl_add_u64 v[146:147], v[218:219], 0, s[18:19]
	s_add_i32 m0, s52, 0x2000
	s_nop 0
	global_load_lds_dwordx4 v[146:147], off
	v_lshl_add_u64 v[146:147], v[220:221], 0, s[18:19]
	s_mov_b32 m0, s77
	s_nop 0
	global_load_lds_dwordx4 v[146:147], off
	v_lshl_add_u64 v[146:147], v[222:223], 0, s[18:19]
	s_mov_b32 m0, s78
	s_nop 0
	global_load_lds_dwordx4 v[146:147], off
	s_waitcnt vmcnt(8)
	s_waitcnt lgkmcnt(0)
	s_barrier
	s_waitcnt lgkmcnt(0)
	v_mfma_f32_16x16x32_bf16 v[62:65], v[142:145], v[182:185], v[62:65]
	v_mfma_f32_16x16x32_bf16 v[58:61], v[158:161], v[182:185], v[58:61]
	v_mfma_f32_16x16x32_bf16 v[46:49], v[142:145], v[190:193], v[46:49]
	v_mfma_f32_16x16x32_bf16 v[42:45], v[158:161], v[190:193], v[42:45]
	v_mfma_f32_16x16x32_bf16 v[30:33], v[142:145], v[198:201], v[30:33]
	v_mfma_f32_16x16x32_bf16 v[26:29], v[158:161], v[198:201], v[26:29]
	v_mfma_f32_16x16x32_bf16 v[14:17], v[142:145], v[206:209], v[14:17]
	v_mfma_f32_16x16x32_bf16 v[10:13], v[158:161], v[206:209], v[10:13]
	v_mfma_f32_16x16x32_bf16 v[62:65], v[154:157], v[186:189], v[62:65]
	v_mfma_f32_16x16x32_bf16 v[58:61], v[162:165], v[186:189], v[58:61]
	v_mfma_f32_16x16x32_bf16 v[46:49], v[154:157], v[194:197], v[46:49]
	v_mfma_f32_16x16x32_bf16 v[42:45], v[162:165], v[194:197], v[42:45]
	v_mfma_f32_16x16x32_bf16 v[30:33], v[154:157], v[202:205], v[30:33]
	v_mfma_f32_16x16x32_bf16 v[26:29], v[162:165], v[202:205], v[26:29]
	v_mfma_f32_16x16x32_bf16 v[14:17], v[154:157], v[210:213], v[14:17]
	v_mfma_f32_16x16x32_bf16 v[10:13], v[162:165], v[210:213], v[10:13]
	v_mfma_f32_16x16x32_bf16 v[54:57], v[166:169], v[182:185], v[54:57]
	v_mfma_f32_16x16x32_bf16 v[50:53], v[174:177], v[182:185], v[50:53]
	v_mfma_f32_16x16x32_bf16 v[38:41], v[166:169], v[190:193], v[38:41]
	v_mfma_f32_16x16x32_bf16 v[34:37], v[174:177], v[190:193], v[34:37]
	v_mfma_f32_16x16x32_bf16 v[22:25], v[166:169], v[198:201], v[22:25]
	v_mfma_f32_16x16x32_bf16 v[18:21], v[174:177], v[198:201], v[18:21]
	v_mfma_f32_16x16x32_bf16 v[6:9], v[166:169], v[206:209], v[6:9]
	v_mfma_f32_16x16x32_bf16 v[2:5], v[174:177], v[206:209], v[2:5]
	v_mfma_f32_16x16x32_bf16 v[54:57], v[170:173], v[186:189], v[54:57]
	v_mfma_f32_16x16x32_bf16 v[50:53], v[178:181], v[186:189], v[50:53]
	v_mfma_f32_16x16x32_bf16 v[38:41], v[170:173], v[194:197], v[38:41]
	v_mfma_f32_16x16x32_bf16 v[34:37], v[178:181], v[194:197], v[34:37]
	v_mfma_f32_16x16x32_bf16 v[22:25], v[170:173], v[202:205], v[22:25]
	v_mfma_f32_16x16x32_bf16 v[18:21], v[178:181], v[202:205], v[18:21]
	v_mfma_f32_16x16x32_bf16 v[6:9], v[170:173], v[210:213], v[6:9]
	v_mfma_f32_16x16x32_bf16 v[2:5], v[178:181], v[210:213], v[2:5]
	s_barrier
	s_add_u32 s90, s90, 0x100
	s_addc_u32 s91, s91, 0
	s_add_u32 s6, s6, 0x100
	s_addc_u32 s7, s7, 0
	s_cmp_ge_i32 s54, s79
	s_mov_b32 s52, s54
	s_cbranch_scc0 .LBB0_886

; #define PG8_STAGE(bufoff, gbase, voff) do { _Pragma("unroll") for (int _i = 0; _i < 2; ++_i) \
;         __builtin_amdgcn_global_load_lds((const unsigned*)((const char*)(gbase) + (voff)[_i]), (PG8_LAS unsigned*)(lds + (bufoff) + ldsw + _i * 8192), 16, 0, 0); } while (0)
; #define PG8_LDA(dst, b, h) do { _Pragma("unroll") for (int m = 0; m < 4; ++m) _Pragma("unroll") for (int k = 0; k < 2; ++k) dst[m][k] = *(const PG8_LAS bf16x8*)(lds + PG8_SA(b, h) + aoff + m * 2048 + k * 1024); } while (0)
; #define PG8_LDB(dst, b, h) do { _Pragma("unroll") for (int n = 0; n < 2; ++n) _Pragma("unroll") for (int k = 0; k < 2; ++k) dst[n][k] = *(const PG8_LAS bf16x8*)(lds + PG8_SB(b, h) + boff + n * 2048 + k * 1024); } while (0)
; #define PG8_MMA(ai, bj, At, Bt) do { __builtin_amdgcn_s_setprio(1); _Pragma("unroll") for (int m = 0; m < 4; ++m) _Pragma("unroll") for (int n = 0; n < 2; ++n) _Pragma("unroll") for (int k = 0; k < 2; ++k) \
;         acc[ai][bj][m][n] = __builtin_amdgcn_mfma_f32_16x16x32_bf16(Bt[n][k], At[m][k], acc[ai][bj][m][n], 0, 0, 0); __builtin_amdgcn_s_setprio(0); } while (0)
; #define PG8_WAIT_V(n) asm volatile("s_waitcnt vmcnt(" #n ")" ::: "memory")
; #define PG8_WAIT_L(n) asm volatile("s_waitcnt lgkmcnt(" #n ")" ::: "memory")
; #define PG8_BAR __builtin_amdgcn_s_barrier()
; #define PG8_SCHED __builtin_amdgcn_sched_barrier(0)
; template <class Epi, class Sched, bool ALIGN_EPI = false, bool SP2 = false>
; __device__ __forceinline__ void gemm_phase(PG8_LAS unsigned char* lds, const Gemm g, const Sched& S, const Epi& E) {
;     ...
;             PG8_LDB(B0, 0, 0); PG8_LDB(B1, 0, 1); PG8_SCHED; PG8_LDA(At, 0, 0); PG8_STAGE(PG8_SA(1, 1), a1 + hstepA, voffA);
;             PG8_WAIT_V(8); PG8_WAIT_L(0); PG8_BAR; PG8_MMA(0, 0, At, B0); PG8_MMA(0, 1, At, B1); PG8_BAR; PG8_SCHED;
;             PG8_LDA(At, 0, 1); PG8_STAGE(PG8_SB(0, 0), b2, voffB); PG8_STAGE(PG8_SB(0, 1), b2 + hstepB, voffB); PG8_STAGE(PG8_SA(0, 0), a2, voffA);
.LBB0_1010:
	ds_read_b128 v[144:147], v153
	ds_read_b128 v[156:159], v153 offset:1024
	ds_read_b128 v[160:163], v153 offset:2048
	ds_read_b128 v[164:167], v153 offset:3072
	ds_read_b128 v[168:171], v154
	ds_read_b128 v[172:175], v154 offset:1024
	ds_read_b128 v[176:179], v154 offset:2048
	ds_read_b128 v[180:183], v154 offset:3072
	s_add_i32 s48, s46, 2
	s_add_u32 s49, s6, 0x80
	s_addc_u32 s47, s7, 0
	s_cmp_eq_u32 s62, s46
	s_cselect_b32 s46, s42, s49
	s_cselect_b32 s47, s43, s47
	s_cselect_b32 s81, s45, s78
	s_cselect_b32 s80, s44, s77
	v_lshl_add_u64 v[148:149], s[6:7], 0, v[140:141]
	s_add_i32 m0, s53, 0xc000
	ds_read_b128 v[184:187], v155
	ds_read_b128 v[188:191], v155 offset:1024
	ds_read_b128 v[192:195], v155 offset:2048
	ds_read_b128 v[196:199], v155 offset:3072
	ds_read_b128 v[200:203], v155 offset:4096
	ds_read_b128 v[204:207], v155 offset:5120
	ds_read_b128 v[208:211], v155 offset:6144
	ds_read_b128 v[212:215], v155 offset:7168
	global_load_lds_dwordx4 v[148:149], off
	v_lshl_add_u64 v[148:149], s[6:7], 0, v[138:139]
	s_add_i32 m0, s53, 0xe000
	s_nop 0
	global_load_lds_dwordx4 v[148:149], off
	s_waitcnt vmcnt(8)
	s_waitcnt lgkmcnt(0)
	s_barrier
	s_waitcnt lgkmcnt(0)
	v_mfma_f32_16x16x32_bf16 v[122:125], v[144:147], v[184:187], v[122:125]
	v_mfma_f32_16x16x32_bf16 v[126:129], v[160:163], v[184:187], v[126:129]
	v_mfma_f32_16x16x32_bf16 v[110:113], v[144:147], v[192:195], v[110:113]
	v_mfma_f32_16x16x32_bf16 v[106:109], v[160:163], v[192:195], v[106:109]
	v_mfma_f32_16x16x32_bf16 v[94:97], v[144:147], v[200:203], v[94:97]
	v_mfma_f32_16x16x32_bf16 v[90:93], v[160:163], v[200:203], v[90:93]
	v_mfma_f32_16x16x32_bf16 v[78:81], v[144:147], v[208:211], v[78:81]
	v_mfma_f32_16x16x32_bf16 v[74:77], v[160:163], v[208:211], v[74:77]
	v_mfma_f32_16x16x32_bf16 v[122:125], v[156:159], v[188:191], v[122:125]
	v_mfma_f32_16x16x32_bf16 v[126:129], v[164:167], v[188:191], v[126:129]
	v_mfma_f32_16x16x32_bf16 v[110:113], v[156:159], v[196:199], v[110:113]
	v_mfma_f32_16x16x32_bf16 v[106:109], v[164:167], v[196:199], v[106:109]
	v_mfma_f32_16x16x32_bf16 v[94:97], v[156:159], v[204:207], v[94:97]
	v_mfma_f32_16x16x32_bf16 v[90:93], v[164:167], v[204:207], v[90:93]
	v_mfma_f32_16x16x32_bf16 v[78:81], v[156:159], v[212:215], v[78:81]
	v_mfma_f32_16x16x32_bf16 v[74:77], v[164:167], v[212:215], v[74:77]
	v_mfma_f32_16x16x32_bf16 v[118:121], v[168:171], v[184:187], v[118:121]
	v_mfma_f32_16x16x32_bf16 v[114:117], v[176:179], v[184:187], v[114:117]
	v_mfma_f32_16x16x32_bf16 v[102:105], v[168:171], v[192:195], v[102:105]
	v_mfma_f32_16x16x32_bf16 v[98:101], v[176:179], v[192:195], v[98:101]
	v_mfma_f32_16x16x32_bf16 v[86:89], v[168:171], v[200:203], v[86:89]
	v_mfma_f32_16x16x32_bf16 v[82:85], v[176:179], v[200:203], v[82:85]
	v_mfma_f32_16x16x32_bf16 v[70:73], v[168:171], v[208:211], v[70:73]
	v_mfma_f32_16x16x32_bf16 v[66:69], v[176:179], v[208:211], v[66:69]
	v_mfma_f32_16x16x32_bf16 v[118:121], v[172:175], v[188:191], v[118:121]
	v_mfma_f32_16x16x32_bf16 v[114:117], v[180:183], v[188:191], v[114:117]
	v_mfma_f32_16x16x32_bf16 v[102:105], v[172:175], v[196:199], v[102:105]
	v_mfma_f32_16x16x32_bf16 v[98:101], v[180:183], v[196:199], v[98:101]
	v_mfma_f32_16x16x32_bf16 v[86:89], v[172:175], v[204:207], v[86:89]
	v_mfma_f32_16x16x32_bf16 v[82:85], v[180:183], v[204:207], v[82:85]
	v_mfma_f32_16x16x32_bf16 v[70:73], v[172:175], v[212:215], v[70:73]
	v_mfma_f32_16x16x32_bf16 v[66:69], v[180:183], v[212:215], v[66:69]
	s_barrier
	s_add_i32 s49, s69, s52
	v_lshl_add_u64 v[148:149], s[80:81], 0, v[132:133]
	s_mov_b32 m0, s49
	ds_read_b128 v[184:187], v155 offset:16384
	ds_read_b128 v[188:191], v155 offset:17408
	ds_read_b128 v[192:195], v155 offset:18432
	ds_read_b128 v[196:199], v155 offset:19456
	ds_read_b128 v[200:203], v155 offset:20480
	ds_read_b128 v[204:207], v155 offset:21504
	ds_read_b128 v[208:211], v155 offset:22528
	ds_read_b128 v[212:215], v155 offset:23552
	global_load_lds_dwordx4 v[148:149], off
	s_add_i32 m0, s49, 0x2000
	v_lshl_add_u64 v[216:217], s[80:81], 0, v[136:137]
	s_add_u32 s80, s80, s16
	s_addc_u32 s81, s81, s17
	s_add_i32 s49, s70, s52
	global_load_lds_dwordx4 v[216:217], off
	v_lshl_add_u64 v[218:219], s[80:81], 0, v[132:133]
	s_mov_b32 m0, s49
	v_lshl_add_u64 v[220:221], s[80:81], 0, v[136:137]
	global_load_lds_dwordx4 v[218:219], off
	s_add_i32 m0, s49, 0x2000
	v_lshl_add_u64 v[222:223], s[46:47], 0, v[130:131]
	global_load_lds_dwordx4 v[220:221], off
	s_mov_b32 m0, s53
	v_lshl_add_u64 v[224:225], s[46:47], 0, v[134:135]
	global_load_lds_dwordx4 v[222:223], off
	s_mov_b32 m0, s54
	s_nop 0
	global_load_lds_dwordx4 v[224:225], off
	s_waitcnt vmcnt(8)
	s_waitcnt lgkmcnt(0)
	s_barrier
; #define PG8_STAGE(bufoff, gbase, voff) do { _Pragma("unroll") for (int _i = 0; _i < 2; ++_i) \
;         __builtin_amdgcn_global_load_lds((const unsigned*)((const char*)(gbase) + (voff)[_i]), (PG8_LAS unsigned*)(lds + (bufoff) + ldsw + _i * 8192), 16, 0, 0); } while (0)
; #define PG8_LDA(dst, b, h) do { _Pragma("unroll") for (int m = 0; m < 4; ++m) _Pragma("unroll") for (int k = 0; k < 2; ++k) dst[m][k] = *(const PG8_LAS bf16x8*)(lds + PG8_SA(b, h) + aoff + m * 2048 + k * 1024); } while (0)
; #define PG8_LDB(dst, b, h) do { _Pragma("unroll") for (int n = 0; n < 2; ++n) _Pragma("unroll") for (int k = 0; k < 2; ++k) dst[n][k] = *(const PG8_LAS bf16x8*)(lds + PG8_SB(b, h) + boff + n * 2048 + k * 1024); } while (0)
; #define PG8_MMA(ai, bj, At, Bt) do { __builtin_amdgcn_s_setprio(1); _Pragma("unroll") for (int m = 0; m < 4; ++m) _Pragma("unroll") for (int n = 0; n < 2; ++n) _Pragma("unroll") for (int k = 0; k < 2; ++k) \
;         acc[ai][bj][m][n] = __builtin_amdgcn_mfma_f32_16x16x32_bf16(Bt[n][k], At[m][k], acc[ai][bj][m][n], 0, 0, 0); __builtin_amdgcn_s_setprio(0); } while (0)
; #define PG8_WAIT_V(n) asm volatile("s_waitcnt vmcnt(" #n ")" ::: "memory")
; #define PG8_WAIT_L(n) asm volatile("s_waitcnt lgkmcnt(" #n ")" ::: "memory")
; #define PG8_BAR __builtin_amdgcn_s_barrier()
; #define PG8_SCHED __builtin_amdgcn_sched_barrier(0)
; template <class Epi, class Sched, bool ALIGN_EPI = false, bool SP2 = false>
; __device__ __forceinline__ void gemm_phase(PG8_LAS unsigned char* lds, const Gemm g, const Sched& S, const Epi& E) {
;     ...
;             PG8_WAIT_V(8); PG8_WAIT_L(0); PG8_BAR; PG8_MMA(1, 0, At, B0); PG8_MMA(1, 1, At, B1); PG8_BAR; PG8_SCHED;
;             PG8_LDB(B0, 1, 0); PG8_LDB(B1, 1, 1); PG8_SCHED; PG8_LDA(At, 1, 0); PG8_STAGE(PG8_SA(0, 1), a2 + hstepA, voffA);
;             PG8_WAIT_V(8); PG8_WAIT_L(0); PG8_BAR; PG8_MMA(0, 0, At, B0); PG8_MMA(0, 1, At, B1); PG8_BAR; PG8_SCHED;
	s_waitcnt lgkmcnt(0)
	v_mfma_f32_16x16x32_bf16 v[62:65], v[144:147], v[184:187], v[62:65]
	v_mfma_f32_16x16x32_bf16 v[58:61], v[160:163], v[184:187], v[58:61]
	v_mfma_f32_16x16x32_bf16 v[46:49], v[144:147], v[192:195], v[46:49]
	v_mfma_f32_16x16x32_bf16 v[42:45], v[160:163], v[192:195], v[42:45]
	v_mfma_f32_16x16x32_bf16 v[30:33], v[144:147], v[200:203], v[30:33]
	v_mfma_f32_16x16x32_bf16 v[26:29], v[160:163], v[200:203], v[26:29]
	v_mfma_f32_16x16x32_bf16 v[14:17], v[144:147], v[208:211], v[14:17]
	v_mfma_f32_16x16x32_bf16 v[10:13], v[160:163], v[208:211], v[10:13]
	v_mfma_f32_16x16x32_bf16 v[62:65], v[156:159], v[188:191], v[62:65]
	v_mfma_f32_16x16x32_bf16 v[58:61], v[164:167], v[188:191], v[58:61]
	v_mfma_f32_16x16x32_bf16 v[46:49], v[156:159], v[196:199], v[46:49]
	v_mfma_f32_16x16x32_bf16 v[42:45], v[164:167], v[196:199], v[42:45]
	v_mfma_f32_16x16x32_bf16 v[30:33], v[156:159], v[204:207], v[30:33]
	v_mfma_f32_16x16x32_bf16 v[26:29], v[164:167], v[204:207], v[26:29]
	v_mfma_f32_16x16x32_bf16 v[14:17], v[156:159], v[212:215], v[14:17]
	v_mfma_f32_16x16x32_bf16 v[10:13], v[164:167], v[212:215], v[10:13]
	v_mfma_f32_16x16x32_bf16 v[54:57], v[168:171], v[184:187], v[54:57]
	v_mfma_f32_16x16x32_bf16 v[50:53], v[176:179], v[184:187], v[50:53]
	v_mfma_f32_16x16x32_bf16 v[38:41], v[168:171], v[192:195], v[38:41]
	v_mfma_f32_16x16x32_bf16 v[34:37], v[176:179], v[192:195], v[34:37]
	v_mfma_f32_16x16x32_bf16 v[22:25], v[168:171], v[200:203], v[22:25]
	v_mfma_f32_16x16x32_bf16 v[18:21], v[176:179], v[200:203], v[18:21]
	v_mfma_f32_16x16x32_bf16 v[6:9], v[168:171], v[208:211], v[6:9]
	v_mfma_f32_16x16x32_bf16 v[2:5], v[176:179], v[208:211], v[2:5]
	v_mfma_f32_16x16x32_bf16 v[54:57], v[172:175], v[188:191], v[54:57]
	v_mfma_f32_16x16x32_bf16 v[50:53], v[180:183], v[188:191], v[50:53]
	v_mfma_f32_16x16x32_bf16 v[38:41], v[172:175], v[196:199], v[38:41]
	v_mfma_f32_16x16x32_bf16 v[34:37], v[180:183], v[196:199], v[34:37]
	v_mfma_f32_16x16x32_bf16 v[22:25], v[172:175], v[204:207], v[22:25]
	v_mfma_f32_16x16x32_bf16 v[18:21], v[180:183], v[204:207], v[18:21]
	v_mfma_f32_16x16x32_bf16 v[6:9], v[172:175], v[212:215], v[6:9]
	v_mfma_f32_16x16x32_bf16 v[2:5], v[180:183], v[212:215], v[2:5]
	s_barrier
	s_add_i32 s49, 0, 0x18000
	s_add_i32 s79, 0, 0x1c000
	v_add_u32_e32 v164, s49, v151
	v_add_u32_e32 v180, s79, v151
	ds_read_b128 v[144:147], v164
	ds_read_b128 v[156:159], v164 offset:1024
	ds_read_b128 v[160:163], v164 offset:2048
	ds_read_b128 v[164:167], v164 offset:3072
	ds_read_b128 v[168:171], v180
	ds_read_b128 v[172:175], v180 offset:1024
	ds_read_b128 v[176:179], v180 offset:2048
	ds_read_b128 v[180:183], v180 offset:3072
	s_add_u32 s46, s46, s10
	s_addc_u32 s47, s47, s11
	s_mov_b32 m0, s55
	v_lshl_add_u64 v[226:227], s[46:47], 0, v[130:131]
	ds_read_b128 v[184:187], v155 offset:32768
	ds_read_b128 v[188:191], v155 offset:33792
	ds_read_b128 v[192:195], v155 offset:34816
	ds_read_b128 v[196:199], v155 offset:35840
	ds_read_b128 v[200:203], v155 offset:36864
	ds_read_b128 v[204:207], v155 offset:37888
	ds_read_b128 v[208:211], v155 offset:38912
	ds_read_b128 v[212:215], v155 offset:39936
	global_load_lds_dwordx4 v[226:227], off
	v_lshl_add_u64 v[226:227], s[46:47], 0, v[134:135]
	s_mov_b32 m0, s56
	s_nop 0
	global_load_lds_dwordx4 v[226:227], off
	s_waitcnt vmcnt(8)
	s_waitcnt lgkmcnt(0)
	s_barrier
	s_waitcnt lgkmcnt(0)
	v_mfma_f32_16x16x32_bf16 v[122:125], v[144:147], v[184:187], v[122:125]
	v_mfma_f32_16x16x32_bf16 v[126:129], v[160:163], v[184:187], v[126:129]
	v_mfma_f32_16x16x32_bf16 v[110:113], v[144:147], v[192:195], v[110:113]
	v_mfma_f32_16x16x32_bf16 v[106:109], v[160:163], v[192:195], v[106:109]
	v_mfma_f32_16x16x32_bf16 v[94:97], v[144:147], v[200:203], v[94:97]
	v_mfma_f32_16x16x32_bf16 v[90:93], v[160:163], v[200:203], v[90:93]
	v_mfma_f32_16x16x32_bf16 v[78:81], v[144:147], v[208:211], v[78:81]
	v_mfma_f32_16x16x32_bf16 v[74:77], v[160:163], v[208:211], v[74:77]
	v_mfma_f32_16x16x32_bf16 v[122:125], v[156:159], v[188:191], v[122:125]
	v_mfma_f32_16x16x32_bf16 v[126:129], v[164:167], v[188:191], v[126:129]
	v_mfma_f32_16x16x32_bf16 v[110:113], v[156:159], v[196:199], v[110:113]
	v_mfma_f32_16x16x32_bf16 v[106:109], v[164:167], v[196:199], v[106:109]
	v_mfma_f32_16x16x32_bf16 v[94:97], v[156:159], v[204:207], v[94:97]
	v_mfma_f32_16x16x32_bf16 v[90:93], v[164:167], v[204:207], v[90:93]
	v_mfma_f32_16x16x32_bf16 v[78:81], v[156:159], v[212:215], v[78:81]
	v_mfma_f32_16x16x32_bf16 v[74:77], v[164:167], v[212:215], v[74:77]
	v_mfma_f32_16x16x32_bf16 v[118:121], v[168:171], v[184:187], v[118:121]
	v_mfma_f32_16x16x32_bf16 v[114:117], v[176:179], v[184:187], v[114:117]
	v_mfma_f32_16x16x32_bf16 v[102:105], v[168:171], v[192:195], v[102:105]
	v_mfma_f32_16x16x32_bf16 v[98:101], v[176:179], v[192:195], v[98:101]
	v_mfma_f32_16x16x32_bf16 v[86:89], v[168:171], v[200:203], v[86:89]
	v_mfma_f32_16x16x32_bf16 v[82:85], v[176:179], v[200:203], v[82:85]
	v_mfma_f32_16x16x32_bf16 v[70:73], v[168:171], v[208:211], v[70:73]
	v_mfma_f32_16x16x32_bf16 v[66:69], v[176:179], v[208:211], v[66:69]
	v_mfma_f32_16x16x32_bf16 v[118:121], v[172:175], v[188:191], v[118:121]
	v_mfma_f32_16x16x32_bf16 v[114:117], v[180:183], v[188:191], v[114:117]
	v_mfma_f32_16x16x32_bf16 v[102:105], v[172:175], v[196:199], v[102:105]
	v_mfma_f32_16x16x32_bf16 v[98:101], v[180:183], v[196:199], v[98:101]
	v_mfma_f32_16x16x32_bf16 v[86:89], v[172:175], v[204:207], v[86:89]
	v_mfma_f32_16x16x32_bf16 v[82:85], v[180:183], v[204:207], v[82:85]
	v_mfma_f32_16x16x32_bf16 v[70:73], v[172:175], v[212:215], v[70:73]
	v_mfma_f32_16x16x32_bf16 v[66:69], v[180:183], v[212:215], v[66:69]
	s_barrier
; #define PG8_STAGE(bufoff, gbase, voff) do { _Pragma("unroll") for (int _i = 0; _i < 2; ++_i) \
;         __builtin_amdgcn_global_load_lds((const unsigned*)((const char*)(gbase) + (voff)[_i]), (PG8_LAS unsigned*)(lds + (bufoff) + ldsw + _i * 8192), 16, 0, 0); } while (0)
; #define PG8_LDA(dst, b, h) do { _Pragma("unroll") for (int m = 0; m < 4; ++m) _Pragma("unroll") for (int k = 0; k < 2; ++k) dst[m][k] = *(const PG8_LAS bf16x8*)(lds + PG8_SA(b, h) + aoff + m * 2048 + k * 1024); } while (0)
; #define PG8_MMA(ai, bj, At, Bt) do { __builtin_amdgcn_s_setprio(1); _Pragma("unroll") for (int m = 0; m < 4; ++m) _Pragma("unroll") for (int n = 0; n < 2; ++n) _Pragma("unroll") for (int k = 0; k < 2; ++k) \
;         acc[ai][bj][m][n] = __builtin_amdgcn_mfma_f32_16x16x32_bf16(Bt[n][k], At[m][k], acc[ai][bj][m][n], 0, 0, 0); __builtin_amdgcn_s_setprio(0); } while (0)
; #define PG8_WAIT_V(n) asm volatile("s_waitcnt vmcnt(" #n ")" ::: "memory")
; #define PG8_WAIT_L(n) asm volatile("s_waitcnt lgkmcnt(" #n ")" ::: "memory")
; #define PG8_BAR __builtin_amdgcn_s_barrier()
; #define PG8_SCHED __builtin_amdgcn_sched_barrier(0)
; template <class Epi, class Sched, bool ALIGN_EPI = false, bool SP2 = false>
; __device__ __forceinline__ void gemm_phase(PG8_LAS unsigned char* lds, const Gemm g, const Sched& S, const Epi& E) {
;     ...
;             PG8_LDA(At, 1, 1); PG8_STAGE(PG8_SB(1, 0), b3, voffB); PG8_STAGE(PG8_SB(1, 1), b3 + hstepB, voffB); PG8_STAGE(PG8_SA(1, 0), a3, voffA);
;             PG8_WAIT_V(8); PG8_WAIT_L(0); PG8_BAR; PG8_MMA(1, 0, At, B0); PG8_MMA(1, 1, At, B1); PG8_BAR; PG8_SCHED;
	s_add_i32 s46, s49, s52
	v_lshl_add_u64 v[148:149], v[148:149], 0, s[34:35]
	s_mov_b32 m0, s46
	ds_read_b128 v[184:187], v155 offset:49152
	ds_read_b128 v[188:191], v155 offset:50176
	ds_read_b128 v[192:195], v155 offset:51200
	ds_read_b128 v[196:199], v155 offset:52224
	ds_read_b128 v[200:203], v155 offset:53248
	ds_read_b128 v[204:207], v155 offset:54272
	ds_read_b128 v[208:211], v155 offset:55296
	ds_read_b128 v[212:215], v155 offset:56320
	global_load_lds_dwordx4 v[148:149], off
	v_lshl_add_u64 v[148:149], v[216:217], 0, s[34:35]
	s_add_i32 m0, s46, 0x2000
	s_add_i32 s46, s79, s52
	global_load_lds_dwordx4 v[148:149], off
	v_lshl_add_u64 v[148:149], v[218:219], 0, s[34:35]
	s_mov_b32 m0, s46
	s_nop 0
	global_load_lds_dwordx4 v[148:149], off
	v_lshl_add_u64 v[148:149], v[220:221], 0, s[34:35]
	s_add_i32 m0, s46, 0x2000
	s_nop 0
	global_load_lds_dwordx4 v[148:149], off
	v_lshl_add_u64 v[148:149], v[222:223], 0, s[34:35]
	s_mov_b32 m0, s59
	s_nop 0
	global_load_lds_dwordx4 v[148:149], off
	v_lshl_add_u64 v[148:149], v[224:225], 0, s[34:35]
	s_mov_b32 m0, s60
	s_nop 0
	global_load_lds_dwordx4 v[148:149], off
	s_waitcnt vmcnt(8)
	s_waitcnt lgkmcnt(0)
	s_barrier
	s_waitcnt lgkmcnt(0)
	v_mfma_f32_16x16x32_bf16 v[62:65], v[144:147], v[184:187], v[62:65]
	v_mfma_f32_16x16x32_bf16 v[58:61], v[160:163], v[184:187], v[58:61]
	v_mfma_f32_16x16x32_bf16 v[46:49], v[144:147], v[192:195], v[46:49]
	v_mfma_f32_16x16x32_bf16 v[42:45], v[160:163], v[192:195], v[42:45]
	v_mfma_f32_16x16x32_bf16 v[30:33], v[144:147], v[200:203], v[30:33]
	v_mfma_f32_16x16x32_bf16 v[26:29], v[160:163], v[200:203], v[26:29]
	v_mfma_f32_16x16x32_bf16 v[14:17], v[144:147], v[208:211], v[14:17]
	v_mfma_f32_16x16x32_bf16 v[10:13], v[160:163], v[208:211], v[10:13]
	v_mfma_f32_16x16x32_bf16 v[62:65], v[156:159], v[188:191], v[62:65]
	v_mfma_f32_16x16x32_bf16 v[58:61], v[164:167], v[188:191], v[58:61]
	v_mfma_f32_16x16x32_bf16 v[46:49], v[156:159], v[196:199], v[46:49]
	v_mfma_f32_16x16x32_bf16 v[42:45], v[164:167], v[196:199], v[42:45]
	v_mfma_f32_16x16x32_bf16 v[30:33], v[156:159], v[204:207], v[30:33]
	v_mfma_f32_16x16x32_bf16 v[26:29], v[164:167], v[204:207], v[26:29]
	v_mfma_f32_16x16x32_bf16 v[14:17], v[156:159], v[212:215], v[14:17]
	v_mfma_f32_16x16x32_bf16 v[10:13], v[164:167], v[212:215], v[10:13]
	v_mfma_f32_16x16x32_bf16 v[54:57], v[168:171], v[184:187], v[54:57]
	v_mfma_f32_16x16x32_bf16 v[50:53], v[176:179], v[184:187], v[50:53]
	v_mfma_f32_16x16x32_bf16 v[38:41], v[168:171], v[192:195], v[38:41]
	v_mfma_f32_16x16x32_bf16 v[34:37], v[176:179], v[192:195], v[34:37]
	v_mfma_f32_16x16x32_bf16 v[22:25], v[168:171], v[200:203], v[22:25]
	v_mfma_f32_16x16x32_bf16 v[18:21], v[176:179], v[200:203], v[18:21]
	v_mfma_f32_16x16x32_bf16 v[6:9], v[168:171], v[208:211], v[6:9]
	v_mfma_f32_16x16x32_bf16 v[2:5], v[176:179], v[208:211], v[2:5]
	v_mfma_f32_16x16x32_bf16 v[54:57], v[172:175], v[188:191], v[54:57]
	v_mfma_f32_16x16x32_bf16 v[50:53], v[180:183], v[188:191], v[50:53]
	v_mfma_f32_16x16x32_bf16 v[38:41], v[172:175], v[196:199], v[38:41]
	v_mfma_f32_16x16x32_bf16 v[34:37], v[180:183], v[196:199], v[34:37]
	v_mfma_f32_16x16x32_bf16 v[22:25], v[172:175], v[204:207], v[22:25]
	v_mfma_f32_16x16x32_bf16 v[18:21], v[180:183], v[204:207], v[18:21]
	v_mfma_f32_16x16x32_bf16 v[6:9], v[172:175], v[212:215], v[6:9]
	v_mfma_f32_16x16x32_bf16 v[2:5], v[180:183], v[212:215], v[2:5]
	s_barrier
	s_add_u32 s77, s77, 0x100
	s_addc_u32 s78, s78, 0
	s_add_u32 s6, s6, 0x100
	s_addc_u32 s7, s7, 0
	s_cmp_ge_i32 s48, s61
	s_mov_b32 s46, s48
	s_cbranch_scc0 .LBB0_1010

; #define PG8_STAGE(bufoff, gbase, voff) do { _Pragma("unroll") for (int _i = 0; _i < 2; ++_i) \
;         __builtin_amdgcn_global_load_lds((const unsigned*)((const char*)(gbase) + (voff)[_i]), (PG8_LAS unsigned*)(lds + (bufoff) + ldsw + _i * 8192), 16, 0, 0); } while (0)
; #define PG8_LDA(dst, b, h) do { _Pragma("unroll") for (int m = 0; m < 4; ++m) _Pragma("unroll") for (int k = 0; k < 2; ++k) dst[m][k] = *(const PG8_LAS bf16x8*)(lds + PG8_SA(b, h) + aoff + m * 2048 + k * 1024); } while (0)
; #define PG8_LDB(dst, b, h) do { _Pragma("unroll") for (int n = 0; n < 2; ++n) _Pragma("unroll") for (int k = 0; k < 2; ++k) dst[n][k] = *(const PG8_LAS bf16x8*)(lds + PG8_SB(b, h) + boff + n * 2048 + k * 1024); } while (0)
; #define PG8_MMA(ai, bj, At, Bt) do { __builtin_amdgcn_s_setprio(1); _Pragma("unroll") for (int m = 0; m < 4; ++m) _Pragma("unroll") for (int n = 0; n < 2; ++n) _Pragma("unroll") for (int k = 0; k < 2; ++k) \
;         acc[ai][bj][m][n] = __builtin_amdgcn_mfma_f32_16x16x32_bf16(Bt[n][k], At[m][k], acc[ai][bj][m][n], 0, 0, 0); __builtin_amdgcn_s_setprio(0); } while (0)
; #define PG8_WAIT_V(n) asm volatile("s_waitcnt vmcnt(" #n ")" ::: "memory")
; #define PG8_BAR __builtin_amdgcn_s_barrier()
; template <class Epi, class Sched, bool ALIGN_EPI = false, bool SP2 = false>
; __device__ __forceinline__ void gemm_phase(PG8_LAS unsigned char* lds, const Gemm g, const Sched& S, const Epi& E) {
;     ...
;         for (int t = 0; t < nt; t += 2) {
;             const bool last = (t == nt - 2);
;             const char* a1 = cA + (size_t)(t + 1) * kstep;
;             const char* a2 = last ? nA : cA + (size_t)(t + 2) * kstep; const char* b2 = last ? nB : cB + (size_t)(t + 2) * kstep;
;             const char* a3 = a2 + kstep; const char* b3 = b2 + kstep;
;             if (last && has_next) S.a_ready(nxt);
;             if constexpr (SP2) {
;             PG8_LDB(B0, 0, 0); PG8_LDB(B1, 0, 1); PG8_SCHED; PG8_LDA(At, 0, 0); PG8_STAGE(PG8_SA(1, 1), a1 + hstepA, voffA);
;             PG8_WAIT_V(8); PG8_WAIT_L(0); PG8_BAR; PG8_MMA(0, 0, At, B0); PG8_MMA(0, 1, At, B1); PG8_BAR; PG8_SCHED;
;             PG8_LDA(At, 0, 1); PG8_STAGE(PG8_SB(0, 0), b2, voffB); PG8_STAGE(PG8_SB(0, 1), b2 + hstepB, voffB); PG8_STAGE(PG8_SA(0, 0), a2, voffA);
;             PG8_WAIT_V(8); PG8_WAIT_L(0); PG8_BAR; PG8_MMA(1, 0, At, B0); PG8_MMA(1, 1, At, B1); PG8_BAR; PG8_SCHED;
.LBB0_1208:
	ds_read_b128 v[144:147], v153
	ds_read_b128 v[156:159], v153 offset:1024
	ds_read_b128 v[160:163], v153 offset:2048
	ds_read_b128 v[164:167], v153 offset:3072
	ds_read_b128 v[168:171], v154
	ds_read_b128 v[172:175], v154 offset:1024
	ds_read_b128 v[176:179], v154 offset:2048
	ds_read_b128 v[180:183], v154 offset:3072
	s_add_i32 s48, s46, 2
	s_add_u32 s49, s6, 0x80
	s_addc_u32 s47, s7, 0
	s_cmp_eq_u32 s61, s46
	s_cselect_b32 s46, s42, s49
	s_cselect_b32 s47, s43, s47
	s_cselect_b32 s81, s45, s78
	s_cselect_b32 s80, s44, s77
	v_lshl_add_u64 v[148:149], s[6:7], 0, v[140:141]
	s_add_i32 m0, s53, 0xc000
	ds_read_b128 v[184:187], v155
	ds_read_b128 v[188:191], v155 offset:1024
	ds_read_b128 v[192:195], v155 offset:2048
	ds_read_b128 v[196:199], v155 offset:3072
	ds_read_b128 v[200:203], v155 offset:4096
	ds_read_b128 v[204:207], v155 offset:5120
	ds_read_b128 v[208:211], v155 offset:6144
	ds_read_b128 v[212:215], v155 offset:7168
	global_load_lds_dwordx4 v[148:149], off
	v_lshl_add_u64 v[148:149], s[6:7], 0, v[138:139]
	s_add_i32 m0, s53, 0xe000
	s_nop 0
	global_load_lds_dwordx4 v[148:149], off
	s_waitcnt vmcnt(8)
	s_waitcnt lgkmcnt(0)
	s_barrier
	s_waitcnt lgkmcnt(0)
	v_mfma_f32_16x16x32_bf16 v[122:125], v[144:147], v[184:187], v[122:125]
	v_mfma_f32_16x16x32_bf16 v[126:129], v[160:163], v[184:187], v[126:129]
	v_mfma_f32_16x16x32_bf16 v[110:113], v[144:147], v[192:195], v[110:113]
	v_mfma_f32_16x16x32_bf16 v[106:109], v[160:163], v[192:195], v[106:109]
	v_mfma_f32_16x16x32_bf16 v[94:97], v[144:147], v[200:203], v[94:97]
	v_mfma_f32_16x16x32_bf16 v[90:93], v[160:163], v[200:203], v[90:93]
	v_mfma_f32_16x16x32_bf16 v[78:81], v[144:147], v[208:211], v[78:81]
	v_mfma_f32_16x16x32_bf16 v[74:77], v[160:163], v[208:211], v[74:77]
	v_mfma_f32_16x16x32_bf16 v[122:125], v[156:159], v[188:191], v[122:125]
	v_mfma_f32_16x16x32_bf16 v[126:129], v[164:167], v[188:191], v[126:129]
	v_mfma_f32_16x16x32_bf16 v[110:113], v[156:159], v[196:199], v[110:113]
	v_mfma_f32_16x16x32_bf16 v[106:109], v[164:167], v[196:199], v[106:109]
	v_mfma_f32_16x16x32_bf16 v[94:97], v[156:159], v[204:207], v[94:97]
	v_mfma_f32_16x16x32_bf16 v[90:93], v[164:167], v[204:207], v[90:93]
	v_mfma_f32_16x16x32_bf16 v[78:81], v[156:159], v[212:215], v[78:81]
	v_mfma_f32_16x16x32_bf16 v[74:77], v[164:167], v[212:215], v[74:77]
	v_mfma_f32_16x16x32_bf16 v[118:121], v[168:171], v[184:187], v[118:121]
	v_mfma_f32_16x16x32_bf16 v[114:117], v[176:179], v[184:187], v[114:117]
	v_mfma_f32_16x16x32_bf16 v[102:105], v[168:171], v[192:195], v[102:105]
	v_mfma_f32_16x16x32_bf16 v[98:101], v[176:179], v[192:195], v[98:101]
	v_mfma_f32_16x16x32_bf16 v[86:89], v[168:171], v[200:203], v[86:89]
	v_mfma_f32_16x16x32_bf16 v[82:85], v[176:179], v[200:203], v[82:85]
	v_mfma_f32_16x16x32_bf16 v[70:73], v[168:171], v[208:211], v[70:73]
	v_mfma_f32_16x16x32_bf16 v[66:69], v[176:179], v[208:211], v[66:69]
	v_mfma_f32_16x16x32_bf16 v[118:121], v[172:175], v[188:191], v[118:121]
	v_mfma_f32_16x16x32_bf16 v[114:117], v[180:183], v[188:191], v[114:117]
	v_mfma_f32_16x16x32_bf16 v[102:105], v[172:175], v[196:199], v[102:105]
	v_mfma_f32_16x16x32_bf16 v[98:101], v[180:183], v[196:199], v[98:101]
	v_mfma_f32_16x16x32_bf16 v[86:89], v[172:175], v[204:207], v[86:89]
	v_mfma_f32_16x16x32_bf16 v[82:85], v[180:183], v[204:207], v[82:85]
	v_mfma_f32_16x16x32_bf16 v[70:73], v[172:175], v[212:215], v[70:73]
	v_mfma_f32_16x16x32_bf16 v[66:69], v[180:183], v[212:215], v[66:69]
	s_barrier
	s_add_i32 s49, s68, s52
	v_lshl_add_u64 v[148:149], s[80:81], 0, v[132:133]
	s_mov_b32 m0, s49
	ds_read_b128 v[184:187], v155 offset:16384
	ds_read_b128 v[188:191], v155 offset:17408
	ds_read_b128 v[192:195], v155 offset:18432
	ds_read_b128 v[196:199], v155 offset:19456
	ds_read_b128 v[200:203], v155 offset:20480
	ds_read_b128 v[204:207], v155 offset:21504
	ds_read_b128 v[208:211], v155 offset:22528
	ds_read_b128 v[212:215], v155 offset:23552
	global_load_lds_dwordx4 v[148:149], off
	s_add_i32 m0, s49, 0x2000
	v_lshl_add_u64 v[216:217], s[80:81], 0, v[136:137]
	s_add_u32 s80, s80, s16
	s_addc_u32 s81, s81, s17
	s_add_i32 s49, s69, s52
	global_load_lds_dwordx4 v[216:217], off
	v_lshl_add_u64 v[218:219], s[80:81], 0, v[132:133]
	s_mov_b32 m0, s49
	v_lshl_add_u64 v[220:221], s[80:81], 0, v[136:137]
	global_load_lds_dwordx4 v[218:219], off
	s_add_i32 m0, s49, 0x2000
	v_lshl_add_u64 v[222:223], s[46:47], 0, v[130:131]
	global_load_lds_dwordx4 v[220:221], off
	s_mov_b32 m0, s53
	v_lshl_add_u64 v[224:225], s[46:47], 0, v[134:135]
	global_load_lds_dwordx4 v[222:223], off
	s_mov_b32 m0, s54
	s_nop 0
	global_load_lds_dwordx4 v[224:225], off
	s_waitcnt vmcnt(8)
	s_waitcnt lgkmcnt(0)
	s_barrier
; #define PG8_STAGE(bufoff, gbase, voff) do { _Pragma("unroll") for (int _i = 0; _i < 2; ++_i) \
;         __builtin_amdgcn_global_load_lds((const unsigned*)((const char*)(gbase) + (voff)[_i]), (PG8_LAS unsigned*)(lds + (bufoff) + ldsw + _i * 8192), 16, 0, 0); } while (0)
; #define PG8_LDA(dst, b, h) do { _Pragma("unroll") for (int m = 0; m < 4; ++m) _Pragma("unroll") for (int k = 0; k < 2; ++k) dst[m][k] = *(const PG8_LAS bf16x8*)(lds + PG8_SA(b, h) + aoff + m * 2048 + k * 1024); } while (0)
; #define PG8_LDB(dst, b, h) do { _Pragma("unroll") for (int n = 0; n < 2; ++n) _Pragma("unroll") for (int k = 0; k < 2; ++k) dst[n][k] = *(const PG8_LAS bf16x8*)(lds + PG8_SB(b, h) + boff + n * 2048 + k * 1024); } while (0)
; #define PG8_MMA(ai, bj, At, Bt) do { __builtin_amdgcn_s_setprio(1); _Pragma("unroll") for (int m = 0; m < 4; ++m) _Pragma("unroll") for (int n = 0; n < 2; ++n) _Pragma("unroll") for (int k = 0; k < 2; ++k) \
;         acc[ai][bj][m][n] = __builtin_amdgcn_mfma_f32_16x16x32_bf16(Bt[n][k], At[m][k], acc[ai][bj][m][n], 0, 0, 0); __builtin_amdgcn_s_setprio(0); } while (0)
; #define PG8_WAIT_V(n) asm volatile("s_waitcnt vmcnt(" #n ")" ::: "memory")
; #define PG8_WAIT_L(n) asm volatile("s_waitcnt lgkmcnt(" #n ")" ::: "memory")
; #define PG8_BAR __builtin_amdgcn_s_barrier()
; #define PG8_SCHED __builtin_amdgcn_sched_barrier(0)
; template <class Epi, class Sched, bool ALIGN_EPI = false, bool SP2 = false>
; __device__ __forceinline__ void gemm_phase(PG8_LAS unsigned char* lds, const Gemm g, const Sched& S, const Epi& E) {
;     ...
;             PG8_WAIT_V(8); PG8_WAIT_L(0); PG8_BAR; PG8_MMA(1, 0, At, B0); PG8_MMA(1, 1, At, B1); PG8_BAR; PG8_SCHED;
;             PG8_LDB(B0, 1, 0); PG8_LDB(B1, 1, 1); PG8_SCHED; PG8_LDA(At, 1, 0); PG8_STAGE(PG8_SA(0, 1), a2 + hstepA, voffA);
;             PG8_WAIT_V(8); PG8_WAIT_L(0); PG8_BAR; PG8_MMA(0, 0, At, B0); PG8_MMA(0, 1, At, B1); PG8_BAR; PG8_SCHED;
	s_waitcnt lgkmcnt(0)
	v_mfma_f32_16x16x32_bf16 v[62:65], v[144:147], v[184:187], v[62:65]
	v_mfma_f32_16x16x32_bf16 v[58:61], v[160:163], v[184:187], v[58:61]
	v_mfma_f32_16x16x32_bf16 v[46:49], v[144:147], v[192:195], v[46:49]
	v_mfma_f32_16x16x32_bf16 v[42:45], v[160:163], v[192:195], v[42:45]
	v_mfma_f32_16x16x32_bf16 v[30:33], v[144:147], v[200:203], v[30:33]
	v_mfma_f32_16x16x32_bf16 v[26:29], v[160:163], v[200:203], v[26:29]
	v_mfma_f32_16x16x32_bf16 v[14:17], v[144:147], v[208:211], v[14:17]
	v_mfma_f32_16x16x32_bf16 v[10:13], v[160:163], v[208:211], v[10:13]
	v_mfma_f32_16x16x32_bf16 v[62:65], v[156:159], v[188:191], v[62:65]
	v_mfma_f32_16x16x32_bf16 v[58:61], v[164:167], v[188:191], v[58:61]
	v_mfma_f32_16x16x32_bf16 v[46:49], v[156:159], v[196:199], v[46:49]
	v_mfma_f32_16x16x32_bf16 v[42:45], v[164:167], v[196:199], v[42:45]
	v_mfma_f32_16x16x32_bf16 v[30:33], v[156:159], v[204:207], v[30:33]
	v_mfma_f32_16x16x32_bf16 v[26:29], v[164:167], v[204:207], v[26:29]
	v_mfma_f32_16x16x32_bf16 v[14:17], v[156:159], v[212:215], v[14:17]
	v_mfma_f32_16x16x32_bf16 v[10:13], v[164:167], v[212:215], v[10:13]
	v_mfma_f32_16x16x32_bf16 v[54:57], v[168:171], v[184:187], v[54:57]
	v_mfma_f32_16x16x32_bf16 v[50:53], v[176:179], v[184:187], v[50:53]
	v_mfma_f32_16x16x32_bf16 v[38:41], v[168:171], v[192:195], v[38:41]
	v_mfma_f32_16x16x32_bf16 v[34:37], v[176:179], v[192:195], v[34:37]
	v_mfma_f32_16x16x32_bf16 v[22:25], v[168:171], v[200:203], v[22:25]
	v_mfma_f32_16x16x32_bf16 v[18:21], v[176:179], v[200:203], v[18:21]
	v_mfma_f32_16x16x32_bf16 v[6:9], v[168:171], v[208:211], v[6:9]
	v_mfma_f32_16x16x32_bf16 v[2:5], v[176:179], v[208:211], v[2:5]
	v_mfma_f32_16x16x32_bf16 v[54:57], v[172:175], v[188:191], v[54:57]
	v_mfma_f32_16x16x32_bf16 v[50:53], v[180:183], v[188:191], v[50:53]
	v_mfma_f32_16x16x32_bf16 v[38:41], v[172:175], v[196:199], v[38:41]
	v_mfma_f32_16x16x32_bf16 v[34:37], v[180:183], v[196:199], v[34:37]
	v_mfma_f32_16x16x32_bf16 v[22:25], v[172:175], v[204:207], v[22:25]
	v_mfma_f32_16x16x32_bf16 v[18:21], v[180:183], v[204:207], v[18:21]
	v_mfma_f32_16x16x32_bf16 v[6:9], v[172:175], v[212:215], v[6:9]
	v_mfma_f32_16x16x32_bf16 v[2:5], v[180:183], v[212:215], v[2:5]
	s_barrier
	s_add_i32 s49, 0, 0x18000
	s_add_i32 s79, 0, 0x1c000
	v_add_u32_e32 v164, s49, v151
	v_add_u32_e32 v180, s79, v151
	ds_read_b128 v[144:147], v164
	ds_read_b128 v[156:159], v164 offset:1024
	ds_read_b128 v[160:163], v164 offset:2048
	ds_read_b128 v[164:167], v164 offset:3072
	ds_read_b128 v[168:171], v180
	ds_read_b128 v[172:175], v180 offset:1024
	ds_read_b128 v[176:179], v180 offset:2048
	ds_read_b128 v[180:183], v180 offset:3072
	s_add_u32 s46, s46, s10
	s_addc_u32 s47, s47, s11
	s_mov_b32 m0, s55
	v_lshl_add_u64 v[226:227], s[46:47], 0, v[130:131]
	ds_read_b128 v[184:187], v155 offset:32768
	ds_read_b128 v[188:191], v155 offset:33792
	ds_read_b128 v[192:195], v155 offset:34816
	ds_read_b128 v[196:199], v155 offset:35840
	ds_read_b128 v[200:203], v155 offset:36864
	ds_read_b128 v[204:207], v155 offset:37888
	ds_read_b128 v[208:211], v155 offset:38912
	ds_read_b128 v[212:215], v155 offset:39936
	global_load_lds_dwordx4 v[226:227], off
	v_lshl_add_u64 v[226:227], s[46:47], 0, v[134:135]
	s_mov_b32 m0, s56
	s_nop 0
	global_load_lds_dwordx4 v[226:227], off
	s_waitcnt vmcnt(8)
	s_waitcnt lgkmcnt(0)
	s_barrier
	s_waitcnt lgkmcnt(0)
	v_mfma_f32_16x16x32_bf16 v[122:125], v[144:147], v[184:187], v[122:125]
	v_mfma_f32_16x16x32_bf16 v[126:129], v[160:163], v[184:187], v[126:129]
	v_mfma_f32_16x16x32_bf16 v[110:113], v[144:147], v[192:195], v[110:113]
	v_mfma_f32_16x16x32_bf16 v[106:109], v[160:163], v[192:195], v[106:109]
	v_mfma_f32_16x16x32_bf16 v[94:97], v[144:147], v[200:203], v[94:97]
	v_mfma_f32_16x16x32_bf16 v[90:93], v[160:163], v[200:203], v[90:93]
	v_mfma_f32_16x16x32_bf16 v[78:81], v[144:147], v[208:211], v[78:81]
	v_mfma_f32_16x16x32_bf16 v[74:77], v[160:163], v[208:211], v[74:77]
	v_mfma_f32_16x16x32_bf16 v[122:125], v[156:159], v[188:191], v[122:125]
	v_mfma_f32_16x16x32_bf16 v[126:129], v[164:167], v[188:191], v[126:129]
	v_mfma_f32_16x16x32_bf16 v[110:113], v[156:159], v[196:199], v[110:113]
	v_mfma_f32_16x16x32_bf16 v[106:109], v[164:167], v[196:199], v[106:109]
	v_mfma_f32_16x16x32_bf16 v[94:97], v[156:159], v[204:207], v[94:97]
	v_mfma_f32_16x16x32_bf16 v[90:93], v[164:167], v[204:207], v[90:93]
	v_mfma_f32_16x16x32_bf16 v[78:81], v[156:159], v[212:215], v[78:81]
	v_mfma_f32_16x16x32_bf16 v[74:77], v[164:167], v[212:215], v[74:77]
	v_mfma_f32_16x16x32_bf16 v[118:121], v[168:171], v[184:187], v[118:121]
	v_mfma_f32_16x16x32_bf16 v[114:117], v[176:179], v[184:187], v[114:117]
	v_mfma_f32_16x16x32_bf16 v[102:105], v[168:171], v[192:195], v[102:105]
	v_mfma_f32_16x16x32_bf16 v[98:101], v[176:179], v[192:195], v[98:101]
	v_mfma_f32_16x16x32_bf16 v[86:89], v[168:171], v[200:203], v[86:89]
	v_mfma_f32_16x16x32_bf16 v[82:85], v[176:179], v[200:203], v[82:85]
	v_mfma_f32_16x16x32_bf16 v[70:73], v[168:171], v[208:211], v[70:73]
	v_mfma_f32_16x16x32_bf16 v[66:69], v[176:179], v[208:211], v[66:69]
	v_mfma_f32_16x16x32_bf16 v[118:121], v[172:175], v[188:191], v[118:121]
	v_mfma_f32_16x16x32_bf16 v[114:117], v[180:183], v[188:191], v[114:117]
	v_mfma_f32_16x16x32_bf16 v[102:105], v[172:175], v[196:199], v[102:105]
	v_mfma_f32_16x16x32_bf16 v[98:101], v[180:183], v[196:199], v[98:101]
	v_mfma_f32_16x16x32_bf16 v[86:89], v[172:175], v[204:207], v[86:89]
	v_mfma_f32_16x16x32_bf16 v[82:85], v[180:183], v[204:207], v[82:85]
	v_mfma_f32_16x16x32_bf16 v[70:73], v[172:175], v[212:215], v[70:73]
	v_mfma_f32_16x16x32_bf16 v[66:69], v[180:183], v[212:215], v[66:69]
	s_barrier
; #define PG8_STAGE(bufoff, gbase, voff) do { _Pragma("unroll") for (int _i = 0; _i < 2; ++_i) \
;         __builtin_amdgcn_global_load_lds((const unsigned*)((const char*)(gbase) + (voff)[_i]), (PG8_LAS unsigned*)(lds + (bufoff) + ldsw + _i * 8192), 16, 0, 0); } while (0)
; #define PG8_LDA(dst, b, h) do { _Pragma("unroll") for (int m = 0; m < 4; ++m) _Pragma("unroll") for (int k = 0; k < 2; ++k) dst[m][k] = *(const PG8_LAS bf16x8*)(lds + PG8_SA(b, h) + aoff + m * 2048 + k * 1024); } while (0)
; #define PG8_MMA(ai, bj, At, Bt) do { __builtin_amdgcn_s_setprio(1); _Pragma("unroll") for (int m = 0; m < 4; ++m) _Pragma("unroll") for (int n = 0; n < 2; ++n) _Pragma("unroll") for (int k = 0; k < 2; ++k) \
;         acc[ai][bj][m][n] = __builtin_amdgcn_mfma_f32_16x16x32_bf16(Bt[n][k], At[m][k], acc[ai][bj][m][n], 0, 0, 0); __builtin_amdgcn_s_setprio(0); } while (0)
; #define PG8_WAIT_V(n) asm volatile("s_waitcnt vmcnt(" #n ")" ::: "memory")
; #define PG8_WAIT_L(n) asm volatile("s_waitcnt lgkmcnt(" #n ")" ::: "memory")
; #define PG8_BAR __builtin_amdgcn_s_barrier()
; #define PG8_SCHED __builtin_amdgcn_sched_barrier(0)
; template <class Epi, class Sched, bool ALIGN_EPI = false, bool SP2 = false>
; __device__ __forceinline__ void gemm_phase(PG8_LAS unsigned char* lds, const Gemm g, const Sched& S, const Epi& E) {
;     ...
;             PG8_LDA(At, 1, 1); PG8_STAGE(PG8_SB(1, 0), b3, voffB); PG8_STAGE(PG8_SB(1, 1), b3 + hstepB, voffB); PG8_STAGE(PG8_SA(1, 0), a3, voffA);
;             PG8_WAIT_V(8); PG8_WAIT_L(0); PG8_BAR; PG8_MMA(1, 0, At, B0); PG8_MMA(1, 1, At, B1); PG8_BAR; PG8_SCHED;
	s_add_i32 s46, s49, s52
	v_lshl_add_u64 v[148:149], v[148:149], 0, s[34:35]
	s_mov_b32 m0, s46
	ds_read_b128 v[184:187], v155 offset:49152
	ds_read_b128 v[188:191], v155 offset:50176
	ds_read_b128 v[192:195], v155 offset:51200
	ds_read_b128 v[196:199], v155 offset:52224
	ds_read_b128 v[200:203], v155 offset:53248
	ds_read_b128 v[204:207], v155 offset:54272
	ds_read_b128 v[208:211], v155 offset:55296
	ds_read_b128 v[212:215], v155 offset:56320
	global_load_lds_dwordx4 v[148:149], off
	v_lshl_add_u64 v[148:149], v[216:217], 0, s[34:35]
	s_add_i32 m0, s46, 0x2000
	s_add_i32 s46, s79, s52
	global_load_lds_dwordx4 v[148:149], off
	v_lshl_add_u64 v[148:149], v[218:219], 0, s[34:35]
	s_mov_b32 m0, s46
	s_nop 0
	global_load_lds_dwordx4 v[148:149], off
	v_lshl_add_u64 v[148:149], v[220:221], 0, s[34:35]
	s_add_i32 m0, s46, 0x2000
	s_nop 0
	global_load_lds_dwordx4 v[148:149], off
	v_lshl_add_u64 v[148:149], v[222:223], 0, s[34:35]
	s_mov_b32 m0, s58
	s_nop 0
	global_load_lds_dwordx4 v[148:149], off
	v_lshl_add_u64 v[148:149], v[224:225], 0, s[34:35]
	s_mov_b32 m0, s59
	s_nop 0
	global_load_lds_dwordx4 v[148:149], off
	s_waitcnt vmcnt(8)
	s_waitcnt lgkmcnt(0)
	s_barrier
	s_waitcnt lgkmcnt(0)
	v_mfma_f32_16x16x32_bf16 v[62:65], v[144:147], v[184:187], v[62:65]
	v_mfma_f32_16x16x32_bf16 v[58:61], v[160:163], v[184:187], v[58:61]
	v_mfma_f32_16x16x32_bf16 v[46:49], v[144:147], v[192:195], v[46:49]
	v_mfma_f32_16x16x32_bf16 v[42:45], v[160:163], v[192:195], v[42:45]
	v_mfma_f32_16x16x32_bf16 v[30:33], v[144:147], v[200:203], v[30:33]
	v_mfma_f32_16x16x32_bf16 v[26:29], v[160:163], v[200:203], v[26:29]
	v_mfma_f32_16x16x32_bf16 v[14:17], v[144:147], v[208:211], v[14:17]
	v_mfma_f32_16x16x32_bf16 v[10:13], v[160:163], v[208:211], v[10:13]
	v_mfma_f32_16x16x32_bf16 v[62:65], v[156:159], v[188:191], v[62:65]
	v_mfma_f32_16x16x32_bf16 v[58:61], v[164:167], v[188:191], v[58:61]
	v_mfma_f32_16x16x32_bf16 v[46:49], v[156:159], v[196:199], v[46:49]
	v_mfma_f32_16x16x32_bf16 v[42:45], v[164:167], v[196:199], v[42:45]
	v_mfma_f32_16x16x32_bf16 v[30:33], v[156:159], v[204:207], v[30:33]
	v_mfma_f32_16x16x32_bf16 v[26:29], v[164:167], v[204:207], v[26:29]
	v_mfma_f32_16x16x32_bf16 v[14:17], v[156:159], v[212:215], v[14:17]
	v_mfma_f32_16x16x32_bf16 v[10:13], v[164:167], v[212:215], v[10:13]
	v_mfma_f32_16x16x32_bf16 v[54:57], v[168:171], v[184:187], v[54:57]
	v_mfma_f32_16x16x32_bf16 v[50:53], v[176:179], v[184:187], v[50:53]
	v_mfma_f32_16x16x32_bf16 v[38:41], v[168:171], v[192:195], v[38:41]
	v_mfma_f32_16x16x32_bf16 v[34:37], v[176:179], v[192:195], v[34:37]
	v_mfma_f32_16x16x32_bf16 v[22:25], v[168:171], v[200:203], v[22:25]
	v_mfma_f32_16x16x32_bf16 v[18:21], v[176:179], v[200:203], v[18:21]
	v_mfma_f32_16x16x32_bf16 v[6:9], v[168:171], v[208:211], v[6:9]
	v_mfma_f32_16x16x32_bf16 v[2:5], v[176:179], v[208:211], v[2:5]
	v_mfma_f32_16x16x32_bf16 v[54:57], v[172:175], v[188:191], v[54:57]
	v_mfma_f32_16x16x32_bf16 v[50:53], v[180:183], v[188:191], v[50:53]
	v_mfma_f32_16x16x32_bf16 v[38:41], v[172:175], v[196:199], v[38:41]
	v_mfma_f32_16x16x32_bf16 v[34:37], v[180:183], v[196:199], v[34:37]
	v_mfma_f32_16x16x32_bf16 v[22:25], v[172:175], v[204:207], v[22:25]
	v_mfma_f32_16x16x32_bf16 v[18:21], v[180:183], v[204:207], v[18:21]
	v_mfma_f32_16x16x32_bf16 v[6:9], v[172:175], v[212:215], v[6:9]
	v_mfma_f32_16x16x32_bf16 v[2:5], v[180:183], v[212:215], v[2:5]
	s_barrier
	s_add_u32 s77, s77, 0x100
	s_addc_u32 s78, s78, 0
	s_add_u32 s6, s6, 0x100
	s_addc_u32 s7, s7, 0
	s_cmp_ge_i32 s48, s60
	s_mov_b32 s46, s48
	s_cbranch_scc0 .LBB0_1208

; #define PG8_STAGE(bufoff, gbase, voff) do { _Pragma("unroll") for (int _i = 0; _i < 2; ++_i) \
;         __builtin_amdgcn_global_load_lds((const unsigned*)((const char*)(gbase) + (voff)[_i]), (PG8_LAS unsigned*)(lds + (bufoff) + ldsw + _i * 8192), 16, 0, 0); } while (0)
; #define PG8_LDA(dst, b, h) do { _Pragma("unroll") for (int m = 0; m < 4; ++m) _Pragma("unroll") for (int k = 0; k < 2; ++k) dst[m][k] = *(const PG8_LAS bf16x8*)(lds + PG8_SA(b, h) + aoff + m * 2048 + k * 1024); } while (0)
; #define PG8_LDB(dst, b, h) do { _Pragma("unroll") for (int n = 0; n < 2; ++n) _Pragma("unroll") for (int k = 0; k < 2; ++k) dst[n][k] = *(const PG8_LAS bf16x8*)(lds + PG8_SB(b, h) + boff + n * 2048 + k * 1024); } while (0)
; #define PG8_MMA(ai, bj, At, Bt) do { __builtin_amdgcn_s_setprio(1); _Pragma("unroll") for (int m = 0; m < 4; ++m) _Pragma("unroll") for (int n = 0; n < 2; ++n) _Pragma("unroll") for (int k = 0; k < 2; ++k) \
;         acc[ai][bj][m][n] = __builtin_amdgcn_mfma_f32_16x16x32_bf16(Bt[n][k], At[m][k], acc[ai][bj][m][n], 0, 0, 0); __builtin_amdgcn_s_setprio(0); } while (0)
; #define PG8_WAIT_V(n) asm volatile("s_waitcnt vmcnt(" #n ")" ::: "memory")
; #define PG8_BAR __builtin_amdgcn_s_barrier()
; template <class Epi, class Sched, bool ALIGN_EPI = false, bool SP2 = false>
; __device__ __forceinline__ void gemm_phase(PG8_LAS unsigned char* lds, const Gemm g, const Sched& S, const Epi& E) {
;     ...
;         for (int t = 0; t < nt; t += 2) {
;             const bool last = (t == nt - 2);
;             const char* a1 = cA + (size_t)(t + 1) * kstep;
;             const char* a2 = last ? nA : cA + (size_t)(t + 2) * kstep; const char* b2 = last ? nB : cB + (size_t)(t + 2) * kstep;
;             const char* a3 = a2 + kstep; const char* b3 = b2 + kstep;
;             if (last && has_next) S.a_ready(nxt);
;             if constexpr (SP2) {
;             PG8_LDB(B0, 0, 0); PG8_LDB(B1, 0, 1); PG8_SCHED; PG8_LDA(At, 0, 0); PG8_STAGE(PG8_SA(1, 1), a1 + hstepA, voffA);
;             PG8_WAIT_V(8); PG8_WAIT_L(0); PG8_BAR; PG8_MMA(0, 0, At, B0); PG8_MMA(0, 1, At, B1); PG8_BAR; PG8_SCHED;
;             PG8_LDA(At, 0, 1); PG8_STAGE(PG8_SB(0, 0), b2, voffB); PG8_STAGE(PG8_SB(0, 1), b2 + hstepB, voffB); PG8_STAGE(PG8_SA(0, 0), a2, voffA);
;             PG8_WAIT_V(8); PG8_WAIT_L(0); PG8_BAR; PG8_MMA(1, 0, At, B0); PG8_MMA(1, 1, At, B1); PG8_BAR; PG8_SCHED;
.LBB0_1332:
	ds_read_b128 v[144:147], v153
	ds_read_b128 v[156:159], v153 offset:1024
	ds_read_b128 v[160:163], v153 offset:2048
	ds_read_b128 v[164:167], v153 offset:3072
	ds_read_b128 v[168:171], v154
	ds_read_b128 v[172:175], v154 offset:1024
	ds_read_b128 v[176:179], v154 offset:2048
	ds_read_b128 v[180:183], v154 offset:3072
	s_add_i32 s50, s48, 2
	s_add_u32 s51, s6, 0x80
	s_addc_u32 s49, s7, 0
	s_cmp_eq_u32 s62, s48
	s_cselect_b32 s48, s44, s51
	s_cselect_b32 s49, s45, s49
	s_cselect_b32 s81, s47, s78
	s_cselect_b32 s80, s46, s77
	v_lshl_add_u64 v[148:149], s[6:7], 0, v[140:141]
	s_add_i32 m0, s53, 0xc000
	ds_read_b128 v[184:187], v155
	ds_read_b128 v[188:191], v155 offset:1024
	ds_read_b128 v[192:195], v155 offset:2048
	ds_read_b128 v[196:199], v155 offset:3072
	ds_read_b128 v[200:203], v155 offset:4096
	ds_read_b128 v[204:207], v155 offset:5120
	ds_read_b128 v[208:211], v155 offset:6144
	ds_read_b128 v[212:215], v155 offset:7168
	global_load_lds_dwordx4 v[148:149], off
	v_lshl_add_u64 v[148:149], s[6:7], 0, v[138:139]
	s_add_i32 m0, s53, 0xe000
	s_nop 0
	global_load_lds_dwordx4 v[148:149], off
	s_waitcnt vmcnt(8)
	s_waitcnt lgkmcnt(0)
	s_barrier
	s_waitcnt lgkmcnt(0)
	v_mfma_f32_16x16x32_bf16 v[122:125], v[144:147], v[184:187], v[122:125]
	v_mfma_f32_16x16x32_bf16 v[126:129], v[160:163], v[184:187], v[126:129]
	v_mfma_f32_16x16x32_bf16 v[110:113], v[144:147], v[192:195], v[110:113]
	v_mfma_f32_16x16x32_bf16 v[106:109], v[160:163], v[192:195], v[106:109]
	v_mfma_f32_16x16x32_bf16 v[94:97], v[144:147], v[200:203], v[94:97]
	v_mfma_f32_16x16x32_bf16 v[90:93], v[160:163], v[200:203], v[90:93]
	v_mfma_f32_16x16x32_bf16 v[78:81], v[144:147], v[208:211], v[78:81]
	v_mfma_f32_16x16x32_bf16 v[74:77], v[160:163], v[208:211], v[74:77]
	v_mfma_f32_16x16x32_bf16 v[122:125], v[156:159], v[188:191], v[122:125]
	v_mfma_f32_16x16x32_bf16 v[126:129], v[164:167], v[188:191], v[126:129]
	v_mfma_f32_16x16x32_bf16 v[110:113], v[156:159], v[196:199], v[110:113]
	v_mfma_f32_16x16x32_bf16 v[106:109], v[164:167], v[196:199], v[106:109]
	v_mfma_f32_16x16x32_bf16 v[94:97], v[156:159], v[204:207], v[94:97]
	v_mfma_f32_16x16x32_bf16 v[90:93], v[164:167], v[204:207], v[90:93]
	v_mfma_f32_16x16x32_bf16 v[78:81], v[156:159], v[212:215], v[78:81]
	v_mfma_f32_16x16x32_bf16 v[74:77], v[164:167], v[212:215], v[74:77]
	v_mfma_f32_16x16x32_bf16 v[118:121], v[168:171], v[184:187], v[118:121]
	v_mfma_f32_16x16x32_bf16 v[114:117], v[176:179], v[184:187], v[114:117]
	v_mfma_f32_16x16x32_bf16 v[102:105], v[168:171], v[192:195], v[102:105]
	v_mfma_f32_16x16x32_bf16 v[98:101], v[176:179], v[192:195], v[98:101]
	v_mfma_f32_16x16x32_bf16 v[86:89], v[168:171], v[200:203], v[86:89]
	v_mfma_f32_16x16x32_bf16 v[82:85], v[176:179], v[200:203], v[82:85]
	v_mfma_f32_16x16x32_bf16 v[70:73], v[168:171], v[208:211], v[70:73]
	v_mfma_f32_16x16x32_bf16 v[66:69], v[176:179], v[208:211], v[66:69]
	v_mfma_f32_16x16x32_bf16 v[118:121], v[172:175], v[188:191], v[118:121]
	v_mfma_f32_16x16x32_bf16 v[114:117], v[180:183], v[188:191], v[114:117]
	v_mfma_f32_16x16x32_bf16 v[102:105], v[172:175], v[196:199], v[102:105]
	v_mfma_f32_16x16x32_bf16 v[98:101], v[180:183], v[196:199], v[98:101]
	v_mfma_f32_16x16x32_bf16 v[86:89], v[172:175], v[204:207], v[86:89]
	v_mfma_f32_16x16x32_bf16 v[82:85], v[180:183], v[204:207], v[82:85]
	v_mfma_f32_16x16x32_bf16 v[70:73], v[172:175], v[212:215], v[70:73]
	v_mfma_f32_16x16x32_bf16 v[66:69], v[180:183], v[212:215], v[66:69]
	s_barrier
	s_add_i32 s51, s69, s52
	v_lshl_add_u64 v[148:149], s[80:81], 0, v[132:133]
	s_mov_b32 m0, s51
	ds_read_b128 v[184:187], v155 offset:16384
	ds_read_b128 v[188:191], v155 offset:17408
	ds_read_b128 v[192:195], v155 offset:18432
	ds_read_b128 v[196:199], v155 offset:19456
	ds_read_b128 v[200:203], v155 offset:20480
	ds_read_b128 v[204:207], v155 offset:21504
	ds_read_b128 v[208:211], v155 offset:22528
	ds_read_b128 v[212:215], v155 offset:23552
	global_load_lds_dwordx4 v[148:149], off
	s_add_i32 m0, s51, 0x2000
	v_lshl_add_u64 v[216:217], s[80:81], 0, v[136:137]
	s_add_u32 s80, s80, s16
	s_addc_u32 s81, s81, s17
	s_add_i32 s51, s70, s52
	global_load_lds_dwordx4 v[216:217], off
	v_lshl_add_u64 v[218:219], s[80:81], 0, v[132:133]
	s_mov_b32 m0, s51
	v_lshl_add_u64 v[220:221], s[80:81], 0, v[136:137]
	global_load_lds_dwordx4 v[218:219], off
	s_add_i32 m0, s51, 0x2000
	v_lshl_add_u64 v[222:223], s[48:49], 0, v[130:131]
	global_load_lds_dwordx4 v[220:221], off
	s_mov_b32 m0, s53
	v_lshl_add_u64 v[224:225], s[48:49], 0, v[134:135]
	global_load_lds_dwordx4 v[222:223], off
	s_mov_b32 m0, s54
	s_nop 0
	global_load_lds_dwordx4 v[224:225], off
	s_waitcnt vmcnt(8)
	s_waitcnt lgkmcnt(0)
	s_barrier
; #define PG8_STAGE(bufoff, gbase, voff) do { _Pragma("unroll") for (int _i = 0; _i < 2; ++_i) \
;         __builtin_amdgcn_global_load_lds((const unsigned*)((const char*)(gbase) + (voff)[_i]), (PG8_LAS unsigned*)(lds + (bufoff) + ldsw + _i * 8192), 16, 0, 0); } while (0)
; #define PG8_LDA(dst, b, h) do { _Pragma("unroll") for (int m = 0; m < 4; ++m) _Pragma("unroll") for (int k = 0; k < 2; ++k) dst[m][k] = *(const PG8_LAS bf16x8*)(lds + PG8_SA(b, h) + aoff + m * 2048 + k * 1024); } while (0)
; #define PG8_LDB(dst, b, h) do { _Pragma("unroll") for (int n = 0; n < 2; ++n) _Pragma("unroll") for (int k = 0; k < 2; ++k) dst[n][k] = *(const PG8_LAS bf16x8*)(lds + PG8_SB(b, h) + boff + n * 2048 + k * 1024); } while (0)
; #define PG8_MMA(ai, bj, At, Bt) do { __builtin_amdgcn_s_setprio(1); _Pragma("unroll") for (int m = 0; m < 4; ++m) _Pragma("unroll") for (int n = 0; n < 2; ++n) _Pragma("unroll") for (int k = 0; k < 2; ++k) \
;         acc[ai][bj][m][n] = __builtin_amdgcn_mfma_f32_16x16x32_bf16(Bt[n][k], At[m][k], acc[ai][bj][m][n], 0, 0, 0); __builtin_amdgcn_s_setprio(0); } while (0)
; #define PG8_WAIT_V(n) asm volatile("s_waitcnt vmcnt(" #n ")" ::: "memory")
; #define PG8_WAIT_L(n) asm volatile("s_waitcnt lgkmcnt(" #n ")" ::: "memory")
; #define PG8_BAR __builtin_amdgcn_s_barrier()
; #define PG8_SCHED __builtin_amdgcn_sched_barrier(0)
; template <class Epi, class Sched, bool ALIGN_EPI = false, bool SP2 = false>
; __device__ __forceinline__ void gemm_phase(PG8_LAS unsigned char* lds, const Gemm g, const Sched& S, const Epi& E) {
;     ...
;             PG8_WAIT_V(8); PG8_WAIT_L(0); PG8_BAR; PG8_MMA(1, 0, At, B0); PG8_MMA(1, 1, At, B1); PG8_BAR; PG8_SCHED;
;             PG8_LDB(B0, 1, 0); PG8_LDB(B1, 1, 1); PG8_SCHED; PG8_LDA(At, 1, 0); PG8_STAGE(PG8_SA(0, 1), a2 + hstepA, voffA);
;             PG8_WAIT_V(8); PG8_WAIT_L(0); PG8_BAR; PG8_MMA(0, 0, At, B0); PG8_MMA(0, 1, At, B1); PG8_BAR; PG8_SCHED;
	s_waitcnt lgkmcnt(0)
	v_mfma_f32_16x16x32_bf16 v[62:65], v[144:147], v[184:187], v[62:65]
	v_mfma_f32_16x16x32_bf16 v[58:61], v[160:163], v[184:187], v[58:61]
	v_mfma_f32_16x16x32_bf16 v[46:49], v[144:147], v[192:195], v[46:49]
	v_mfma_f32_16x16x32_bf16 v[42:45], v[160:163], v[192:195], v[42:45]
	v_mfma_f32_16x16x32_bf16 v[30:33], v[144:147], v[200:203], v[30:33]
	v_mfma_f32_16x16x32_bf16 v[26:29], v[160:163], v[200:203], v[26:29]
	v_mfma_f32_16x16x32_bf16 v[14:17], v[144:147], v[208:211], v[14:17]
	v_mfma_f32_16x16x32_bf16 v[10:13], v[160:163], v[208:211], v[10:13]
	v_mfma_f32_16x16x32_bf16 v[62:65], v[156:159], v[188:191], v[62:65]
	v_mfma_f32_16x16x32_bf16 v[58:61], v[164:167], v[188:191], v[58:61]
	v_mfma_f32_16x16x32_bf16 v[46:49], v[156:159], v[196:199], v[46:49]
	v_mfma_f32_16x16x32_bf16 v[42:45], v[164:167], v[196:199], v[42:45]
	v_mfma_f32_16x16x32_bf16 v[30:33], v[156:159], v[204:207], v[30:33]
	v_mfma_f32_16x16x32_bf16 v[26:29], v[164:167], v[204:207], v[26:29]
	v_mfma_f32_16x16x32_bf16 v[14:17], v[156:159], v[212:215], v[14:17]
	v_mfma_f32_16x16x32_bf16 v[10:13], v[164:167], v[212:215], v[10:13]
	v_mfma_f32_16x16x32_bf16 v[54:57], v[168:171], v[184:187], v[54:57]
	v_mfma_f32_16x16x32_bf16 v[50:53], v[176:179], v[184:187], v[50:53]
	v_mfma_f32_16x16x32_bf16 v[38:41], v[168:171], v[192:195], v[38:41]
	v_mfma_f32_16x16x32_bf16 v[34:37], v[176:179], v[192:195], v[34:37]
	v_mfma_f32_16x16x32_bf16 v[22:25], v[168:171], v[200:203], v[22:25]
	v_mfma_f32_16x16x32_bf16 v[18:21], v[176:179], v[200:203], v[18:21]
	v_mfma_f32_16x16x32_bf16 v[6:9], v[168:171], v[208:211], v[6:9]
	v_mfma_f32_16x16x32_bf16 v[2:5], v[176:179], v[208:211], v[2:5]
	v_mfma_f32_16x16x32_bf16 v[54:57], v[172:175], v[188:191], v[54:57]
	v_mfma_f32_16x16x32_bf16 v[50:53], v[180:183], v[188:191], v[50:53]
	v_mfma_f32_16x16x32_bf16 v[38:41], v[172:175], v[196:199], v[38:41]
	v_mfma_f32_16x16x32_bf16 v[34:37], v[180:183], v[196:199], v[34:37]
	v_mfma_f32_16x16x32_bf16 v[22:25], v[172:175], v[204:207], v[22:25]
	v_mfma_f32_16x16x32_bf16 v[18:21], v[180:183], v[204:207], v[18:21]
	v_mfma_f32_16x16x32_bf16 v[6:9], v[172:175], v[212:215], v[6:9]
	v_mfma_f32_16x16x32_bf16 v[2:5], v[180:183], v[212:215], v[2:5]
	s_barrier
	s_add_i32 s51, 0, 0x18000
	s_add_i32 s79, 0, 0x1c000
	v_add_u32_e32 v164, s51, v151
	v_add_u32_e32 v180, s79, v151
	ds_read_b128 v[144:147], v164
	ds_read_b128 v[156:159], v164 offset:1024
	ds_read_b128 v[160:163], v164 offset:2048
	ds_read_b128 v[164:167], v164 offset:3072
	ds_read_b128 v[168:171], v180
	ds_read_b128 v[172:175], v180 offset:1024
	ds_read_b128 v[176:179], v180 offset:2048
	ds_read_b128 v[180:183], v180 offset:3072
	s_add_u32 s48, s48, s10
	s_addc_u32 s49, s49, s11
	s_mov_b32 m0, s55
	v_lshl_add_u64 v[226:227], s[48:49], 0, v[130:131]
	ds_read_b128 v[184:187], v155 offset:32768
	ds_read_b128 v[188:191], v155 offset:33792
	ds_read_b128 v[192:195], v155 offset:34816
	ds_read_b128 v[196:199], v155 offset:35840
	ds_read_b128 v[200:203], v155 offset:36864
	ds_read_b128 v[204:207], v155 offset:37888
	ds_read_b128 v[208:211], v155 offset:38912
	ds_read_b128 v[212:215], v155 offset:39936
	global_load_lds_dwordx4 v[226:227], off
	v_lshl_add_u64 v[226:227], s[48:49], 0, v[134:135]
	s_mov_b32 m0, s56
	s_nop 0
	global_load_lds_dwordx4 v[226:227], off
	s_waitcnt vmcnt(8)
	s_waitcnt lgkmcnt(0)
	s_barrier
	s_waitcnt lgkmcnt(0)
	v_mfma_f32_16x16x32_bf16 v[122:125], v[144:147], v[184:187], v[122:125]
	v_mfma_f32_16x16x32_bf16 v[126:129], v[160:163], v[184:187], v[126:129]
	v_mfma_f32_16x16x32_bf16 v[110:113], v[144:147], v[192:195], v[110:113]
	v_mfma_f32_16x16x32_bf16 v[106:109], v[160:163], v[192:195], v[106:109]
	v_mfma_f32_16x16x32_bf16 v[94:97], v[144:147], v[200:203], v[94:97]
	v_mfma_f32_16x16x32_bf16 v[90:93], v[160:163], v[200:203], v[90:93]
	v_mfma_f32_16x16x32_bf16 v[78:81], v[144:147], v[208:211], v[78:81]
	v_mfma_f32_16x16x32_bf16 v[74:77], v[160:163], v[208:211], v[74:77]
	v_mfma_f32_16x16x32_bf16 v[122:125], v[156:159], v[188:191], v[122:125]
	v_mfma_f32_16x16x32_bf16 v[126:129], v[164:167], v[188:191], v[126:129]
	v_mfma_f32_16x16x32_bf16 v[110:113], v[156:159], v[196:199], v[110:113]
	v_mfma_f32_16x16x32_bf16 v[106:109], v[164:167], v[196:199], v[106:109]
	v_mfma_f32_16x16x32_bf16 v[94:97], v[156:159], v[204:207], v[94:97]
	v_mfma_f32_16x16x32_bf16 v[90:93], v[164:167], v[204:207], v[90:93]
	v_mfma_f32_16x16x32_bf16 v[78:81], v[156:159], v[212:215], v[78:81]
	v_mfma_f32_16x16x32_bf16 v[74:77], v[164:167], v[212:215], v[74:77]
	v_mfma_f32_16x16x32_bf16 v[118:121], v[168:171], v[184:187], v[118:121]
	v_mfma_f32_16x16x32_bf16 v[114:117], v[176:179], v[184:187], v[114:117]
	v_mfma_f32_16x16x32_bf16 v[102:105], v[168:171], v[192:195], v[102:105]
	v_mfma_f32_16x16x32_bf16 v[98:101], v[176:179], v[192:195], v[98:101]
	v_mfma_f32_16x16x32_bf16 v[86:89], v[168:171], v[200:203], v[86:89]
	v_mfma_f32_16x16x32_bf16 v[82:85], v[176:179], v[200:203], v[82:85]
	v_mfma_f32_16x16x32_bf16 v[70:73], v[168:171], v[208:211], v[70:73]
	v_mfma_f32_16x16x32_bf16 v[66:69], v[176:179], v[208:211], v[66:69]
	v_mfma_f32_16x16x32_bf16 v[118:121], v[172:175], v[188:191], v[118:121]
	v_mfma_f32_16x16x32_bf16 v[114:117], v[180:183], v[188:191], v[114:117]
	v_mfma_f32_16x16x32_bf16 v[102:105], v[172:175], v[196:199], v[102:105]
	v_mfma_f32_16x16x32_bf16 v[98:101], v[180:183], v[196:199], v[98:101]
	v_mfma_f32_16x16x32_bf16 v[86:89], v[172:175], v[204:207], v[86:89]
	v_mfma_f32_16x16x32_bf16 v[82:85], v[180:183], v[204:207], v[82:85]
	v_mfma_f32_16x16x32_bf16 v[70:73], v[172:175], v[212:215], v[70:73]
	v_mfma_f32_16x16x32_bf16 v[66:69], v[180:183], v[212:215], v[66:69]
	s_barrier
; #define PG8_STAGE(bufoff, gbase, voff) do { _Pragma("unroll") for (int _i = 0; _i < 2; ++_i) \
;         __builtin_amdgcn_global_load_lds((const unsigned*)((const char*)(gbase) + (voff)[_i]), (PG8_LAS unsigned*)(lds + (bufoff) + ldsw + _i * 8192), 16, 0, 0); } while (0)
; #define PG8_LDA(dst, b, h) do { _Pragma("unroll") for (int m = 0; m < 4; ++m) _Pragma("unroll") for (int k = 0; k < 2; ++k) dst[m][k] = *(const PG8_LAS bf16x8*)(lds + PG8_SA(b, h) + aoff + m * 2048 + k * 1024); } while (0)
; #define PG8_MMA(ai, bj, At, Bt) do { __builtin_amdgcn_s_setprio(1); _Pragma("unroll") for (int m = 0; m < 4; ++m) _Pragma("unroll") for (int n = 0; n < 2; ++n) _Pragma("unroll") for (int k = 0; k < 2; ++k) \
;         acc[ai][bj][m][n] = __builtin_amdgcn_mfma_f32_16x16x32_bf16(Bt[n][k], At[m][k], acc[ai][bj][m][n], 0, 0, 0); __builtin_amdgcn_s_setprio(0); } while (0)
; #define PG8_WAIT_V(n) asm volatile("s_waitcnt vmcnt(" #n ")" ::: "memory")
; #define PG8_WAIT_L(n) asm volatile("s_waitcnt lgkmcnt(" #n ")" ::: "memory")
; #define PG8_BAR __builtin_amdgcn_s_barrier()
; #define PG8_SCHED __builtin_amdgcn_sched_barrier(0)
; template <class Epi, class Sched, bool ALIGN_EPI = false, bool SP2 = false>
; __device__ __forceinline__ void gemm_phase(PG8_LAS unsigned char* lds, const Gemm g, const Sched& S, const Epi& E) {
;     ...
;             PG8_LDA(At, 1, 1); PG8_STAGE(PG8_SB(1, 0), b3, voffB); PG8_STAGE(PG8_SB(1, 1), b3 + hstepB, voffB); PG8_STAGE(PG8_SA(1, 0), a3, voffA);
;             PG8_WAIT_V(8); PG8_WAIT_L(0); PG8_BAR; PG8_MMA(1, 0, At, B0); PG8_MMA(1, 1, At, B1); PG8_BAR; PG8_SCHED;
	s_add_i32 s48, s51, s52
	v_lshl_add_u64 v[148:149], v[148:149], 0, s[36:37]
	s_mov_b32 m0, s48
	ds_read_b128 v[184:187], v155 offset:49152
	ds_read_b128 v[188:191], v155 offset:50176
	ds_read_b128 v[192:195], v155 offset:51200
	ds_read_b128 v[196:199], v155 offset:52224
	ds_read_b128 v[200:203], v155 offset:53248
	ds_read_b128 v[204:207], v155 offset:54272
	ds_read_b128 v[208:211], v155 offset:55296
	ds_read_b128 v[212:215], v155 offset:56320
	global_load_lds_dwordx4 v[148:149], off
	v_lshl_add_u64 v[148:149], v[216:217], 0, s[36:37]
	s_add_i32 m0, s48, 0x2000
	s_add_i32 s48, s79, s52
	global_load_lds_dwordx4 v[148:149], off
	v_lshl_add_u64 v[148:149], v[218:219], 0, s[36:37]
	s_mov_b32 m0, s48
	s_nop 0
	global_load_lds_dwordx4 v[148:149], off
	v_lshl_add_u64 v[148:149], v[220:221], 0, s[36:37]
	s_add_i32 m0, s48, 0x2000
	s_nop 0
	global_load_lds_dwordx4 v[148:149], off
	v_lshl_add_u64 v[148:149], v[222:223], 0, s[36:37]
	s_mov_b32 m0, s59
	s_nop 0
	global_load_lds_dwordx4 v[148:149], off
	v_lshl_add_u64 v[148:149], v[224:225], 0, s[36:37]
	s_mov_b32 m0, s60
	s_nop 0
	global_load_lds_dwordx4 v[148:149], off
	s_waitcnt vmcnt(8)
	s_waitcnt lgkmcnt(0)
	s_barrier
	s_waitcnt lgkmcnt(0)
	v_mfma_f32_16x16x32_bf16 v[62:65], v[144:147], v[184:187], v[62:65]
	v_mfma_f32_16x16x32_bf16 v[58:61], v[160:163], v[184:187], v[58:61]
	v_mfma_f32_16x16x32_bf16 v[46:49], v[144:147], v[192:195], v[46:49]
	v_mfma_f32_16x16x32_bf16 v[42:45], v[160:163], v[192:195], v[42:45]
	v_mfma_f32_16x16x32_bf16 v[30:33], v[144:147], v[200:203], v[30:33]
	v_mfma_f32_16x16x32_bf16 v[26:29], v[160:163], v[200:203], v[26:29]
	v_mfma_f32_16x16x32_bf16 v[14:17], v[144:147], v[208:211], v[14:17]
	v_mfma_f32_16x16x32_bf16 v[10:13], v[160:163], v[208:211], v[10:13]
	v_mfma_f32_16x16x32_bf16 v[62:65], v[156:159], v[188:191], v[62:65]
	v_mfma_f32_16x16x32_bf16 v[58:61], v[164:167], v[188:191], v[58:61]
	v_mfma_f32_16x16x32_bf16 v[46:49], v[156:159], v[196:199], v[46:49]
	v_mfma_f32_16x16x32_bf16 v[42:45], v[164:167], v[196:199], v[42:45]
	v_mfma_f32_16x16x32_bf16 v[30:33], v[156:159], v[204:207], v[30:33]
	v_mfma_f32_16x16x32_bf16 v[26:29], v[164:167], v[204:207], v[26:29]
	v_mfma_f32_16x16x32_bf16 v[14:17], v[156:159], v[212:215], v[14:17]
	v_mfma_f32_16x16x32_bf16 v[10:13], v[164:167], v[212:215], v[10:13]
	v_mfma_f32_16x16x32_bf16 v[54:57], v[168:171], v[184:187], v[54:57]
	v_mfma_f32_16x16x32_bf16 v[50:53], v[176:179], v[184:187], v[50:53]
	v_mfma_f32_16x16x32_bf16 v[38:41], v[168:171], v[192:195], v[38:41]
	v_mfma_f32_16x16x32_bf16 v[34:37], v[176:179], v[192:195], v[34:37]
	v_mfma_f32_16x16x32_bf16 v[22:25], v[168:171], v[200:203], v[22:25]
	v_mfma_f32_16x16x32_bf16 v[18:21], v[176:179], v[200:203], v[18:21]
	v_mfma_f32_16x16x32_bf16 v[6:9], v[168:171], v[208:211], v[6:9]
	v_mfma_f32_16x16x32_bf16 v[2:5], v[176:179], v[208:211], v[2:5]
	v_mfma_f32_16x16x32_bf16 v[54:57], v[172:175], v[188:191], v[54:57]
	v_mfma_f32_16x16x32_bf16 v[50:53], v[180:183], v[188:191], v[50:53]
	v_mfma_f32_16x16x32_bf16 v[38:41], v[172:175], v[196:199], v[38:41]
	v_mfma_f32_16x16x32_bf16 v[34:37], v[180:183], v[196:199], v[34:37]
	v_mfma_f32_16x16x32_bf16 v[22:25], v[172:175], v[204:207], v[22:25]
	v_mfma_f32_16x16x32_bf16 v[18:21], v[180:183], v[204:207], v[18:21]
	v_mfma_f32_16x16x32_bf16 v[6:9], v[172:175], v[212:215], v[6:9]
	v_mfma_f32_16x16x32_bf16 v[2:5], v[180:183], v[212:215], v[2:5]
	s_barrier
	s_add_u32 s77, s77, 0x100
	s_addc_u32 s78, s78, 0
	s_add_u32 s6, s6, 0x100
	s_addc_u32 s7, s7, 0
	s_cmp_ge_i32 s50, s61
	s_mov_b32 s48, s50
	s_cbranch_scc0 .LBB0_1332
